# 4+4 LDS-DMA issue rebalance: As[b][0] staging pair moved from SP2(t) to SP1(t+1), SP2(t) wait vmcnt(8)->vmcnt(6); on top of saddr, wait removal, prio moves
# speedup vs baseline: 1.0067x; 1.0027x over previous
.LBB0_249:
	ds_read_b128 v[152:155], v146
	ds_read_b128 v[156:159], v146 offset:1024
	ds_read_b128 v[160:163], v146 offset:2048
	ds_read_b128 v[164:167], v146 offset:3072
	ds_read_b128 v[168:171], v147
	ds_read_b128 v[172:175], v147 offset:1024
	ds_read_b128 v[176:179], v147 offset:2048
	ds_read_b128 v[180:183], v147 offset:3072
	s_add_u32 s16, s70, 0xfff00080
	s_addc_u32 s17, s71, -1
	s_cmp_eq_u32 s15, 60
	s_cselect_b32 s75, s47, s17
	s_cselect_b32 s74, s93, s16
	s_cselect_b32 s67, s4, s14
	s_cselect_b32 s66, s94, s57
	s_mov_b32 m0, s78
	ds_read_b128 v[184:187], v148
	ds_read_b128 v[188:191], v148 offset:1024
	ds_read_b128 v[192:195], v148 offset:2048
	ds_read_b128 v[196:199], v148 offset:3072
	ds_read_b128 v[200:203], v148 offset:4096
	ds_read_b128 v[204:207], v148 offset:5120
	ds_read_b128 v[208:211], v148 offset:6144
	ds_read_b128 v[212:215], v148 offset:7168
	global_load_lds_dwordx4 v138, s[70:71]
	s_mov_b32 m0, s79
	s_nop 0
	global_load_lds_dwordx4 v140, s[70:71]
	s_waitcnt vmcnt(8)
	s_waitcnt lgkmcnt(0)
	s_setprio 1
	s_barrier
	v_mfma_f32_16x16x32_bf16 v[122:125], v[152:155], v[184:187], v[122:125]
	v_mfma_f32_16x16x32_bf16 v[114:117], v[160:163], v[184:187], v[114:117]
	v_mfma_f32_16x16x32_bf16 v[106:109], v[152:155], v[192:195], v[106:109]
	v_mfma_f32_16x16x32_bf16 v[98:101], v[160:163], v[192:195], v[98:101]
	v_mfma_f32_16x16x32_bf16 v[90:93], v[152:155], v[200:203], v[90:93]
	v_mfma_f32_16x16x32_bf16 v[82:85], v[160:163], v[200:203], v[82:85]
	v_mfma_f32_16x16x32_bf16 v[74:77], v[152:155], v[208:211], v[74:77]
	v_mfma_f32_16x16x32_bf16 v[58:61], v[160:163], v[208:211], v[58:61]
	v_mfma_f32_16x16x32_bf16 v[122:125], v[156:159], v[188:191], v[122:125]
	v_mfma_f32_16x16x32_bf16 v[114:117], v[164:167], v[188:191], v[114:117]
	v_mfma_f32_16x16x32_bf16 v[106:109], v[156:159], v[196:199], v[106:109]
	v_mfma_f32_16x16x32_bf16 v[98:101], v[164:167], v[196:199], v[98:101]
	v_mfma_f32_16x16x32_bf16 v[90:93], v[156:159], v[204:207], v[90:93]
	v_mfma_f32_16x16x32_bf16 v[82:85], v[164:167], v[204:207], v[82:85]
	v_mfma_f32_16x16x32_bf16 v[74:77], v[156:159], v[212:215], v[74:77]
	v_mfma_f32_16x16x32_bf16 v[58:61], v[164:167], v[212:215], v[58:61]
	s_setprio 0
	s_setprio 1
	v_mfma_f32_16x16x32_bf16 v[126:129], v[168:171], v[184:187], v[126:129]
	v_mfma_f32_16x16x32_bf16 v[118:121], v[176:179], v[184:187], v[118:121]
	v_mfma_f32_16x16x32_bf16 v[110:113], v[168:171], v[192:195], v[110:113]
	v_mfma_f32_16x16x32_bf16 v[102:105], v[176:179], v[192:195], v[102:105]
	v_mfma_f32_16x16x32_bf16 v[94:97], v[168:171], v[200:203], v[94:97]
	v_mfma_f32_16x16x32_bf16 v[86:89], v[176:179], v[200:203], v[86:89]
	v_mfma_f32_16x16x32_bf16 v[78:81], v[168:171], v[208:211], v[78:81]
	v_mfma_f32_16x16x32_bf16 v[66:69], v[176:179], v[208:211], v[66:69]
	v_mfma_f32_16x16x32_bf16 v[126:129], v[172:175], v[188:191], v[126:129]
	v_mfma_f32_16x16x32_bf16 v[118:121], v[180:183], v[188:191], v[118:121]
	v_mfma_f32_16x16x32_bf16 v[110:113], v[172:175], v[196:199], v[110:113]
	v_mfma_f32_16x16x32_bf16 v[102:105], v[180:183], v[196:199], v[102:105]
	v_mfma_f32_16x16x32_bf16 v[94:97], v[172:175], v[204:207], v[94:97]
	v_mfma_f32_16x16x32_bf16 v[86:89], v[180:183], v[204:207], v[86:89]
	v_mfma_f32_16x16x32_bf16 v[78:81], v[172:175], v[212:215], v[78:81]
	v_mfma_f32_16x16x32_bf16 v[66:69], v[180:183], v[212:215], v[66:69]
	s_barrier
	s_setprio 0
	s_mov_b32 m0, s81
	s_mov_b64 s[98:99], s[66:67]
	s_add_u32 s16, s66, 0x100000
	ds_read_b128 v[184:187], v148 offset:16384
	ds_read_b128 v[188:191], v148 offset:17408
	ds_read_b128 v[192:195], v148 offset:18432
	ds_read_b128 v[196:199], v148 offset:19456
	ds_read_b128 v[200:203], v148 offset:20480
	ds_read_b128 v[204:207], v148 offset:21504
	ds_read_b128 v[208:211], v148 offset:22528
	ds_read_b128 v[212:215], v148 offset:23552
	global_load_lds_dwordx4 v134, s[66:67]
	s_mov_b32 m0, s82
	s_addc_u32 s17, s67, 0
	global_load_lds_dwordx4 v130, s[66:67]
	s_mov_b32 m0, s83
	s_mov_b64 s[100:101], s[74:75]
	global_load_lds_dwordx4 v134, s[16:17]
	s_mov_b32 m0, s86
	s_nop 0
	global_load_lds_dwordx4 v130, s[16:17]
	s_waitcnt vmcnt(6)
	s_waitcnt lgkmcnt(0)
	s_setprio 1
	s_barrier
	v_mfma_f32_16x16x32_bf16 v[62:65], v[152:155], v[184:187], v[62:65]
	v_mfma_f32_16x16x32_bf16 v[50:53], v[160:163], v[184:187], v[50:53]
	v_mfma_f32_16x16x32_bf16 v[42:45], v[152:155], v[192:195], v[42:45]
	v_mfma_f32_16x16x32_bf16 v[34:37], v[160:163], v[192:195], v[34:37]
	v_mfma_f32_16x16x32_bf16 v[26:29], v[152:155], v[200:203], v[26:29]
	v_mfma_f32_16x16x32_bf16 v[18:21], v[160:163], v[200:203], v[18:21]
	v_mfma_f32_16x16x32_bf16 v[10:13], v[152:155], v[208:211], v[10:13]
	v_mfma_f32_16x16x32_bf16 v[2:5], v[160:163], v[208:211], v[2:5]
	v_mfma_f32_16x16x32_bf16 v[62:65], v[156:159], v[188:191], v[62:65]
	v_mfma_f32_16x16x32_bf16 v[50:53], v[164:167], v[188:191], v[50:53]
	v_mfma_f32_16x16x32_bf16 v[42:45], v[156:159], v[196:199], v[42:45]
	v_mfma_f32_16x16x32_bf16 v[34:37], v[164:167], v[196:199], v[34:37]
	v_mfma_f32_16x16x32_bf16 v[26:29], v[156:159], v[204:207], v[26:29]
	v_mfma_f32_16x16x32_bf16 v[18:21], v[164:167], v[204:207], v[18:21]
	v_mfma_f32_16x16x32_bf16 v[10:13], v[156:159], v[212:215], v[10:13]
	v_mfma_f32_16x16x32_bf16 v[2:5], v[164:167], v[212:215], v[2:5]
	s_setprio 0
	s_setprio 1
	v_mfma_f32_16x16x32_bf16 v[70:73], v[168:171], v[184:187], v[70:73]
	v_mfma_f32_16x16x32_bf16 v[54:57], v[176:179], v[184:187], v[54:57]
	v_mfma_f32_16x16x32_bf16 v[46:49], v[168:171], v[192:195], v[46:49]
	v_mfma_f32_16x16x32_bf16 v[38:41], v[176:179], v[192:195], v[38:41]
	v_mfma_f32_16x16x32_bf16 v[30:33], v[168:171], v[200:203], v[30:33]
	v_mfma_f32_16x16x32_bf16 v[22:25], v[176:179], v[200:203], v[22:25]
	v_mfma_f32_16x16x32_bf16 v[14:17], v[168:171], v[208:211], v[14:17]
	v_mfma_f32_16x16x32_bf16 v[6:9], v[176:179], v[208:211], v[6:9]
	v_mfma_f32_16x16x32_bf16 v[70:73], v[172:175], v[188:191], v[70:73]
	v_mfma_f32_16x16x32_bf16 v[54:57], v[180:183], v[188:191], v[54:57]
	v_mfma_f32_16x16x32_bf16 v[46:49], v[172:175], v[196:199], v[46:49]
	v_mfma_f32_16x16x32_bf16 v[38:41], v[180:183], v[196:199], v[38:41]
	v_mfma_f32_16x16x32_bf16 v[30:33], v[172:175], v[204:207], v[30:33]
	v_mfma_f32_16x16x32_bf16 v[22:25], v[180:183], v[204:207], v[22:25]
	v_mfma_f32_16x16x32_bf16 v[14:17], v[172:175], v[212:215], v[14:17]
	v_mfma_f32_16x16x32_bf16 v[6:9], v[180:183], v[212:215], v[6:9]
	s_barrier
	s_setprio 0
	ds_read_b128 v[152:155], v149
	ds_read_b128 v[156:159], v149 offset:1024
	ds_read_b128 v[160:163], v149 offset:2048
	ds_read_b128 v[164:167], v149 offset:3072
	ds_read_b128 v[168:171], v150
	ds_read_b128 v[172:175], v150 offset:1024
	ds_read_b128 v[176:179], v150 offset:2048
	ds_read_b128 v[180:183], v150 offset:3072
	s_add_u32 s16, s74, 0x100000
	s_addc_u32 s17, s75, 0
	s_mov_b32 m0, s29
	s_nop 0
	global_load_lds_dwordx4 v136, s[100:101]
	s_mov_b32 m0, s33
	s_nop 0
	global_load_lds_dwordx4 v132, s[100:101]
	s_mov_b32 m0, s58
	ds_read_b128 v[184:187], v148 offset:32768
	ds_read_b128 v[188:191], v148 offset:33792
	ds_read_b128 v[192:195], v148 offset:34816
	ds_read_b128 v[196:199], v148 offset:35840
	ds_read_b128 v[200:203], v148 offset:36864
	ds_read_b128 v[204:207], v148 offset:37888
	ds_read_b128 v[208:211], v148 offset:38912
	ds_read_b128 v[212:215], v148 offset:39936
	global_load_lds_dwordx4 v136, s[16:17]
	s_mov_b32 m0, s59
	s_nop 0
	global_load_lds_dwordx4 v132, s[16:17]
	s_waitcnt vmcnt(8)
	s_waitcnt lgkmcnt(0)
	s_setprio 1
	s_barrier
	v_mfma_f32_16x16x32_bf16 v[122:125], v[152:155], v[184:187], v[122:125]
	v_mfma_f32_16x16x32_bf16 v[114:117], v[160:163], v[184:187], v[114:117]
	v_mfma_f32_16x16x32_bf16 v[106:109], v[152:155], v[192:195], v[106:109]
	v_mfma_f32_16x16x32_bf16 v[98:101], v[160:163], v[192:195], v[98:101]
	v_mfma_f32_16x16x32_bf16 v[90:93], v[152:155], v[200:203], v[90:93]
	v_mfma_f32_16x16x32_bf16 v[82:85], v[160:163], v[200:203], v[82:85]
	v_mfma_f32_16x16x32_bf16 v[74:77], v[152:155], v[208:211], v[74:77]
	v_mfma_f32_16x16x32_bf16 v[58:61], v[160:163], v[208:211], v[58:61]
	v_mfma_f32_16x16x32_bf16 v[122:125], v[156:159], v[188:191], v[122:125]
	v_mfma_f32_16x16x32_bf16 v[114:117], v[164:167], v[188:191], v[114:117]
	v_mfma_f32_16x16x32_bf16 v[106:109], v[156:159], v[196:199], v[106:109]
	v_mfma_f32_16x16x32_bf16 v[98:101], v[164:167], v[196:199], v[98:101]
	v_mfma_f32_16x16x32_bf16 v[90:93], v[156:159], v[204:207], v[90:93]
	v_mfma_f32_16x16x32_bf16 v[82:85], v[164:167], v[204:207], v[82:85]
	v_mfma_f32_16x16x32_bf16 v[74:77], v[156:159], v[212:215], v[74:77]
	v_mfma_f32_16x16x32_bf16 v[58:61], v[164:167], v[212:215], v[58:61]
	s_setprio 0
	s_setprio 1
	v_mfma_f32_16x16x32_bf16 v[126:129], v[168:171], v[184:187], v[126:129]
	v_mfma_f32_16x16x32_bf16 v[118:121], v[176:179], v[184:187], v[118:121]
	v_mfma_f32_16x16x32_bf16 v[110:113], v[168:171], v[192:195], v[110:113]
	v_mfma_f32_16x16x32_bf16 v[102:105], v[176:179], v[192:195], v[102:105]
	v_mfma_f32_16x16x32_bf16 v[94:97], v[168:171], v[200:203], v[94:97]
	v_mfma_f32_16x16x32_bf16 v[86:89], v[176:179], v[200:203], v[86:89]
	v_mfma_f32_16x16x32_bf16 v[78:81], v[168:171], v[208:211], v[78:81]
	v_mfma_f32_16x16x32_bf16 v[66:69], v[176:179], v[208:211], v[66:69]
	v_mfma_f32_16x16x32_bf16 v[126:129], v[172:175], v[188:191], v[126:129]
	v_mfma_f32_16x16x32_bf16 v[118:121], v[180:183], v[188:191], v[118:121]
	v_mfma_f32_16x16x32_bf16 v[110:113], v[172:175], v[196:199], v[110:113]
	v_mfma_f32_16x16x32_bf16 v[102:105], v[180:183], v[196:199], v[102:105]
	v_mfma_f32_16x16x32_bf16 v[94:97], v[172:175], v[204:207], v[94:97]
	v_mfma_f32_16x16x32_bf16 v[86:89], v[180:183], v[204:207], v[86:89]
	v_mfma_f32_16x16x32_bf16 v[78:81], v[172:175], v[212:215], v[78:81]
	v_mfma_f32_16x16x32_bf16 v[66:69], v[180:183], v[212:215], v[66:69]
	s_barrier
	s_setprio 0
	s_mov_b32 m0, s87
	s_add_u32 s98, s98, 0x80
	s_addc_u32 s99, s99, 0
	s_add_u32 s100, s100, 0x80
	s_addc_u32 s101, s101, 0
	s_add_u32 s16, s66, 0x100080
	ds_read_b128 v[184:187], v148 offset:49152
	ds_read_b128 v[188:191], v148 offset:50176
	ds_read_b128 v[192:195], v148 offset:51200
	ds_read_b128 v[196:199], v148 offset:52224
	ds_read_b128 v[200:203], v148 offset:53248
	ds_read_b128 v[204:207], v148 offset:54272
	ds_read_b128 v[208:211], v148 offset:55296
	ds_read_b128 v[212:215], v148 offset:56320
	global_load_lds_dwordx4 v134, s[98:99]
	s_mov_b32 m0, s88
	s_addc_u32 s17, s67, 0
	global_load_lds_dwordx4 v130, s[98:99]
	s_mov_b32 m0, s89
	s_nop 0
	global_load_lds_dwordx4 v134, s[16:17]
	s_mov_b32 m0, s56
	s_nop 0
	global_load_lds_dwordx4 v130, s[16:17]
	s_mov_b32 m0, s65
	s_nop 0
	global_load_lds_dwordx4 v136, s[100:101]
	s_mov_b32 m0, s76
	s_nop 0
	global_load_lds_dwordx4 v132, s[100:101]
	s_waitcnt vmcnt(8)
	s_waitcnt lgkmcnt(0)
	s_setprio 1
	s_barrier
	v_mfma_f32_16x16x32_bf16 v[62:65], v[152:155], v[184:187], v[62:65]
	v_mfma_f32_16x16x32_bf16 v[50:53], v[160:163], v[184:187], v[50:53]
	v_mfma_f32_16x16x32_bf16 v[42:45], v[152:155], v[192:195], v[42:45]
	v_mfma_f32_16x16x32_bf16 v[34:37], v[160:163], v[192:195], v[34:37]
	v_mfma_f32_16x16x32_bf16 v[26:29], v[152:155], v[200:203], v[26:29]
	v_mfma_f32_16x16x32_bf16 v[18:21], v[160:163], v[200:203], v[18:21]
	v_mfma_f32_16x16x32_bf16 v[10:13], v[152:155], v[208:211], v[10:13]
	v_mfma_f32_16x16x32_bf16 v[2:5], v[160:163], v[208:211], v[2:5]
	v_mfma_f32_16x16x32_bf16 v[62:65], v[156:159], v[188:191], v[62:65]
	v_mfma_f32_16x16x32_bf16 v[50:53], v[164:167], v[188:191], v[50:53]
	v_mfma_f32_16x16x32_bf16 v[42:45], v[156:159], v[196:199], v[42:45]
	v_mfma_f32_16x16x32_bf16 v[34:37], v[164:167], v[196:199], v[34:37]
	v_mfma_f32_16x16x32_bf16 v[26:29], v[156:159], v[204:207], v[26:29]
	v_mfma_f32_16x16x32_bf16 v[18:21], v[164:167], v[204:207], v[18:21]
	v_mfma_f32_16x16x32_bf16 v[10:13], v[156:159], v[212:215], v[10:13]
	v_mfma_f32_16x16x32_bf16 v[2:5], v[164:167], v[212:215], v[2:5]
	s_setprio 0
	s_setprio 1
	v_mfma_f32_16x16x32_bf16 v[70:73], v[168:171], v[184:187], v[70:73]
	v_mfma_f32_16x16x32_bf16 v[54:57], v[176:179], v[184:187], v[54:57]
	v_mfma_f32_16x16x32_bf16 v[46:49], v[168:171], v[192:195], v[46:49]
	v_mfma_f32_16x16x32_bf16 v[38:41], v[176:179], v[192:195], v[38:41]
	v_mfma_f32_16x16x32_bf16 v[30:33], v[168:171], v[200:203], v[30:33]
	v_mfma_f32_16x16x32_bf16 v[22:25], v[176:179], v[200:203], v[22:25]
	v_mfma_f32_16x16x32_bf16 v[14:17], v[168:171], v[208:211], v[14:17]
	v_mfma_f32_16x16x32_bf16 v[6:9], v[176:179], v[208:211], v[6:9]
	v_mfma_f32_16x16x32_bf16 v[70:73], v[172:175], v[188:191], v[70:73]
	v_mfma_f32_16x16x32_bf16 v[54:57], v[180:183], v[188:191], v[54:57]
	v_mfma_f32_16x16x32_bf16 v[46:49], v[172:175], v[196:199], v[46:49]
	v_mfma_f32_16x16x32_bf16 v[38:41], v[180:183], v[196:199], v[38:41]
	v_mfma_f32_16x16x32_bf16 v[30:33], v[172:175], v[204:207], v[30:33]
	v_mfma_f32_16x16x32_bf16 v[22:25], v[180:183], v[204:207], v[22:25]
	v_mfma_f32_16x16x32_bf16 v[14:17], v[172:175], v[212:215], v[14:17]
	v_mfma_f32_16x16x32_bf16 v[6:9], v[180:183], v[212:215], v[6:9]
	s_barrier
	s_setprio 0
	s_add_i32 s15, s15, 2
	s_add_u32 s70, s70, 0x100
	s_addc_u32 s71, s71, 0
	s_add_u32 s57, s57, 0x100
	s_addc_u32 s14, s14, 0
	s_cmp_gt_u32 s15, 61
	s_cbranch_scc0 .LBB0_249
	s_and_b64 vcc, exec, s[12:13]
	s_cbranch_vccz .LBB0_252
	s_barrier

.LBB0_331:
	ds_read_b128 v[132:135], v207
	ds_read_b128 v[136:139], v207 offset:1024
	ds_read_b128 v[140:143], v207 offset:2048
	ds_read_b128 v[144:147], v207 offset:3072
	ds_read_b128 v[148:151], v208
	ds_read_b128 v[152:155], v208 offset:1024
	ds_read_b128 v[156:159], v208 offset:2048
	ds_read_b128 v[160:163], v208 offset:3072
	s_add_u32 s16, s66, 0x200
	s_addc_u32 s17, s67, 0
	s_cmpk_eq_i32 s15, 0xa8
	s_cselect_b32 s75, s1, s17
	s_cselect_b32 s74, s0, s16
	s_cselect_b32 s71, s65, s14
	s_cselect_b32 s70, s64, s90
	s_mov_b32 m0, s86
	ds_read_b128 v[164:167], v209
	ds_read_b128 v[168:171], v209 offset:1024
	ds_read_b128 v[172:175], v209 offset:2048
	ds_read_b128 v[194:197], v209 offset:3072
	ds_read_b128 v[198:201], v209 offset:4096
	ds_read_b128 v[202:205], v209 offset:5120
	ds_read_b128 v[210:213], v209 offset:6144
	ds_read_b128 v[214:217], v209 offset:7168
	global_load_lds_dwordx4 v186, s[66:67]
	s_mov_b32 m0, s87
	s_nop 0
	global_load_lds_dwordx4 v188, s[66:67]
	s_waitcnt vmcnt(8)
	s_waitcnt lgkmcnt(0)
	s_setprio 1
	s_barrier
	v_mfma_f32_16x16x32_bf16 v[122:125], v[132:135], v[164:167], v[122:125]
	v_mfma_f32_16x16x32_bf16 v[118:121], v[140:143], v[164:167], v[118:121]
	v_mfma_f32_16x16x32_bf16 v[110:113], v[132:135], v[172:175], v[110:113]
	v_mfma_f32_16x16x32_bf16 v[106:109], v[140:143], v[172:175], v[106:109]
	v_mfma_f32_16x16x32_bf16 v[94:97], v[132:135], v[198:201], v[94:97]
	v_mfma_f32_16x16x32_bf16 v[90:93], v[140:143], v[198:201], v[90:93]
	v_mfma_f32_16x16x32_bf16 v[78:81], v[132:135], v[210:213], v[78:81]
	v_mfma_f32_16x16x32_bf16 v[74:77], v[140:143], v[210:213], v[74:77]
	v_mfma_f32_16x16x32_bf16 v[122:125], v[136:139], v[168:171], v[122:125]
	v_mfma_f32_16x16x32_bf16 v[118:121], v[144:147], v[168:171], v[118:121]
	v_mfma_f32_16x16x32_bf16 v[110:113], v[136:139], v[194:197], v[110:113]
	v_mfma_f32_16x16x32_bf16 v[106:109], v[144:147], v[194:197], v[106:109]
	v_mfma_f32_16x16x32_bf16 v[94:97], v[136:139], v[202:205], v[94:97]
	v_mfma_f32_16x16x32_bf16 v[90:93], v[144:147], v[202:205], v[90:93]
	v_mfma_f32_16x16x32_bf16 v[78:81], v[136:139], v[214:217], v[78:81]
	v_mfma_f32_16x16x32_bf16 v[74:77], v[144:147], v[214:217], v[74:77]
	s_setprio 0
	s_setprio 1
	v_mfma_f32_16x16x32_bf16 v[126:129], v[148:151], v[164:167], v[126:129]
	v_mfma_f32_16x16x32_bf16 v[114:117], v[156:159], v[164:167], v[114:117]
	v_mfma_f32_16x16x32_bf16 v[102:105], v[148:151], v[172:175], v[102:105]
	v_mfma_f32_16x16x32_bf16 v[98:101], v[156:159], v[172:175], v[98:101]
	v_mfma_f32_16x16x32_bf16 v[86:89], v[148:151], v[198:201], v[86:89]
	v_mfma_f32_16x16x32_bf16 v[82:85], v[156:159], v[198:201], v[82:85]
	v_mfma_f32_16x16x32_bf16 v[70:73], v[148:151], v[210:213], v[70:73]
	v_mfma_f32_16x16x32_bf16 v[66:69], v[156:159], v[210:213], v[66:69]
	v_mfma_f32_16x16x32_bf16 v[126:129], v[152:155], v[168:171], v[126:129]
	v_mfma_f32_16x16x32_bf16 v[114:117], v[160:163], v[168:171], v[114:117]
	v_mfma_f32_16x16x32_bf16 v[102:105], v[152:155], v[194:197], v[102:105]
	v_mfma_f32_16x16x32_bf16 v[98:101], v[160:163], v[194:197], v[98:101]
	v_mfma_f32_16x16x32_bf16 v[86:89], v[152:155], v[202:205], v[86:89]
	v_mfma_f32_16x16x32_bf16 v[82:85], v[160:163], v[202:205], v[82:85]
	v_mfma_f32_16x16x32_bf16 v[70:73], v[152:155], v[214:217], v[70:73]
	v_mfma_f32_16x16x32_bf16 v[66:69], v[160:163], v[214:217], v[66:69]
	s_barrier
	s_setprio 0
	s_mov_b32 m0, s88
	s_mov_b64 s[98:99], s[70:71]
	s_add_u32 s16, s70, 0x2b0000
	ds_read_b128 v[164:167], v209 offset:16384
	ds_read_b128 v[168:171], v209 offset:17408
	ds_read_b128 v[172:175], v209 offset:18432
	ds_read_b128 v[194:197], v209 offset:19456
	ds_read_b128 v[198:201], v209 offset:20480
	ds_read_b128 v[202:205], v209 offset:21504
	ds_read_b128 v[210:213], v209 offset:22528
	ds_read_b128 v[214:217], v209 offset:23552
	global_load_lds_dwordx4 v180, s[70:71]
	s_mov_b32 m0, s84
	s_addc_u32 s17, s71, 0
	global_load_lds_dwordx4 v184, s[70:71]
	s_mov_b32 m0, s85
	s_mov_b64 s[100:101], s[74:75]
	global_load_lds_dwordx4 v180, s[16:17]
	s_mov_b32 m0, s46
	s_nop 0
	global_load_lds_dwordx4 v184, s[16:17]
	s_waitcnt vmcnt(6)
	s_waitcnt lgkmcnt(0)
	s_setprio 1
	s_barrier
	v_mfma_f32_16x16x32_bf16 v[58:61], v[132:135], v[164:167], v[58:61]
	v_mfma_f32_16x16x32_bf16 v[54:57], v[140:143], v[164:167], v[54:57]
	v_mfma_f32_16x16x32_bf16 v[46:49], v[132:135], v[172:175], v[46:49]
	v_mfma_f32_16x16x32_bf16 v[42:45], v[140:143], v[172:175], v[42:45]
	v_mfma_f32_16x16x32_bf16 v[30:33], v[132:135], v[198:201], v[30:33]
	v_mfma_f32_16x16x32_bf16 v[26:29], v[140:143], v[198:201], v[26:29]
	v_mfma_f32_16x16x32_bf16 v[14:17], v[132:135], v[210:213], v[14:17]
	v_mfma_f32_16x16x32_bf16 v[10:13], v[140:143], v[210:213], v[10:13]
	v_mfma_f32_16x16x32_bf16 v[58:61], v[136:139], v[168:171], v[58:61]
	v_mfma_f32_16x16x32_bf16 v[54:57], v[144:147], v[168:171], v[54:57]
	v_mfma_f32_16x16x32_bf16 v[46:49], v[136:139], v[194:197], v[46:49]
	v_mfma_f32_16x16x32_bf16 v[42:45], v[144:147], v[194:197], v[42:45]
	v_mfma_f32_16x16x32_bf16 v[30:33], v[136:139], v[202:205], v[30:33]
	v_mfma_f32_16x16x32_bf16 v[26:29], v[144:147], v[202:205], v[26:29]
	v_mfma_f32_16x16x32_bf16 v[14:17], v[136:139], v[214:217], v[14:17]
	v_mfma_f32_16x16x32_bf16 v[10:13], v[144:147], v[214:217], v[10:13]
	s_setprio 0
	s_setprio 1
	v_mfma_f32_16x16x32_bf16 v[62:65], v[148:151], v[164:167], v[62:65]
	v_mfma_f32_16x16x32_bf16 v[50:53], v[156:159], v[164:167], v[50:53]
	v_mfma_f32_16x16x32_bf16 v[38:41], v[148:151], v[172:175], v[38:41]
	v_mfma_f32_16x16x32_bf16 v[34:37], v[156:159], v[172:175], v[34:37]
	v_mfma_f32_16x16x32_bf16 v[22:25], v[148:151], v[198:201], v[22:25]
	v_mfma_f32_16x16x32_bf16 v[18:21], v[156:159], v[198:201], v[18:21]
	v_mfma_f32_16x16x32_bf16 v[6:9], v[148:151], v[210:213], v[6:9]
	v_mfma_f32_16x16x32_bf16 v[2:5], v[156:159], v[210:213], v[2:5]
	v_mfma_f32_16x16x32_bf16 v[62:65], v[152:155], v[168:171], v[62:65]
	v_mfma_f32_16x16x32_bf16 v[50:53], v[160:163], v[168:171], v[50:53]
	v_mfma_f32_16x16x32_bf16 v[38:41], v[152:155], v[194:197], v[38:41]
	v_mfma_f32_16x16x32_bf16 v[34:37], v[160:163], v[194:197], v[34:37]
	v_mfma_f32_16x16x32_bf16 v[22:25], v[152:155], v[202:205], v[22:25]
	v_mfma_f32_16x16x32_bf16 v[18:21], v[160:163], v[202:205], v[18:21]
	v_mfma_f32_16x16x32_bf16 v[6:9], v[152:155], v[214:217], v[6:9]
	v_mfma_f32_16x16x32_bf16 v[2:5], v[160:163], v[214:217], v[2:5]
	s_barrier
	s_setprio 0
	ds_read_b128 v[132:135], v130
	ds_read_b128 v[136:139], v130 offset:1024
	ds_read_b128 v[140:143], v130 offset:2048
	ds_read_b128 v[144:147], v130 offset:3072
	ds_read_b128 v[148:151], v131
	ds_read_b128 v[152:155], v131 offset:1024
	ds_read_b128 v[156:159], v131 offset:2048
	ds_read_b128 v[160:163], v131 offset:3072
	s_add_u32 s16, s74, 0x2b0000
	s_addc_u32 s17, s75, 0
	s_mov_b32 m0, s11
	s_nop 0
	global_load_lds_dwordx4 v178, s[100:101]
	s_mov_b32 m0, s12
	s_nop 0
	global_load_lds_dwordx4 v182, s[100:101]
	s_mov_b32 m0, s13
	ds_read_b128 v[164:167], v209 offset:32768
	ds_read_b128 v[168:171], v209 offset:33792
	ds_read_b128 v[172:175], v209 offset:34816
	ds_read_b128 v[194:197], v209 offset:35840
	ds_read_b128 v[198:201], v209 offset:36864
	ds_read_b128 v[202:205], v209 offset:37888
	ds_read_b128 v[210:213], v209 offset:38912
	ds_read_b128 v[214:217], v209 offset:39936
	global_load_lds_dwordx4 v178, s[16:17]
	s_mov_b32 m0, s29
	s_nop 0
	global_load_lds_dwordx4 v182, s[16:17]
	s_waitcnt vmcnt(8)
	s_waitcnt lgkmcnt(0)
	s_setprio 1
	s_barrier
	v_mfma_f32_16x16x32_bf16 v[122:125], v[132:135], v[164:167], v[122:125]
	v_mfma_f32_16x16x32_bf16 v[118:121], v[140:143], v[164:167], v[118:121]
	v_mfma_f32_16x16x32_bf16 v[110:113], v[132:135], v[172:175], v[110:113]
	v_mfma_f32_16x16x32_bf16 v[106:109], v[140:143], v[172:175], v[106:109]
	v_mfma_f32_16x16x32_bf16 v[94:97], v[132:135], v[198:201], v[94:97]
	v_mfma_f32_16x16x32_bf16 v[90:93], v[140:143], v[198:201], v[90:93]
	v_mfma_f32_16x16x32_bf16 v[78:81], v[132:135], v[210:213], v[78:81]
	v_mfma_f32_16x16x32_bf16 v[74:77], v[140:143], v[210:213], v[74:77]
	v_mfma_f32_16x16x32_bf16 v[122:125], v[136:139], v[168:171], v[122:125]
	v_mfma_f32_16x16x32_bf16 v[118:121], v[144:147], v[168:171], v[118:121]
	v_mfma_f32_16x16x32_bf16 v[110:113], v[136:139], v[194:197], v[110:113]
	v_mfma_f32_16x16x32_bf16 v[106:109], v[144:147], v[194:197], v[106:109]
	v_mfma_f32_16x16x32_bf16 v[94:97], v[136:139], v[202:205], v[94:97]
	v_mfma_f32_16x16x32_bf16 v[90:93], v[144:147], v[202:205], v[90:93]
	v_mfma_f32_16x16x32_bf16 v[78:81], v[136:139], v[214:217], v[78:81]
	v_mfma_f32_16x16x32_bf16 v[74:77], v[144:147], v[214:217], v[74:77]
	s_setprio 0
	s_setprio 1
	v_mfma_f32_16x16x32_bf16 v[126:129], v[148:151], v[164:167], v[126:129]
	v_mfma_f32_16x16x32_bf16 v[114:117], v[156:159], v[164:167], v[114:117]
	v_mfma_f32_16x16x32_bf16 v[102:105], v[148:151], v[172:175], v[102:105]
	v_mfma_f32_16x16x32_bf16 v[98:101], v[156:159], v[172:175], v[98:101]
	v_mfma_f32_16x16x32_bf16 v[86:89], v[148:151], v[198:201], v[86:89]
	v_mfma_f32_16x16x32_bf16 v[82:85], v[156:159], v[198:201], v[82:85]
	v_mfma_f32_16x16x32_bf16 v[70:73], v[148:151], v[210:213], v[70:73]
	v_mfma_f32_16x16x32_bf16 v[66:69], v[156:159], v[210:213], v[66:69]
	v_mfma_f32_16x16x32_bf16 v[126:129], v[152:155], v[168:171], v[126:129]
	v_mfma_f32_16x16x32_bf16 v[114:117], v[160:163], v[168:171], v[114:117]
	v_mfma_f32_16x16x32_bf16 v[102:105], v[152:155], v[194:197], v[102:105]
	v_mfma_f32_16x16x32_bf16 v[98:101], v[160:163], v[194:197], v[98:101]
	v_mfma_f32_16x16x32_bf16 v[86:89], v[152:155], v[202:205], v[86:89]
	v_mfma_f32_16x16x32_bf16 v[82:85], v[160:163], v[202:205], v[82:85]
	v_mfma_f32_16x16x32_bf16 v[70:73], v[152:155], v[214:217], v[70:73]
	v_mfma_f32_16x16x32_bf16 v[66:69], v[160:163], v[214:217], v[66:69]
	s_barrier
	s_setprio 0
	s_mov_b32 m0, s47
	s_add_u32 s98, s98, 0x80
	s_addc_u32 s99, s99, 0
	s_add_u32 s100, s100, 0x80
	s_addc_u32 s101, s101, 0
	s_add_u32 s16, s70, 0x2b0080
	ds_read_b128 v[164:167], v209 offset:49152
	ds_read_b128 v[168:171], v209 offset:50176
	ds_read_b128 v[172:175], v209 offset:51200
	ds_read_b128 v[194:197], v209 offset:52224
	ds_read_b128 v[198:201], v209 offset:53248
	ds_read_b128 v[202:205], v209 offset:54272
	ds_read_b128 v[210:213], v209 offset:55296
	ds_read_b128 v[214:217], v209 offset:56320
	global_load_lds_dwordx4 v180, s[98:99]
	s_mov_b32 m0, s89
	s_addc_u32 s17, s71, 0
	global_load_lds_dwordx4 v184, s[98:99]
	s_mov_b32 m0, s56
	s_nop 0
	global_load_lds_dwordx4 v180, s[16:17]
	s_mov_b32 m0, s57
	s_nop 0
	global_load_lds_dwordx4 v184, s[16:17]
	s_mov_b32 m0, s58
	s_nop 0
	global_load_lds_dwordx4 v178, s[100:101]
	s_mov_b32 m0, s59
	s_nop 0
	global_load_lds_dwordx4 v182, s[100:101]
	s_waitcnt vmcnt(8)
	s_waitcnt lgkmcnt(0)
	s_setprio 1
	s_barrier
	v_mfma_f32_16x16x32_bf16 v[58:61], v[132:135], v[164:167], v[58:61]
	v_mfma_f32_16x16x32_bf16 v[54:57], v[140:143], v[164:167], v[54:57]
	v_mfma_f32_16x16x32_bf16 v[46:49], v[132:135], v[172:175], v[46:49]
	v_mfma_f32_16x16x32_bf16 v[42:45], v[140:143], v[172:175], v[42:45]
	v_mfma_f32_16x16x32_bf16 v[30:33], v[132:135], v[198:201], v[30:33]
	v_mfma_f32_16x16x32_bf16 v[26:29], v[140:143], v[198:201], v[26:29]
	v_mfma_f32_16x16x32_bf16 v[14:17], v[132:135], v[210:213], v[14:17]
	v_mfma_f32_16x16x32_bf16 v[10:13], v[140:143], v[210:213], v[10:13]
	v_mfma_f32_16x16x32_bf16 v[58:61], v[136:139], v[168:171], v[58:61]
	v_mfma_f32_16x16x32_bf16 v[54:57], v[144:147], v[168:171], v[54:57]
	v_mfma_f32_16x16x32_bf16 v[46:49], v[136:139], v[194:197], v[46:49]
	v_mfma_f32_16x16x32_bf16 v[42:45], v[144:147], v[194:197], v[42:45]
	v_mfma_f32_16x16x32_bf16 v[30:33], v[136:139], v[202:205], v[30:33]
	v_mfma_f32_16x16x32_bf16 v[26:29], v[144:147], v[202:205], v[26:29]
	v_mfma_f32_16x16x32_bf16 v[14:17], v[136:139], v[214:217], v[14:17]
	v_mfma_f32_16x16x32_bf16 v[10:13], v[144:147], v[214:217], v[10:13]
	s_setprio 0
	s_setprio 1
	v_mfma_f32_16x16x32_bf16 v[62:65], v[148:151], v[164:167], v[62:65]
	v_mfma_f32_16x16x32_bf16 v[50:53], v[156:159], v[164:167], v[50:53]
	v_mfma_f32_16x16x32_bf16 v[38:41], v[148:151], v[172:175], v[38:41]
	v_mfma_f32_16x16x32_bf16 v[34:37], v[156:159], v[172:175], v[34:37]
	v_mfma_f32_16x16x32_bf16 v[22:25], v[148:151], v[198:201], v[22:25]
	v_mfma_f32_16x16x32_bf16 v[18:21], v[156:159], v[198:201], v[18:21]
	v_mfma_f32_16x16x32_bf16 v[6:9], v[148:151], v[210:213], v[6:9]
	v_mfma_f32_16x16x32_bf16 v[2:5], v[156:159], v[210:213], v[2:5]
	v_mfma_f32_16x16x32_bf16 v[62:65], v[152:155], v[168:171], v[62:65]
	v_mfma_f32_16x16x32_bf16 v[50:53], v[160:163], v[168:171], v[50:53]
	v_mfma_f32_16x16x32_bf16 v[38:41], v[152:155], v[194:197], v[38:41]
	v_mfma_f32_16x16x32_bf16 v[34:37], v[160:163], v[194:197], v[34:37]
	v_mfma_f32_16x16x32_bf16 v[22:25], v[152:155], v[202:205], v[22:25]
	v_mfma_f32_16x16x32_bf16 v[18:21], v[160:163], v[202:205], v[18:21]
	v_mfma_f32_16x16x32_bf16 v[6:9], v[152:155], v[214:217], v[6:9]
	v_mfma_f32_16x16x32_bf16 v[2:5], v[160:163], v[214:217], v[2:5]
	s_barrier
	s_setprio 0
	s_add_i32 s15, s15, 2
	s_add_u32 s66, s66, 0x100
	s_addc_u32 s67, s67, 0
	s_add_u32 s90, s90, 0x100
	s_addc_u32 s14, s14, 0
	s_cmpk_gt_u32 s15, 0xa9
	s_cbranch_scc0 .LBB0_331
	s_and_b64 vcc, exec, s[30:31]
	s_cbranch_vccz .LBB0_334
	s_barrier

.LBB0_415:
	ds_read_b128 v[150:153], v163
	ds_read_b128 v[154:157], v163 offset:1024
	ds_read_b128 v[158:161], v163 offset:2048
	ds_read_b128 v[168:171], v163 offset:3072
	ds_read_b128 v[172:175], v164
	ds_read_b128 v[176:179], v164 offset:1024
	ds_read_b128 v[180:183], v164 offset:2048
	ds_read_b128 v[184:187], v164 offset:3072
	s_add_u32 s6, s80, 0xfff00080
	s_addc_u32 s7, s81, -1
	s_cmp_eq_u32 s15, 60
	s_cselect_b32 s83, s1, s7
	s_cselect_b32 s82, s75, s6
	s_cselect_b32 s7, s18, s14
	s_cselect_b32 s6, vcc_lo, s30
	s_mov_b32 m0, s89
	ds_read_b128 v[188:191], v165
	ds_read_b128 v[192:195], v165 offset:1024
	ds_read_b128 v[196:199], v165 offset:2048
	ds_read_b128 v[200:203], v165 offset:3072
	ds_read_b128 v[204:207], v165 offset:4096
	ds_read_b128 v[208:211], v165 offset:5120
	ds_read_b128 v[212:215], v165 offset:6144
	ds_read_b128 v[216:219], v165 offset:7168
	global_load_lds_dwordx4 v140, s[80:81]
	s_mov_b32 m0, s92
	s_nop 0
	global_load_lds_dwordx4 v142, s[80:81]
	s_waitcnt vmcnt(8)
	s_waitcnt lgkmcnt(0)
	s_setprio 1
	s_barrier
	v_mfma_f32_16x16x32_bf16 v[118:121], v[150:153], v[188:191], v[118:121]
	v_mfma_f32_16x16x32_bf16 v[114:117], v[158:161], v[188:191], v[114:117]
	v_mfma_f32_16x16x32_bf16 v[102:105], v[150:153], v[196:199], v[102:105]
	v_mfma_f32_16x16x32_bf16 v[98:101], v[158:161], v[196:199], v[98:101]
	v_mfma_f32_16x16x32_bf16 v[86:89], v[150:153], v[204:207], v[86:89]
	v_mfma_f32_16x16x32_bf16 v[82:85], v[158:161], v[204:207], v[82:85]
	v_mfma_f32_16x16x32_bf16 v[70:73], v[150:153], v[212:215], v[70:73]
	v_mfma_f32_16x16x32_bf16 v[66:69], v[158:161], v[212:215], v[66:69]
	v_mfma_f32_16x16x32_bf16 v[118:121], v[154:157], v[192:195], v[118:121]
	v_mfma_f32_16x16x32_bf16 v[114:117], v[168:171], v[192:195], v[114:117]
	v_mfma_f32_16x16x32_bf16 v[102:105], v[154:157], v[200:203], v[102:105]
	v_mfma_f32_16x16x32_bf16 v[98:101], v[168:171], v[200:203], v[98:101]
	v_mfma_f32_16x16x32_bf16 v[86:89], v[154:157], v[208:211], v[86:89]
	v_mfma_f32_16x16x32_bf16 v[82:85], v[168:171], v[208:211], v[82:85]
	v_mfma_f32_16x16x32_bf16 v[70:73], v[154:157], v[216:219], v[70:73]
	v_mfma_f32_16x16x32_bf16 v[66:69], v[168:171], v[216:219], v[66:69]
	s_setprio 0
	s_setprio 1
	v_mfma_f32_16x16x32_bf16 v[126:129], v[172:175], v[188:191], v[126:129]
	v_mfma_f32_16x16x32_bf16 v[122:125], v[180:183], v[188:191], v[122:125]
	v_mfma_f32_16x16x32_bf16 v[110:113], v[172:175], v[196:199], v[110:113]
	v_mfma_f32_16x16x32_bf16 v[106:109], v[180:183], v[196:199], v[106:109]
	v_mfma_f32_16x16x32_bf16 v[94:97], v[172:175], v[204:207], v[94:97]
	v_mfma_f32_16x16x32_bf16 v[90:93], v[180:183], v[204:207], v[90:93]
	v_mfma_f32_16x16x32_bf16 v[78:81], v[172:175], v[212:215], v[78:81]
	v_mfma_f32_16x16x32_bf16 v[74:77], v[180:183], v[212:215], v[74:77]
	v_mfma_f32_16x16x32_bf16 v[126:129], v[176:179], v[192:195], v[126:129]
	v_mfma_f32_16x16x32_bf16 v[122:125], v[184:187], v[192:195], v[122:125]
	v_mfma_f32_16x16x32_bf16 v[110:113], v[176:179], v[200:203], v[110:113]
	v_mfma_f32_16x16x32_bf16 v[106:109], v[184:187], v[200:203], v[106:109]
	v_mfma_f32_16x16x32_bf16 v[94:97], v[176:179], v[208:211], v[94:97]
	v_mfma_f32_16x16x32_bf16 v[90:93], v[184:187], v[208:211], v[90:93]
	v_mfma_f32_16x16x32_bf16 v[78:81], v[176:179], v[216:219], v[78:81]
	v_mfma_f32_16x16x32_bf16 v[74:77], v[184:187], v[216:219], v[74:77]
	s_barrier
	s_setprio 0
	s_mov_b32 m0, vcc_hi
	s_mov_b64 s[98:99], s[6:7]
	s_add_u32 s16, s6, 0x100000
	ds_read_b128 v[188:191], v165 offset:16384
	ds_read_b128 v[192:195], v165 offset:17408
	ds_read_b128 v[196:199], v165 offset:18432
	ds_read_b128 v[200:203], v165 offset:19456
	ds_read_b128 v[204:207], v165 offset:20480
	ds_read_b128 v[208:211], v165 offset:21504
	ds_read_b128 v[212:215], v165 offset:22528
	ds_read_b128 v[216:219], v165 offset:23552
	global_load_lds_dwordx4 v134, s[6:7]
	s_mov_b32 m0, s84
	s_addc_u32 s17, s7, 0
	global_load_lds_dwordx4 v130, s[6:7]
	s_mov_b32 m0, s85
	s_mov_b64 s[100:101], s[82:83]
	global_load_lds_dwordx4 v134, s[16:17]
	s_mov_b32 m0, s46
	s_nop 0
	global_load_lds_dwordx4 v130, s[16:17]
	s_waitcnt vmcnt(6)
	s_waitcnt lgkmcnt(0)
	s_setprio 1
	s_barrier
	v_mfma_f32_16x16x32_bf16 v[54:57], v[150:153], v[188:191], v[54:57]
	v_mfma_f32_16x16x32_bf16 v[50:53], v[158:161], v[188:191], v[50:53]
	v_mfma_f32_16x16x32_bf16 v[38:41], v[150:153], v[196:199], v[38:41]
	v_mfma_f32_16x16x32_bf16 v[34:37], v[158:161], v[196:199], v[34:37]
	v_mfma_f32_16x16x32_bf16 v[22:25], v[150:153], v[204:207], v[22:25]
	v_mfma_f32_16x16x32_bf16 v[18:21], v[158:161], v[204:207], v[18:21]
	v_mfma_f32_16x16x32_bf16 v[6:9], v[150:153], v[212:215], v[6:9]
	v_mfma_f32_16x16x32_bf16 v[2:5], v[158:161], v[212:215], v[2:5]
	v_mfma_f32_16x16x32_bf16 v[54:57], v[154:157], v[192:195], v[54:57]
	v_mfma_f32_16x16x32_bf16 v[50:53], v[168:171], v[192:195], v[50:53]
	v_mfma_f32_16x16x32_bf16 v[38:41], v[154:157], v[200:203], v[38:41]
	v_mfma_f32_16x16x32_bf16 v[34:37], v[168:171], v[200:203], v[34:37]
	v_mfma_f32_16x16x32_bf16 v[22:25], v[154:157], v[208:211], v[22:25]
	v_mfma_f32_16x16x32_bf16 v[18:21], v[168:171], v[208:211], v[18:21]
	v_mfma_f32_16x16x32_bf16 v[6:9], v[154:157], v[216:219], v[6:9]
	v_mfma_f32_16x16x32_bf16 v[2:5], v[168:171], v[216:219], v[2:5]
	s_setprio 0
	s_setprio 1
	v_mfma_f32_16x16x32_bf16 v[62:65], v[172:175], v[188:191], v[62:65]
	v_mfma_f32_16x16x32_bf16 v[58:61], v[180:183], v[188:191], v[58:61]
	v_mfma_f32_16x16x32_bf16 v[46:49], v[172:175], v[196:199], v[46:49]
	v_mfma_f32_16x16x32_bf16 v[42:45], v[180:183], v[196:199], v[42:45]
	v_mfma_f32_16x16x32_bf16 v[30:33], v[172:175], v[204:207], v[30:33]
	v_mfma_f32_16x16x32_bf16 v[26:29], v[180:183], v[204:207], v[26:29]
	v_mfma_f32_16x16x32_bf16 v[14:17], v[172:175], v[212:215], v[14:17]
	v_mfma_f32_16x16x32_bf16 v[10:13], v[180:183], v[212:215], v[10:13]
	v_mfma_f32_16x16x32_bf16 v[62:65], v[176:179], v[192:195], v[62:65]
	v_mfma_f32_16x16x32_bf16 v[58:61], v[184:187], v[192:195], v[58:61]
	v_mfma_f32_16x16x32_bf16 v[46:49], v[176:179], v[200:203], v[46:49]
	v_mfma_f32_16x16x32_bf16 v[42:45], v[184:187], v[200:203], v[42:45]
	v_mfma_f32_16x16x32_bf16 v[30:33], v[176:179], v[208:211], v[30:33]
	v_mfma_f32_16x16x32_bf16 v[26:29], v[184:187], v[208:211], v[26:29]
	v_mfma_f32_16x16x32_bf16 v[14:17], v[176:179], v[216:219], v[14:17]
	v_mfma_f32_16x16x32_bf16 v[10:13], v[184:187], v[216:219], v[10:13]
	s_barrier
	s_setprio 0
	ds_read_b128 v[150:153], v138
	ds_read_b128 v[154:157], v138 offset:1024
	ds_read_b128 v[158:161], v138 offset:2048
	ds_read_b128 v[168:171], v138 offset:3072
	ds_read_b128 v[172:175], v148
	ds_read_b128 v[176:179], v148 offset:1024
	ds_read_b128 v[180:183], v148 offset:2048
	ds_read_b128 v[184:187], v148 offset:3072
	s_add_u32 s16, s82, 0x100000
	s_addc_u32 s17, s83, 0
	s_mov_b32 m0, s86
	s_nop 0
	global_load_lds_dwordx4 v136, s[100:101]
	s_mov_b32 m0, s93
	s_nop 0
	global_load_lds_dwordx4 v132, s[100:101]
	s_mov_b32 m0, s94
	ds_read_b128 v[188:191], v165 offset:32768
	ds_read_b128 v[192:195], v165 offset:33792
	ds_read_b128 v[196:199], v165 offset:34816
	ds_read_b128 v[200:203], v165 offset:35840
	ds_read_b128 v[204:207], v165 offset:36864
	ds_read_b128 v[208:211], v165 offset:37888
	ds_read_b128 v[212:215], v165 offset:38912
	ds_read_b128 v[216:219], v165 offset:39936
	global_load_lds_dwordx4 v136, s[16:17]
	s_mov_b32 m0, s95
	s_nop 0
	global_load_lds_dwordx4 v132, s[16:17]
	s_waitcnt vmcnt(8)
	s_waitcnt lgkmcnt(0)
	s_setprio 1
	s_barrier
	v_mfma_f32_16x16x32_bf16 v[118:121], v[150:153], v[188:191], v[118:121]
	v_mfma_f32_16x16x32_bf16 v[114:117], v[158:161], v[188:191], v[114:117]
	v_mfma_f32_16x16x32_bf16 v[102:105], v[150:153], v[196:199], v[102:105]
	v_mfma_f32_16x16x32_bf16 v[98:101], v[158:161], v[196:199], v[98:101]
	v_mfma_f32_16x16x32_bf16 v[86:89], v[150:153], v[204:207], v[86:89]
	v_mfma_f32_16x16x32_bf16 v[82:85], v[158:161], v[204:207], v[82:85]
	v_mfma_f32_16x16x32_bf16 v[70:73], v[150:153], v[212:215], v[70:73]
	v_mfma_f32_16x16x32_bf16 v[66:69], v[158:161], v[212:215], v[66:69]
	v_mfma_f32_16x16x32_bf16 v[118:121], v[154:157], v[192:195], v[118:121]
	v_mfma_f32_16x16x32_bf16 v[114:117], v[168:171], v[192:195], v[114:117]
	v_mfma_f32_16x16x32_bf16 v[102:105], v[154:157], v[200:203], v[102:105]
	v_mfma_f32_16x16x32_bf16 v[98:101], v[168:171], v[200:203], v[98:101]
	v_mfma_f32_16x16x32_bf16 v[86:89], v[154:157], v[208:211], v[86:89]
	v_mfma_f32_16x16x32_bf16 v[82:85], v[168:171], v[208:211], v[82:85]
	v_mfma_f32_16x16x32_bf16 v[70:73], v[154:157], v[216:219], v[70:73]
	v_mfma_f32_16x16x32_bf16 v[66:69], v[168:171], v[216:219], v[66:69]
	s_setprio 0
	s_setprio 1
	v_mfma_f32_16x16x32_bf16 v[126:129], v[172:175], v[188:191], v[126:129]
	v_mfma_f32_16x16x32_bf16 v[122:125], v[180:183], v[188:191], v[122:125]
	v_mfma_f32_16x16x32_bf16 v[110:113], v[172:175], v[196:199], v[110:113]
	v_mfma_f32_16x16x32_bf16 v[106:109], v[180:183], v[196:199], v[106:109]
	v_mfma_f32_16x16x32_bf16 v[94:97], v[172:175], v[204:207], v[94:97]
	v_mfma_f32_16x16x32_bf16 v[90:93], v[180:183], v[204:207], v[90:93]
	v_mfma_f32_16x16x32_bf16 v[78:81], v[172:175], v[212:215], v[78:81]
	v_mfma_f32_16x16x32_bf16 v[74:77], v[180:183], v[212:215], v[74:77]
	v_mfma_f32_16x16x32_bf16 v[126:129], v[176:179], v[192:195], v[126:129]
	v_mfma_f32_16x16x32_bf16 v[122:125], v[184:187], v[192:195], v[122:125]
	v_mfma_f32_16x16x32_bf16 v[110:113], v[176:179], v[200:203], v[110:113]
	v_mfma_f32_16x16x32_bf16 v[106:109], v[184:187], v[200:203], v[106:109]
	v_mfma_f32_16x16x32_bf16 v[94:97], v[176:179], v[208:211], v[94:97]
	v_mfma_f32_16x16x32_bf16 v[90:93], v[184:187], v[208:211], v[90:93]
	v_mfma_f32_16x16x32_bf16 v[78:81], v[176:179], v[216:219], v[78:81]
	v_mfma_f32_16x16x32_bf16 v[74:77], v[184:187], v[216:219], v[74:77]
	s_barrier
	s_setprio 0
	s_mov_b32 m0, s47
	s_add_u32 s98, s98, 0x80
	s_addc_u32 s99, s99, 0
	s_add_u32 s100, s100, 0x80
	s_addc_u32 s101, s101, 0
	s_add_u32 s6, s6, 0x100080
	ds_read_b128 v[188:191], v165 offset:49152
	ds_read_b128 v[192:195], v165 offset:50176
	ds_read_b128 v[196:199], v165 offset:51200
	ds_read_b128 v[200:203], v165 offset:52224
	ds_read_b128 v[204:207], v165 offset:53248
	ds_read_b128 v[208:211], v165 offset:54272
	ds_read_b128 v[212:215], v165 offset:55296
	ds_read_b128 v[216:219], v165 offset:56320
	global_load_lds_dwordx4 v134, s[98:99]
	s_mov_b32 m0, s91
	s_addc_u32 s7, s7, 0
	global_load_lds_dwordx4 v130, s[98:99]
	s_mov_b32 m0, s56
	s_nop 0
	global_load_lds_dwordx4 v134, s[6:7]
	s_mov_b32 m0, s57
	s_nop 0
	global_load_lds_dwordx4 v130, s[6:7]
	s_mov_b32 m0, s96
	s_nop 0
	global_load_lds_dwordx4 v136, s[100:101]
	s_mov_b32 m0, s97
	s_nop 0
	global_load_lds_dwordx4 v132, s[100:101]
	s_waitcnt vmcnt(8)
	s_waitcnt lgkmcnt(0)
	s_setprio 1
	s_barrier
	v_mfma_f32_16x16x32_bf16 v[54:57], v[150:153], v[188:191], v[54:57]
	v_mfma_f32_16x16x32_bf16 v[50:53], v[158:161], v[188:191], v[50:53]
	v_mfma_f32_16x16x32_bf16 v[38:41], v[150:153], v[196:199], v[38:41]
	v_mfma_f32_16x16x32_bf16 v[34:37], v[158:161], v[196:199], v[34:37]
	v_mfma_f32_16x16x32_bf16 v[22:25], v[150:153], v[204:207], v[22:25]
	v_mfma_f32_16x16x32_bf16 v[18:21], v[158:161], v[204:207], v[18:21]
	v_mfma_f32_16x16x32_bf16 v[6:9], v[150:153], v[212:215], v[6:9]
	v_mfma_f32_16x16x32_bf16 v[2:5], v[158:161], v[212:215], v[2:5]
	v_mfma_f32_16x16x32_bf16 v[54:57], v[154:157], v[192:195], v[54:57]
	v_mfma_f32_16x16x32_bf16 v[50:53], v[168:171], v[192:195], v[50:53]
	v_mfma_f32_16x16x32_bf16 v[38:41], v[154:157], v[200:203], v[38:41]
	v_mfma_f32_16x16x32_bf16 v[34:37], v[168:171], v[200:203], v[34:37]
	v_mfma_f32_16x16x32_bf16 v[22:25], v[154:157], v[208:211], v[22:25]
	v_mfma_f32_16x16x32_bf16 v[18:21], v[168:171], v[208:211], v[18:21]
	v_mfma_f32_16x16x32_bf16 v[6:9], v[154:157], v[216:219], v[6:9]
	v_mfma_f32_16x16x32_bf16 v[2:5], v[168:171], v[216:219], v[2:5]
	s_setprio 0
	s_setprio 1
	v_mfma_f32_16x16x32_bf16 v[62:65], v[172:175], v[188:191], v[62:65]
	v_mfma_f32_16x16x32_bf16 v[58:61], v[180:183], v[188:191], v[58:61]
	v_mfma_f32_16x16x32_bf16 v[46:49], v[172:175], v[196:199], v[46:49]
	v_mfma_f32_16x16x32_bf16 v[42:45], v[180:183], v[196:199], v[42:45]
	v_mfma_f32_16x16x32_bf16 v[30:33], v[172:175], v[204:207], v[30:33]
	v_mfma_f32_16x16x32_bf16 v[26:29], v[180:183], v[204:207], v[26:29]
	v_mfma_f32_16x16x32_bf16 v[14:17], v[172:175], v[212:215], v[14:17]
	v_mfma_f32_16x16x32_bf16 v[10:13], v[180:183], v[212:215], v[10:13]
	v_mfma_f32_16x16x32_bf16 v[62:65], v[176:179], v[192:195], v[62:65]
	v_mfma_f32_16x16x32_bf16 v[58:61], v[184:187], v[192:195], v[58:61]
	v_mfma_f32_16x16x32_bf16 v[46:49], v[176:179], v[200:203], v[46:49]
	v_mfma_f32_16x16x32_bf16 v[42:45], v[184:187], v[200:203], v[42:45]
	v_mfma_f32_16x16x32_bf16 v[30:33], v[176:179], v[208:211], v[30:33]
	v_mfma_f32_16x16x32_bf16 v[26:29], v[184:187], v[208:211], v[26:29]
	v_mfma_f32_16x16x32_bf16 v[14:17], v[176:179], v[216:219], v[14:17]
	v_mfma_f32_16x16x32_bf16 v[10:13], v[184:187], v[216:219], v[10:13]
	s_barrier
	s_setprio 0
	s_add_i32 s15, s15, 2
	s_add_u32 s80, s80, 0x100
	s_addc_u32 s81, s81, 0
	s_add_u32 s30, s30, 0x100
	s_addc_u32 s14, s14, 0
	s_cmp_gt_u32 s15, 61
	s_cbranch_scc0 .LBB0_415
	s_and_b64 vcc, exec, s[64:65]
	s_cbranch_vccz .LBB0_418
	s_barrier

.LBB0_435:
	ds_read_b128 v[146:149], v141
	ds_read_b128 v[150:153], v141 offset:1024
	ds_read_b128 v[154:157], v141 offset:2048
	ds_read_b128 v[158:161], v141 offset:3072
	ds_read_b128 v[162:165], v142
	ds_read_b128 v[166:169], v142 offset:1024
	ds_read_b128 v[170:173], v142 offset:2048
	ds_read_b128 v[174:177], v142 offset:3072
	s_add_u32 s17, s78, 0xfff00080
	s_addc_u32 s20, s79, -1
	s_cmp_eq_u32 s16, 60
	s_cselect_b32 s81, s9, s20
	s_cselect_b32 s80, s67, s17
	s_cselect_b32 s77, s18, s15
	s_cselect_b32 s76, s95, s14
	s_mov_b32 m0, s96
	ds_read_b128 v[178:181], v143
	ds_read_b128 v[182:185], v143 offset:1024
	ds_read_b128 v[186:189], v143 offset:2048
	ds_read_b128 v[190:193], v143 offset:3072
	ds_read_b128 v[194:197], v143 offset:4096
	ds_read_b128 v[198:201], v143 offset:5120
	ds_read_b128 v[202:205], v143 offset:6144
	ds_read_b128 v[206:209], v143 offset:7168
	global_load_lds_dwordx4 v136, s[78:79]
	s_mov_b32 m0, s97
	s_nop 0
	global_load_lds_dwordx4 v138, s[78:79]
	s_waitcnt vmcnt(8)
	s_waitcnt lgkmcnt(0)
	s_setprio 1
	s_barrier
	v_mfma_f32_16x16x32_bf16 v[34:37], v[146:149], v[178:181], v[34:37]
	v_mfma_f32_16x16x32_bf16 v[38:41], v[154:157], v[178:181], v[38:41]
	v_mfma_f32_16x16x32_bf16 v[18:21], v[146:149], v[186:189], v[18:21]
	v_mfma_f32_16x16x32_bf16 v[22:25], v[154:157], v[186:189], v[22:25]
	v_mfma_f32_16x16x32_bf16 v[10:13], v[146:149], v[194:197], v[10:13]
	v_mfma_f32_16x16x32_bf16 v[14:17], v[154:157], v[194:197], v[14:17]
	v_mfma_f32_16x16x32_bf16 v[2:5], v[146:149], v[202:205], v[2:5]
	v_mfma_f32_16x16x32_bf16 v[6:9], v[154:157], v[202:205], v[6:9]
	v_mfma_f32_16x16x32_bf16 v[34:37], v[150:153], v[182:185], v[34:37]
	v_mfma_f32_16x16x32_bf16 v[38:41], v[158:161], v[182:185], v[38:41]
	v_mfma_f32_16x16x32_bf16 v[18:21], v[150:153], v[190:193], v[18:21]
	v_mfma_f32_16x16x32_bf16 v[22:25], v[158:161], v[190:193], v[22:25]
	v_mfma_f32_16x16x32_bf16 v[10:13], v[150:153], v[198:201], v[10:13]
	v_mfma_f32_16x16x32_bf16 v[14:17], v[158:161], v[198:201], v[14:17]
	v_mfma_f32_16x16x32_bf16 v[2:5], v[150:153], v[206:209], v[2:5]
	v_mfma_f32_16x16x32_bf16 v[6:9], v[158:161], v[206:209], v[6:9]
	s_setprio 0
	s_setprio 1
	v_mfma_f32_16x16x32_bf16 v[66:69], v[162:165], v[178:181], v[66:69]
	v_mfma_f32_16x16x32_bf16 v[70:73], v[170:173], v[178:181], v[70:73]
	v_mfma_f32_16x16x32_bf16 v[54:57], v[162:165], v[186:189], v[54:57]
	v_mfma_f32_16x16x32_bf16 v[62:65], v[170:173], v[186:189], v[62:65]
	v_mfma_f32_16x16x32_bf16 v[42:45], v[162:165], v[194:197], v[42:45]
	v_mfma_f32_16x16x32_bf16 v[46:49], v[170:173], v[194:197], v[46:49]
	v_mfma_f32_16x16x32_bf16 v[26:29], v[162:165], v[202:205], v[26:29]
	v_mfma_f32_16x16x32_bf16 v[30:33], v[170:173], v[202:205], v[30:33]
	v_mfma_f32_16x16x32_bf16 v[66:69], v[166:169], v[182:185], v[66:69]
	v_mfma_f32_16x16x32_bf16 v[70:73], v[174:177], v[182:185], v[70:73]
	v_mfma_f32_16x16x32_bf16 v[54:57], v[166:169], v[190:193], v[54:57]
	v_mfma_f32_16x16x32_bf16 v[62:65], v[174:177], v[190:193], v[62:65]
	v_mfma_f32_16x16x32_bf16 v[42:45], v[166:169], v[198:201], v[42:45]
	v_mfma_f32_16x16x32_bf16 v[46:49], v[174:177], v[198:201], v[46:49]
	v_mfma_f32_16x16x32_bf16 v[26:29], v[166:169], v[206:209], v[26:29]
	v_mfma_f32_16x16x32_bf16 v[30:33], v[174:177], v[206:209], v[30:33]
	s_barrier
	s_setprio 0
	s_mov_b32 m0, vcc_lo
	s_mov_b64 s[98:99], s[76:77]
	s_add_u32 s20, s76, 0x100000
	ds_read_b128 v[178:181], v143 offset:16384
	ds_read_b128 v[182:185], v143 offset:17408
	ds_read_b128 v[186:189], v143 offset:18432
	ds_read_b128 v[190:193], v143 offset:19456
	ds_read_b128 v[194:197], v143 offset:20480
	ds_read_b128 v[198:201], v143 offset:21504
	ds_read_b128 v[202:205], v143 offset:22528
	ds_read_b128 v[206:209], v143 offset:23552
	global_load_lds_dwordx4 v132, s[76:77]
	s_mov_b32 m0, s84
	s_addc_u32 s21, s77, 0
	global_load_lds_dwordx4 v130, s[76:77]
	s_mov_b32 m0, s85
	s_mov_b64 s[100:101], s[80:81]
	global_load_lds_dwordx4 v132, s[20:21]
	s_mov_b32 m0, s46
	s_nop 0
	global_load_lds_dwordx4 v130, s[20:21]
	s_waitcnt vmcnt(6)
	s_waitcnt lgkmcnt(0)
	s_setprio 1
	s_barrier
	v_mfma_f32_16x16x32_bf16 v[102:105], v[146:149], v[178:181], v[102:105]
	v_mfma_f32_16x16x32_bf16 v[110:113], v[154:157], v[178:181], v[110:113]
	v_mfma_f32_16x16x32_bf16 v[90:93], v[146:149], v[186:189], v[90:93]
	v_mfma_f32_16x16x32_bf16 v[94:97], v[154:157], v[186:189], v[94:97]
	v_mfma_f32_16x16x32_bf16 v[74:77], v[146:149], v[194:197], v[74:77]
	v_mfma_f32_16x16x32_bf16 v[78:81], v[154:157], v[194:197], v[78:81]
	v_mfma_f32_16x16x32_bf16 v[50:53], v[146:149], v[202:205], v[50:53]
	v_mfma_f32_16x16x32_bf16 v[58:61], v[154:157], v[202:205], v[58:61]
	v_mfma_f32_16x16x32_bf16 v[102:105], v[150:153], v[182:185], v[102:105]
	v_mfma_f32_16x16x32_bf16 v[110:113], v[158:161], v[182:185], v[110:113]
	v_mfma_f32_16x16x32_bf16 v[90:93], v[150:153], v[190:193], v[90:93]
	v_mfma_f32_16x16x32_bf16 v[94:97], v[158:161], v[190:193], v[94:97]
	v_mfma_f32_16x16x32_bf16 v[74:77], v[150:153], v[198:201], v[74:77]
	v_mfma_f32_16x16x32_bf16 v[78:81], v[158:161], v[198:201], v[78:81]
	v_mfma_f32_16x16x32_bf16 v[50:53], v[150:153], v[206:209], v[50:53]
	v_mfma_f32_16x16x32_bf16 v[58:61], v[158:161], v[206:209], v[58:61]
	s_setprio 0
	s_setprio 1
	v_mfma_f32_16x16x32_bf16 v[122:125], v[162:165], v[178:181], v[122:125]
	v_mfma_f32_16x16x32_bf16 v[126:129], v[170:173], v[178:181], v[126:129]
	v_mfma_f32_16x16x32_bf16 v[114:117], v[162:165], v[186:189], v[114:117]
	v_mfma_f32_16x16x32_bf16 v[118:121], v[170:173], v[186:189], v[118:121]
	v_mfma_f32_16x16x32_bf16 v[98:101], v[162:165], v[194:197], v[98:101]
	v_mfma_f32_16x16x32_bf16 v[106:109], v[170:173], v[194:197], v[106:109]
	v_mfma_f32_16x16x32_bf16 v[82:85], v[162:165], v[202:205], v[82:85]
	v_mfma_f32_16x16x32_bf16 v[86:89], v[170:173], v[202:205], v[86:89]
	v_mfma_f32_16x16x32_bf16 v[122:125], v[166:169], v[182:185], v[122:125]
	v_mfma_f32_16x16x32_bf16 v[126:129], v[174:177], v[182:185], v[126:129]
	v_mfma_f32_16x16x32_bf16 v[114:117], v[166:169], v[190:193], v[114:117]
	v_mfma_f32_16x16x32_bf16 v[118:121], v[174:177], v[190:193], v[118:121]
	v_mfma_f32_16x16x32_bf16 v[98:101], v[166:169], v[198:201], v[98:101]
	v_mfma_f32_16x16x32_bf16 v[106:109], v[174:177], v[198:201], v[106:109]
	v_mfma_f32_16x16x32_bf16 v[82:85], v[166:169], v[206:209], v[82:85]
	v_mfma_f32_16x16x32_bf16 v[86:89], v[174:177], v[206:209], v[86:89]
	s_barrier
	s_setprio 0
	ds_read_b128 v[146:149], v134
	ds_read_b128 v[150:153], v134 offset:1024
	ds_read_b128 v[154:157], v134 offset:2048
	ds_read_b128 v[158:161], v134 offset:3072
	ds_read_b128 v[162:165], v144
	ds_read_b128 v[166:169], v144 offset:1024
	ds_read_b128 v[170:173], v144 offset:2048
	ds_read_b128 v[174:177], v144 offset:3072
	s_add_u32 s20, s80, 0x100000
	s_addc_u32 s21, s81, 0
	s_mov_b32 m0, s59
	s_nop 0
	global_load_lds_dwordx4 v132, s[100:101]
	s_mov_b32 m0, s82
	s_nop 0
	global_load_lds_dwordx4 v130, s[100:101]
	s_mov_b32 m0, s83
	ds_read_b128 v[178:181], v143 offset:32768
	ds_read_b128 v[182:185], v143 offset:33792
	ds_read_b128 v[186:189], v143 offset:34816
	ds_read_b128 v[190:193], v143 offset:35840
	ds_read_b128 v[194:197], v143 offset:36864
	ds_read_b128 v[198:201], v143 offset:37888
	ds_read_b128 v[202:205], v143 offset:38912
	ds_read_b128 v[206:209], v143 offset:39936
	global_load_lds_dwordx4 v132, s[20:21]
	s_mov_b32 m0, s86
	s_nop 0
	global_load_lds_dwordx4 v130, s[20:21]
	s_waitcnt vmcnt(8)
	s_waitcnt lgkmcnt(0)
	s_setprio 1
	s_barrier
	v_mfma_f32_16x16x32_bf16 v[34:37], v[146:149], v[178:181], v[34:37]
	v_mfma_f32_16x16x32_bf16 v[38:41], v[154:157], v[178:181], v[38:41]
	v_mfma_f32_16x16x32_bf16 v[18:21], v[146:149], v[186:189], v[18:21]
	v_mfma_f32_16x16x32_bf16 v[22:25], v[154:157], v[186:189], v[22:25]
	v_mfma_f32_16x16x32_bf16 v[10:13], v[146:149], v[194:197], v[10:13]
	v_mfma_f32_16x16x32_bf16 v[14:17], v[154:157], v[194:197], v[14:17]
	v_mfma_f32_16x16x32_bf16 v[2:5], v[146:149], v[202:205], v[2:5]
	v_mfma_f32_16x16x32_bf16 v[6:9], v[154:157], v[202:205], v[6:9]
	v_mfma_f32_16x16x32_bf16 v[34:37], v[150:153], v[182:185], v[34:37]
	v_mfma_f32_16x16x32_bf16 v[38:41], v[158:161], v[182:185], v[38:41]
	v_mfma_f32_16x16x32_bf16 v[18:21], v[150:153], v[190:193], v[18:21]
	v_mfma_f32_16x16x32_bf16 v[22:25], v[158:161], v[190:193], v[22:25]
	v_mfma_f32_16x16x32_bf16 v[10:13], v[150:153], v[198:201], v[10:13]
	v_mfma_f32_16x16x32_bf16 v[14:17], v[158:161], v[198:201], v[14:17]
	v_mfma_f32_16x16x32_bf16 v[2:5], v[150:153], v[206:209], v[2:5]
	v_mfma_f32_16x16x32_bf16 v[6:9], v[158:161], v[206:209], v[6:9]
	s_setprio 0
	s_setprio 1
	v_mfma_f32_16x16x32_bf16 v[66:69], v[162:165], v[178:181], v[66:69]
	v_mfma_f32_16x16x32_bf16 v[70:73], v[170:173], v[178:181], v[70:73]
	v_mfma_f32_16x16x32_bf16 v[54:57], v[162:165], v[186:189], v[54:57]
	v_mfma_f32_16x16x32_bf16 v[62:65], v[170:173], v[186:189], v[62:65]
	v_mfma_f32_16x16x32_bf16 v[42:45], v[162:165], v[194:197], v[42:45]
	v_mfma_f32_16x16x32_bf16 v[46:49], v[170:173], v[194:197], v[46:49]
	v_mfma_f32_16x16x32_bf16 v[26:29], v[162:165], v[202:205], v[26:29]
	v_mfma_f32_16x16x32_bf16 v[30:33], v[170:173], v[202:205], v[30:33]
	v_mfma_f32_16x16x32_bf16 v[66:69], v[166:169], v[182:185], v[66:69]
	v_mfma_f32_16x16x32_bf16 v[70:73], v[174:177], v[182:185], v[70:73]
	v_mfma_f32_16x16x32_bf16 v[54:57], v[166:169], v[190:193], v[54:57]
	v_mfma_f32_16x16x32_bf16 v[62:65], v[174:177], v[190:193], v[62:65]
	v_mfma_f32_16x16x32_bf16 v[42:45], v[166:169], v[198:201], v[42:45]
	v_mfma_f32_16x16x32_bf16 v[46:49], v[174:177], v[198:201], v[46:49]
	v_mfma_f32_16x16x32_bf16 v[26:29], v[166:169], v[206:209], v[26:29]
	v_mfma_f32_16x16x32_bf16 v[30:33], v[174:177], v[206:209], v[30:33]
	s_barrier
	s_setprio 0
	s_mov_b32 m0, s47
	s_add_u32 s98, s98, 0x80
	s_addc_u32 s99, s99, 0
	s_add_u32 s100, s100, 0x80
	s_addc_u32 s101, s101, 0
	s_add_u32 s20, s76, 0x100080
	ds_read_b128 v[178:181], v143 offset:49152
	ds_read_b128 v[182:185], v143 offset:50176
	ds_read_b128 v[186:189], v143 offset:51200
	ds_read_b128 v[190:193], v143 offset:52224
	ds_read_b128 v[194:197], v143 offset:53248
	ds_read_b128 v[198:201], v143 offset:54272
	ds_read_b128 v[202:205], v143 offset:55296
	ds_read_b128 v[206:209], v143 offset:56320
	global_load_lds_dwordx4 v132, s[98:99]
	s_mov_b32 m0, vcc_hi
	s_addc_u32 s21, s77, 0
	global_load_lds_dwordx4 v130, s[98:99]
	s_mov_b32 m0, s56
	s_nop 0
	global_load_lds_dwordx4 v132, s[20:21]
	s_mov_b32 m0, s57
	s_nop 0
	global_load_lds_dwordx4 v130, s[20:21]
	s_mov_b32 m0, s88
	s_nop 0
	global_load_lds_dwordx4 v132, s[100:101]
	s_mov_b32 m0, s89
	s_nop 0
	global_load_lds_dwordx4 v130, s[100:101]
	s_waitcnt vmcnt(8)
	s_waitcnt lgkmcnt(0)
	s_setprio 1
	s_barrier
	v_mfma_f32_16x16x32_bf16 v[102:105], v[146:149], v[178:181], v[102:105]
	v_mfma_f32_16x16x32_bf16 v[110:113], v[154:157], v[178:181], v[110:113]
	v_mfma_f32_16x16x32_bf16 v[90:93], v[146:149], v[186:189], v[90:93]
	v_mfma_f32_16x16x32_bf16 v[94:97], v[154:157], v[186:189], v[94:97]
	v_mfma_f32_16x16x32_bf16 v[74:77], v[146:149], v[194:197], v[74:77]
	v_mfma_f32_16x16x32_bf16 v[78:81], v[154:157], v[194:197], v[78:81]
	v_mfma_f32_16x16x32_bf16 v[50:53], v[146:149], v[202:205], v[50:53]
	v_mfma_f32_16x16x32_bf16 v[58:61], v[154:157], v[202:205], v[58:61]
	v_mfma_f32_16x16x32_bf16 v[102:105], v[150:153], v[182:185], v[102:105]
	v_mfma_f32_16x16x32_bf16 v[110:113], v[158:161], v[182:185], v[110:113]
	v_mfma_f32_16x16x32_bf16 v[90:93], v[150:153], v[190:193], v[90:93]
	v_mfma_f32_16x16x32_bf16 v[94:97], v[158:161], v[190:193], v[94:97]
	v_mfma_f32_16x16x32_bf16 v[74:77], v[150:153], v[198:201], v[74:77]
	v_mfma_f32_16x16x32_bf16 v[78:81], v[158:161], v[198:201], v[78:81]
	v_mfma_f32_16x16x32_bf16 v[50:53], v[150:153], v[206:209], v[50:53]
	v_mfma_f32_16x16x32_bf16 v[58:61], v[158:161], v[206:209], v[58:61]
	s_setprio 0
	s_setprio 1
	v_mfma_f32_16x16x32_bf16 v[122:125], v[162:165], v[178:181], v[122:125]
	v_mfma_f32_16x16x32_bf16 v[126:129], v[170:173], v[178:181], v[126:129]
	v_mfma_f32_16x16x32_bf16 v[114:117], v[162:165], v[186:189], v[114:117]
	v_mfma_f32_16x16x32_bf16 v[118:121], v[170:173], v[186:189], v[118:121]
	v_mfma_f32_16x16x32_bf16 v[98:101], v[162:165], v[194:197], v[98:101]
	v_mfma_f32_16x16x32_bf16 v[106:109], v[170:173], v[194:197], v[106:109]
	v_mfma_f32_16x16x32_bf16 v[82:85], v[162:165], v[202:205], v[82:85]
	v_mfma_f32_16x16x32_bf16 v[86:89], v[170:173], v[202:205], v[86:89]
	v_mfma_f32_16x16x32_bf16 v[122:125], v[166:169], v[182:185], v[122:125]
	v_mfma_f32_16x16x32_bf16 v[126:129], v[174:177], v[182:185], v[126:129]
	v_mfma_f32_16x16x32_bf16 v[114:117], v[166:169], v[190:193], v[114:117]
	v_mfma_f32_16x16x32_bf16 v[118:121], v[174:177], v[190:193], v[118:121]
	v_mfma_f32_16x16x32_bf16 v[98:101], v[166:169], v[198:201], v[98:101]
	v_mfma_f32_16x16x32_bf16 v[106:109], v[174:177], v[198:201], v[106:109]
	v_mfma_f32_16x16x32_bf16 v[82:85], v[166:169], v[206:209], v[82:85]
	v_mfma_f32_16x16x32_bf16 v[86:89], v[174:177], v[206:209], v[86:89]
	s_barrier
	s_setprio 0
	s_add_i32 s16, s16, 2
	s_add_u32 s78, s78, 0x100
	s_addc_u32 s79, s79, 0
	s_add_u32 s14, s14, 0x100
	s_addc_u32 s15, s15, 0
	s_cmp_gt_u32 s16, 61
	s_cbranch_scc0 .LBB0_435
	s_and_b64 vcc, exec, s[30:31]
	s_cbranch_vccz .LBB0_438
	s_barrier

.LBB0_644:
	ds_read_b128 v[146:149], v1
	ds_read_b128 v[154:157], v1 offset:1024
	ds_read_b128 v[158:161], v1 offset:2048
	ds_read_b128 v[162:165], v1 offset:3072
	ds_read_b128 v[166:169], v150
	ds_read_b128 v[170:173], v150 offset:1024
	ds_read_b128 v[174:177], v150 offset:2048
	ds_read_b128 v[178:181], v150 offset:3072
	s_add_u32 s27, s62, 0xfffc0080
	s_addc_u32 s46, s63, -1
	s_cmp_eq_u32 s26, 12
	s_cselect_b32 s65, s23, s46
	s_cselect_b32 s64, s83, s27
	s_cselect_b32 s55, s0, s15
	s_cselect_b32 s54, s86, s14
	s_mov_b32 m0, s69
	ds_read_b128 v[182:185], v151
	ds_read_b128 v[186:189], v151 offset:1024
	ds_read_b128 v[190:193], v151 offset:2048
	ds_read_b128 v[194:197], v151 offset:3072
	ds_read_b128 v[198:201], v151 offset:4096
	ds_read_b128 v[202:205], v151 offset:5120
	ds_read_b128 v[206:209], v151 offset:6144
	ds_read_b128 v[210:213], v151 offset:7168
	global_load_lds_dwordx4 v138, s[62:63]
	s_mov_b32 m0, s70
	s_nop 0
	global_load_lds_dwordx4 v140, s[62:63]
	s_waitcnt vmcnt(8)
	s_waitcnt lgkmcnt(0)
	s_setprio 1
	s_barrier
	v_mfma_f32_16x16x32_bf16 v[122:125], v[146:149], v[182:185], v[122:125]
	v_mfma_f32_16x16x32_bf16 v[114:117], v[158:161], v[182:185], v[114:117]
	v_mfma_f32_16x16x32_bf16 v[106:109], v[146:149], v[190:193], v[106:109]
	v_mfma_f32_16x16x32_bf16 v[98:101], v[158:161], v[190:193], v[98:101]
	v_mfma_f32_16x16x32_bf16 v[90:93], v[146:149], v[198:201], v[90:93]
	v_mfma_f32_16x16x32_bf16 v[82:85], v[158:161], v[198:201], v[82:85]
	v_mfma_f32_16x16x32_bf16 v[58:61], v[146:149], v[206:209], v[58:61]
	v_mfma_f32_16x16x32_bf16 v[50:53], v[158:161], v[206:209], v[50:53]
	v_mfma_f32_16x16x32_bf16 v[122:125], v[154:157], v[186:189], v[122:125]
	v_mfma_f32_16x16x32_bf16 v[114:117], v[162:165], v[186:189], v[114:117]
	v_mfma_f32_16x16x32_bf16 v[106:109], v[154:157], v[194:197], v[106:109]
	v_mfma_f32_16x16x32_bf16 v[98:101], v[162:165], v[194:197], v[98:101]
	v_mfma_f32_16x16x32_bf16 v[90:93], v[154:157], v[202:205], v[90:93]
	v_mfma_f32_16x16x32_bf16 v[82:85], v[162:165], v[202:205], v[82:85]
	v_mfma_f32_16x16x32_bf16 v[58:61], v[154:157], v[210:213], v[58:61]
	v_mfma_f32_16x16x32_bf16 v[50:53], v[162:165], v[210:213], v[50:53]
	s_setprio 0
	s_setprio 1
	v_mfma_f32_16x16x32_bf16 v[126:129], v[166:169], v[182:185], v[126:129]
	v_mfma_f32_16x16x32_bf16 v[118:121], v[174:177], v[182:185], v[118:121]
	v_mfma_f32_16x16x32_bf16 v[110:113], v[166:169], v[190:193], v[110:113]
	v_mfma_f32_16x16x32_bf16 v[102:105], v[174:177], v[190:193], v[102:105]
	v_mfma_f32_16x16x32_bf16 v[94:97], v[166:169], v[198:201], v[94:97]
	v_mfma_f32_16x16x32_bf16 v[86:89], v[174:177], v[198:201], v[86:89]
	v_mfma_f32_16x16x32_bf16 v[62:65], v[166:169], v[206:209], v[62:65]
	v_mfma_f32_16x16x32_bf16 v[54:57], v[174:177], v[206:209], v[54:57]
	v_mfma_f32_16x16x32_bf16 v[126:129], v[170:173], v[186:189], v[126:129]
	v_mfma_f32_16x16x32_bf16 v[118:121], v[178:181], v[186:189], v[118:121]
	v_mfma_f32_16x16x32_bf16 v[110:113], v[170:173], v[194:197], v[110:113]
	v_mfma_f32_16x16x32_bf16 v[102:105], v[178:181], v[194:197], v[102:105]
	v_mfma_f32_16x16x32_bf16 v[94:97], v[170:173], v[202:205], v[94:97]
	v_mfma_f32_16x16x32_bf16 v[86:89], v[178:181], v[202:205], v[86:89]
	v_mfma_f32_16x16x32_bf16 v[62:65], v[170:173], v[210:213], v[62:65]
	v_mfma_f32_16x16x32_bf16 v[54:57], v[178:181], v[210:213], v[54:57]
	s_barrier
	s_setprio 0
	s_mov_b32 m0, s72
	s_mov_b64 s[98:99], s[54:55]
	s_add_u32 s46, s54, 0x40000
	ds_read_b128 v[182:185], v151 offset:16384
	ds_read_b128 v[186:189], v151 offset:17408
	ds_read_b128 v[190:193], v151 offset:18432
	ds_read_b128 v[194:197], v151 offset:19456
	ds_read_b128 v[198:201], v151 offset:20480
	ds_read_b128 v[202:205], v151 offset:21504
	ds_read_b128 v[206:209], v151 offset:22528
	ds_read_b128 v[210:213], v151 offset:23552
	global_load_lds_dwordx4 v134, s[54:55]
	s_mov_b32 m0, s73
	s_addc_u32 s47, s55, 0
	global_load_lds_dwordx4 v130, s[54:55]
	s_mov_b32 m0, s74
	s_mov_b64 s[100:101], s[64:65]
	global_load_lds_dwordx4 v134, s[46:47]
	s_mov_b32 m0, s75
	s_nop 0
	global_load_lds_dwordx4 v130, s[46:47]
	s_waitcnt vmcnt(6)
	s_waitcnt lgkmcnt(0)
	s_setprio 1
	s_barrier
	v_mfma_f32_16x16x32_bf16 v[74:77], v[146:149], v[182:185], v[74:77]
	v_mfma_f32_16x16x32_bf16 v[66:69], v[158:161], v[182:185], v[66:69]
	v_mfma_f32_16x16x32_bf16 v[42:45], v[146:149], v[190:193], v[42:45]
	v_mfma_f32_16x16x32_bf16 v[34:37], v[158:161], v[190:193], v[34:37]
	v_mfma_f32_16x16x32_bf16 v[26:29], v[146:149], v[198:201], v[26:29]
	v_mfma_f32_16x16x32_bf16 v[18:21], v[158:161], v[198:201], v[18:21]
	v_mfma_f32_16x16x32_bf16 v[10:13], v[146:149], v[206:209], v[10:13]
	v_mfma_f32_16x16x32_bf16 v[2:5], v[158:161], v[206:209], v[2:5]
	v_mfma_f32_16x16x32_bf16 v[74:77], v[154:157], v[186:189], v[74:77]
	v_mfma_f32_16x16x32_bf16 v[66:69], v[162:165], v[186:189], v[66:69]
	v_mfma_f32_16x16x32_bf16 v[42:45], v[154:157], v[194:197], v[42:45]
	v_mfma_f32_16x16x32_bf16 v[34:37], v[162:165], v[194:197], v[34:37]
	v_mfma_f32_16x16x32_bf16 v[26:29], v[154:157], v[202:205], v[26:29]
	v_mfma_f32_16x16x32_bf16 v[18:21], v[162:165], v[202:205], v[18:21]
	v_mfma_f32_16x16x32_bf16 v[10:13], v[154:157], v[210:213], v[10:13]
	v_mfma_f32_16x16x32_bf16 v[2:5], v[162:165], v[210:213], v[2:5]
	s_setprio 0
	s_setprio 1
	v_mfma_f32_16x16x32_bf16 v[78:81], v[166:169], v[182:185], v[78:81]
	v_mfma_f32_16x16x32_bf16 v[70:73], v[174:177], v[182:185], v[70:73]
	v_mfma_f32_16x16x32_bf16 v[46:49], v[166:169], v[190:193], v[46:49]
	v_mfma_f32_16x16x32_bf16 v[38:41], v[174:177], v[190:193], v[38:41]
	v_mfma_f32_16x16x32_bf16 v[30:33], v[166:169], v[198:201], v[30:33]
	v_mfma_f32_16x16x32_bf16 v[22:25], v[174:177], v[198:201], v[22:25]
	v_mfma_f32_16x16x32_bf16 v[14:17], v[166:169], v[206:209], v[14:17]
	v_mfma_f32_16x16x32_bf16 v[6:9], v[174:177], v[206:209], v[6:9]
	v_mfma_f32_16x16x32_bf16 v[78:81], v[170:173], v[186:189], v[78:81]
	v_mfma_f32_16x16x32_bf16 v[70:73], v[178:181], v[186:189], v[70:73]
	v_mfma_f32_16x16x32_bf16 v[46:49], v[170:173], v[194:197], v[46:49]
	v_mfma_f32_16x16x32_bf16 v[38:41], v[178:181], v[194:197], v[38:41]
	v_mfma_f32_16x16x32_bf16 v[30:33], v[170:173], v[202:205], v[30:33]
	v_mfma_f32_16x16x32_bf16 v[22:25], v[178:181], v[202:205], v[22:25]
	v_mfma_f32_16x16x32_bf16 v[14:17], v[170:173], v[210:213], v[14:17]
	v_mfma_f32_16x16x32_bf16 v[6:9], v[178:181], v[210:213], v[6:9]
	s_barrier
	s_setprio 0
	ds_read_b128 v[146:149], v152
	ds_read_b128 v[154:157], v152 offset:1024
	ds_read_b128 v[158:161], v152 offset:2048
	ds_read_b128 v[162:165], v152 offset:3072
	ds_read_b128 v[166:169], v153
	ds_read_b128 v[170:173], v153 offset:1024
	ds_read_b128 v[174:177], v153 offset:2048
	ds_read_b128 v[178:181], v153 offset:3072
	s_add_u32 s46, s64, 0x40000
	s_addc_u32 s47, s65, 0
	s_mov_b32 m0, s33
	s_nop 0
	global_load_lds_dwordx4 v136, s[100:101]
	s_mov_b32 m0, s41
	s_nop 0
	global_load_lds_dwordx4 v132, s[100:101]
	s_mov_b32 m0, s58
	ds_read_b128 v[182:185], v151 offset:32768
	ds_read_b128 v[186:189], v151 offset:33792
	ds_read_b128 v[190:193], v151 offset:34816
	ds_read_b128 v[194:197], v151 offset:35840
	ds_read_b128 v[198:201], v151 offset:36864
	ds_read_b128 v[202:205], v151 offset:37888
	ds_read_b128 v[206:209], v151 offset:38912
	ds_read_b128 v[210:213], v151 offset:39936
	global_load_lds_dwordx4 v136, s[46:47]
	s_mov_b32 m0, s59
	s_nop 0
	global_load_lds_dwordx4 v132, s[46:47]
	s_waitcnt vmcnt(8)
	s_waitcnt lgkmcnt(0)
	s_setprio 1
	s_barrier
	v_mfma_f32_16x16x32_bf16 v[122:125], v[146:149], v[182:185], v[122:125]
	v_mfma_f32_16x16x32_bf16 v[114:117], v[158:161], v[182:185], v[114:117]
	v_mfma_f32_16x16x32_bf16 v[106:109], v[146:149], v[190:193], v[106:109]
	v_mfma_f32_16x16x32_bf16 v[98:101], v[158:161], v[190:193], v[98:101]
	v_mfma_f32_16x16x32_bf16 v[90:93], v[146:149], v[198:201], v[90:93]
	v_mfma_f32_16x16x32_bf16 v[82:85], v[158:161], v[198:201], v[82:85]
	v_mfma_f32_16x16x32_bf16 v[58:61], v[146:149], v[206:209], v[58:61]
	v_mfma_f32_16x16x32_bf16 v[50:53], v[158:161], v[206:209], v[50:53]
	v_mfma_f32_16x16x32_bf16 v[122:125], v[154:157], v[186:189], v[122:125]
	v_mfma_f32_16x16x32_bf16 v[114:117], v[162:165], v[186:189], v[114:117]
	v_mfma_f32_16x16x32_bf16 v[106:109], v[154:157], v[194:197], v[106:109]
	v_mfma_f32_16x16x32_bf16 v[98:101], v[162:165], v[194:197], v[98:101]
	v_mfma_f32_16x16x32_bf16 v[90:93], v[154:157], v[202:205], v[90:93]
	v_mfma_f32_16x16x32_bf16 v[82:85], v[162:165], v[202:205], v[82:85]
	v_mfma_f32_16x16x32_bf16 v[58:61], v[154:157], v[210:213], v[58:61]
	v_mfma_f32_16x16x32_bf16 v[50:53], v[162:165], v[210:213], v[50:53]
	s_setprio 0
	s_setprio 1
	v_mfma_f32_16x16x32_bf16 v[126:129], v[166:169], v[182:185], v[126:129]
	v_mfma_f32_16x16x32_bf16 v[118:121], v[174:177], v[182:185], v[118:121]
	v_mfma_f32_16x16x32_bf16 v[110:113], v[166:169], v[190:193], v[110:113]
	v_mfma_f32_16x16x32_bf16 v[102:105], v[174:177], v[190:193], v[102:105]
	v_mfma_f32_16x16x32_bf16 v[94:97], v[166:169], v[198:201], v[94:97]
	v_mfma_f32_16x16x32_bf16 v[86:89], v[174:177], v[198:201], v[86:89]
	v_mfma_f32_16x16x32_bf16 v[62:65], v[166:169], v[206:209], v[62:65]
	v_mfma_f32_16x16x32_bf16 v[54:57], v[174:177], v[206:209], v[54:57]
	v_mfma_f32_16x16x32_bf16 v[126:129], v[170:173], v[186:189], v[126:129]
	v_mfma_f32_16x16x32_bf16 v[118:121], v[178:181], v[186:189], v[118:121]
	v_mfma_f32_16x16x32_bf16 v[110:113], v[170:173], v[194:197], v[110:113]
	v_mfma_f32_16x16x32_bf16 v[102:105], v[178:181], v[194:197], v[102:105]
	v_mfma_f32_16x16x32_bf16 v[94:97], v[170:173], v[202:205], v[94:97]
	v_mfma_f32_16x16x32_bf16 v[86:89], v[178:181], v[202:205], v[86:89]
	v_mfma_f32_16x16x32_bf16 v[62:65], v[170:173], v[210:213], v[62:65]
	v_mfma_f32_16x16x32_bf16 v[54:57], v[178:181], v[210:213], v[54:57]
	s_barrier
	s_setprio 0
	s_mov_b32 m0, s76
	s_add_u32 s98, s98, 0x80
	s_addc_u32 s99, s99, 0
	s_add_u32 s100, s100, 0x80
	s_addc_u32 s101, s101, 0
	s_add_u32 s46, s54, 0x40080
	ds_read_b128 v[182:185], v151 offset:49152
	ds_read_b128 v[186:189], v151 offset:50176
	ds_read_b128 v[190:193], v151 offset:51200
	ds_read_b128 v[194:197], v151 offset:52224
	ds_read_b128 v[198:201], v151 offset:53248
	ds_read_b128 v[202:205], v151 offset:54272
	ds_read_b128 v[206:209], v151 offset:55296
	ds_read_b128 v[210:213], v151 offset:56320
	global_load_lds_dwordx4 v134, s[98:99]
	s_mov_b32 m0, s77
	s_addc_u32 s47, s55, 0
	global_load_lds_dwordx4 v130, s[98:99]
	s_mov_b32 m0, s78
	s_nop 0
	global_load_lds_dwordx4 v134, s[46:47]
	s_mov_b32 m0, s79
	s_nop 0
	global_load_lds_dwordx4 v130, s[46:47]
	s_mov_b32 m0, s66
	s_nop 0
	global_load_lds_dwordx4 v136, s[100:101]
	s_mov_b32 m0, s67
	s_nop 0
	global_load_lds_dwordx4 v132, s[100:101]
	s_waitcnt vmcnt(8)
	s_waitcnt lgkmcnt(0)
	s_setprio 1
	s_barrier
	v_mfma_f32_16x16x32_bf16 v[74:77], v[146:149], v[182:185], v[74:77]
	v_mfma_f32_16x16x32_bf16 v[66:69], v[158:161], v[182:185], v[66:69]
	v_mfma_f32_16x16x32_bf16 v[42:45], v[146:149], v[190:193], v[42:45]
	v_mfma_f32_16x16x32_bf16 v[34:37], v[158:161], v[190:193], v[34:37]
	v_mfma_f32_16x16x32_bf16 v[26:29], v[146:149], v[198:201], v[26:29]
	v_mfma_f32_16x16x32_bf16 v[18:21], v[158:161], v[198:201], v[18:21]
	v_mfma_f32_16x16x32_bf16 v[10:13], v[146:149], v[206:209], v[10:13]
	v_mfma_f32_16x16x32_bf16 v[2:5], v[158:161], v[206:209], v[2:5]
	v_mfma_f32_16x16x32_bf16 v[74:77], v[154:157], v[186:189], v[74:77]
	v_mfma_f32_16x16x32_bf16 v[66:69], v[162:165], v[186:189], v[66:69]
	v_mfma_f32_16x16x32_bf16 v[42:45], v[154:157], v[194:197], v[42:45]
	v_mfma_f32_16x16x32_bf16 v[34:37], v[162:165], v[194:197], v[34:37]
	v_mfma_f32_16x16x32_bf16 v[26:29], v[154:157], v[202:205], v[26:29]
	v_mfma_f32_16x16x32_bf16 v[18:21], v[162:165], v[202:205], v[18:21]
	v_mfma_f32_16x16x32_bf16 v[10:13], v[154:157], v[210:213], v[10:13]
	v_mfma_f32_16x16x32_bf16 v[2:5], v[162:165], v[210:213], v[2:5]
	s_setprio 0
	s_setprio 1
	v_mfma_f32_16x16x32_bf16 v[78:81], v[166:169], v[182:185], v[78:81]
	v_mfma_f32_16x16x32_bf16 v[70:73], v[174:177], v[182:185], v[70:73]
	v_mfma_f32_16x16x32_bf16 v[46:49], v[166:169], v[190:193], v[46:49]
	v_mfma_f32_16x16x32_bf16 v[38:41], v[174:177], v[190:193], v[38:41]
	v_mfma_f32_16x16x32_bf16 v[30:33], v[166:169], v[198:201], v[30:33]
	v_mfma_f32_16x16x32_bf16 v[22:25], v[174:177], v[198:201], v[22:25]
	v_mfma_f32_16x16x32_bf16 v[14:17], v[166:169], v[206:209], v[14:17]
	v_mfma_f32_16x16x32_bf16 v[6:9], v[174:177], v[206:209], v[6:9]
	v_mfma_f32_16x16x32_bf16 v[78:81], v[170:173], v[186:189], v[78:81]
	v_mfma_f32_16x16x32_bf16 v[70:73], v[178:181], v[186:189], v[70:73]
	v_mfma_f32_16x16x32_bf16 v[46:49], v[170:173], v[194:197], v[46:49]
	v_mfma_f32_16x16x32_bf16 v[38:41], v[178:181], v[194:197], v[38:41]
	v_mfma_f32_16x16x32_bf16 v[30:33], v[170:173], v[202:205], v[30:33]
	v_mfma_f32_16x16x32_bf16 v[22:25], v[178:181], v[202:205], v[22:25]
	v_mfma_f32_16x16x32_bf16 v[14:17], v[170:173], v[210:213], v[14:17]
	v_mfma_f32_16x16x32_bf16 v[6:9], v[178:181], v[210:213], v[6:9]
	s_barrier
	s_setprio 0
	s_add_i32 s26, s26, 2
	s_add_u32 s62, s62, 0x100
	s_addc_u32 s63, s63, 0
	s_add_u32 s14, s14, 0x100
	s_addc_u32 s15, s15, 0
	s_cmp_gt_u32 s26, 13
	s_cbranch_scc0 .LBB0_644
	s_and_b64 vcc, exec, s[16:17]
	s_cbranch_vccz .LBB0_647
	s_barrier

.LBB0_670:
	ds_read_b128 v[132:135], v158
	ds_read_b128 v[154:157], v158 offset:1024
	ds_read_b128 v[162:165], v158 offset:2048
	ds_read_b128 v[166:169], v158 offset:3072
	ds_read_b128 v[170:173], v159
	ds_read_b128 v[174:177], v159 offset:1024
	ds_read_b128 v[178:181], v159 offset:2048
	ds_read_b128 v[182:185], v159 offset:3072
	s_add_u32 s6, s64, 0xfffe0080
	s_addc_u32 s7, s65, -1
	s_cmp_eq_u32 s26, 4
	s_cselect_b32 s67, s29, s7
	s_cselect_b32 s66, s79, s6
	s_cselect_b32 s7, s0, s15
	s_cselect_b32 s6, s80, s14
	s_mov_b32 m0, s81
	ds_read_b128 v[186:189], v160
	ds_read_b128 v[190:193], v160 offset:1024
	ds_read_b128 v[194:197], v160 offset:2048
	ds_read_b128 v[198:201], v160 offset:3072
	ds_read_b128 v[202:205], v160 offset:4096
	ds_read_b128 v[206:209], v160 offset:5120
	ds_read_b128 v[210:213], v160 offset:6144
	ds_read_b128 v[214:217], v160 offset:7168
	global_load_lds_dwordx4 v146, s[64:65]
	s_mov_b32 m0, s82
	s_nop 0
	global_load_lds_dwordx4 v148, s[64:65]
	s_waitcnt vmcnt(8)
	s_waitcnt lgkmcnt(0)
	s_setprio 1
	s_barrier
	v_mfma_f32_16x16x32_bf16 v[118:121], v[132:135], v[186:189], v[118:121]
	v_mfma_f32_16x16x32_bf16 v[114:117], v[162:165], v[186:189], v[114:117]
	v_mfma_f32_16x16x32_bf16 v[110:113], v[132:135], v[194:197], v[110:113]
	v_mfma_f32_16x16x32_bf16 v[98:101], v[162:165], v[194:197], v[98:101]
	v_mfma_f32_16x16x32_bf16 v[94:97], v[132:135], v[202:205], v[94:97]
	v_mfma_f32_16x16x32_bf16 v[90:93], v[162:165], v[202:205], v[90:93]
	v_mfma_f32_16x16x32_bf16 v[78:81], v[132:135], v[210:213], v[78:81]
	v_mfma_f32_16x16x32_bf16 v[70:73], v[162:165], v[210:213], v[70:73]
	v_mfma_f32_16x16x32_bf16 v[118:121], v[154:157], v[190:193], v[118:121]
	v_mfma_f32_16x16x32_bf16 v[114:117], v[166:169], v[190:193], v[114:117]
	v_mfma_f32_16x16x32_bf16 v[110:113], v[154:157], v[198:201], v[110:113]
	v_mfma_f32_16x16x32_bf16 v[98:101], v[166:169], v[198:201], v[98:101]
	v_mfma_f32_16x16x32_bf16 v[94:97], v[154:157], v[206:209], v[94:97]
	v_mfma_f32_16x16x32_bf16 v[90:93], v[166:169], v[206:209], v[90:93]
	v_mfma_f32_16x16x32_bf16 v[78:81], v[154:157], v[214:217], v[78:81]
	v_mfma_f32_16x16x32_bf16 v[70:73], v[166:169], v[214:217], v[70:73]
	s_setprio 0
	s_setprio 1
	v_mfma_f32_16x16x32_bf16 v[126:129], v[170:173], v[186:189], v[126:129]
	v_mfma_f32_16x16x32_bf16 v[122:125], v[178:181], v[186:189], v[122:125]
	v_mfma_f32_16x16x32_bf16 v[106:109], v[170:173], v[194:197], v[106:109]
	v_mfma_f32_16x16x32_bf16 v[102:105], v[178:181], v[194:197], v[102:105]
	v_mfma_f32_16x16x32_bf16 v[86:89], v[170:173], v[202:205], v[86:89]
	v_mfma_f32_16x16x32_bf16 v[82:85], v[178:181], v[202:205], v[82:85]
	v_mfma_f32_16x16x32_bf16 v[62:65], v[170:173], v[210:213], v[62:65]
	v_mfma_f32_16x16x32_bf16 v[58:61], v[178:181], v[210:213], v[58:61]
	v_mfma_f32_16x16x32_bf16 v[126:129], v[174:177], v[190:193], v[126:129]
	v_mfma_f32_16x16x32_bf16 v[122:125], v[182:185], v[190:193], v[122:125]
	v_mfma_f32_16x16x32_bf16 v[106:109], v[174:177], v[198:201], v[106:109]
	v_mfma_f32_16x16x32_bf16 v[102:105], v[182:185], v[198:201], v[102:105]
	v_mfma_f32_16x16x32_bf16 v[86:89], v[174:177], v[206:209], v[86:89]
	v_mfma_f32_16x16x32_bf16 v[82:85], v[182:185], v[206:209], v[82:85]
	v_mfma_f32_16x16x32_bf16 v[62:65], v[174:177], v[214:217], v[62:65]
	v_mfma_f32_16x16x32_bf16 v[58:61], v[182:185], v[214:217], v[58:61]
	s_barrier
	s_setprio 0
	s_mov_b32 m0, s83
	s_mov_b64 s[98:99], s[6:7]
	s_add_u32 s88, s6, 0x20000
	ds_read_b128 v[186:189], v160 offset:16384
	ds_read_b128 v[190:193], v160 offset:17408
	ds_read_b128 v[194:197], v160 offset:18432
	ds_read_b128 v[198:201], v160 offset:19456
	ds_read_b128 v[202:205], v160 offset:20480
	ds_read_b128 v[206:209], v160 offset:21504
	ds_read_b128 v[210:213], v160 offset:22528
	ds_read_b128 v[214:217], v160 offset:23552
	global_load_lds_dwordx4 v140, s[6:7]
	s_mov_b32 m0, s84
	s_addc_u32 s89, s7, 0
	global_load_lds_dwordx4 v144, s[6:7]
	s_mov_b32 m0, s85
	s_mov_b64 s[100:101], s[66:67]
	global_load_lds_dwordx4 v140, s[88:89]
	s_mov_b32 m0, s46
	s_nop 0
	global_load_lds_dwordx4 v144, s[88:89]
	s_waitcnt vmcnt(6)
	s_waitcnt lgkmcnt(0)
	s_setprio 1
	s_barrier
	v_mfma_f32_16x16x32_bf16 v[74:77], v[132:135], v[186:189], v[74:77]
	v_mfma_f32_16x16x32_bf16 v[66:69], v[162:165], v[186:189], v[66:69]
	v_mfma_f32_16x16x32_bf16 v[46:49], v[132:135], v[194:197], v[46:49]
	v_mfma_f32_16x16x32_bf16 v[42:45], v[162:165], v[194:197], v[42:45]
	v_mfma_f32_16x16x32_bf16 v[30:33], v[132:135], v[202:205], v[30:33]
	v_mfma_f32_16x16x32_bf16 v[26:29], v[162:165], v[202:205], v[26:29]
	v_mfma_f32_16x16x32_bf16 v[14:17], v[132:135], v[210:213], v[14:17]
	v_mfma_f32_16x16x32_bf16 v[10:13], v[162:165], v[210:213], v[10:13]
	v_mfma_f32_16x16x32_bf16 v[74:77], v[154:157], v[190:193], v[74:77]
	v_mfma_f32_16x16x32_bf16 v[66:69], v[166:169], v[190:193], v[66:69]
	v_mfma_f32_16x16x32_bf16 v[46:49], v[154:157], v[198:201], v[46:49]
	v_mfma_f32_16x16x32_bf16 v[42:45], v[166:169], v[198:201], v[42:45]
	v_mfma_f32_16x16x32_bf16 v[30:33], v[154:157], v[206:209], v[30:33]
	v_mfma_f32_16x16x32_bf16 v[26:29], v[166:169], v[206:209], v[26:29]
	v_mfma_f32_16x16x32_bf16 v[14:17], v[154:157], v[214:217], v[14:17]
	v_mfma_f32_16x16x32_bf16 v[10:13], v[166:169], v[214:217], v[10:13]
	s_setprio 0
	s_setprio 1
	v_mfma_f32_16x16x32_bf16 v[54:57], v[170:173], v[186:189], v[54:57]
	v_mfma_f32_16x16x32_bf16 v[50:53], v[178:181], v[186:189], v[50:53]
	v_mfma_f32_16x16x32_bf16 v[38:41], v[170:173], v[194:197], v[38:41]
	v_mfma_f32_16x16x32_bf16 v[34:37], v[178:181], v[194:197], v[34:37]
	v_mfma_f32_16x16x32_bf16 v[22:25], v[170:173], v[202:205], v[22:25]
	v_mfma_f32_16x16x32_bf16 v[18:21], v[178:181], v[202:205], v[18:21]
	v_mfma_f32_16x16x32_bf16 v[6:9], v[170:173], v[210:213], v[6:9]
	v_mfma_f32_16x16x32_bf16 v[2:5], v[178:181], v[210:213], v[2:5]
	v_mfma_f32_16x16x32_bf16 v[54:57], v[174:177], v[190:193], v[54:57]
	v_mfma_f32_16x16x32_bf16 v[50:53], v[182:185], v[190:193], v[50:53]
	v_mfma_f32_16x16x32_bf16 v[38:41], v[174:177], v[198:201], v[38:41]
	v_mfma_f32_16x16x32_bf16 v[34:37], v[182:185], v[198:201], v[34:37]
	v_mfma_f32_16x16x32_bf16 v[22:25], v[174:177], v[206:209], v[22:25]
	v_mfma_f32_16x16x32_bf16 v[18:21], v[182:185], v[206:209], v[18:21]
	v_mfma_f32_16x16x32_bf16 v[6:9], v[174:177], v[214:217], v[6:9]
	v_mfma_f32_16x16x32_bf16 v[2:5], v[182:185], v[214:217], v[2:5]
	s_barrier
	s_setprio 0
	ds_read_b128 v[132:135], v130
	ds_read_b128 v[154:157], v130 offset:1024
	ds_read_b128 v[162:165], v130 offset:2048
	ds_read_b128 v[166:169], v130 offset:3072
	ds_read_b128 v[170:173], v131
	ds_read_b128 v[174:177], v131 offset:1024
	ds_read_b128 v[178:181], v131 offset:2048
	ds_read_b128 v[182:185], v131 offset:3072
	s_add_u32 s66, s66, 0x20000
	s_addc_u32 s67, s67, 0
	s_mov_b32 m0, s58
	s_nop 0
	global_load_lds_dwordx4 v138, s[100:101]
	s_mov_b32 m0, s59
	s_nop 0
	global_load_lds_dwordx4 v142, s[100:101]
	s_mov_b32 m0, s63
	ds_read_b128 v[186:189], v160 offset:32768
	ds_read_b128 v[190:193], v160 offset:33792
	ds_read_b128 v[194:197], v160 offset:34816
	ds_read_b128 v[198:201], v160 offset:35840
	ds_read_b128 v[202:205], v160 offset:36864
	ds_read_b128 v[206:209], v160 offset:37888
	ds_read_b128 v[210:213], v160 offset:38912
	ds_read_b128 v[214:217], v160 offset:39936
	global_load_lds_dwordx4 v138, s[66:67]
	s_mov_b32 m0, s68
	s_nop 0
	global_load_lds_dwordx4 v142, s[66:67]
	s_waitcnt vmcnt(8)
	s_waitcnt lgkmcnt(0)
	s_setprio 1
	s_barrier
	v_mfma_f32_16x16x32_bf16 v[118:121], v[132:135], v[186:189], v[118:121]
	v_mfma_f32_16x16x32_bf16 v[114:117], v[162:165], v[186:189], v[114:117]
	v_mfma_f32_16x16x32_bf16 v[110:113], v[132:135], v[194:197], v[110:113]
	v_mfma_f32_16x16x32_bf16 v[98:101], v[162:165], v[194:197], v[98:101]
	v_mfma_f32_16x16x32_bf16 v[94:97], v[132:135], v[202:205], v[94:97]
	v_mfma_f32_16x16x32_bf16 v[90:93], v[162:165], v[202:205], v[90:93]
	v_mfma_f32_16x16x32_bf16 v[78:81], v[132:135], v[210:213], v[78:81]
	v_mfma_f32_16x16x32_bf16 v[70:73], v[162:165], v[210:213], v[70:73]
	v_mfma_f32_16x16x32_bf16 v[118:121], v[154:157], v[190:193], v[118:121]
	v_mfma_f32_16x16x32_bf16 v[114:117], v[166:169], v[190:193], v[114:117]
	v_mfma_f32_16x16x32_bf16 v[110:113], v[154:157], v[198:201], v[110:113]
	v_mfma_f32_16x16x32_bf16 v[98:101], v[166:169], v[198:201], v[98:101]
	v_mfma_f32_16x16x32_bf16 v[94:97], v[154:157], v[206:209], v[94:97]
	v_mfma_f32_16x16x32_bf16 v[90:93], v[166:169], v[206:209], v[90:93]
	v_mfma_f32_16x16x32_bf16 v[78:81], v[154:157], v[214:217], v[78:81]
	v_mfma_f32_16x16x32_bf16 v[70:73], v[166:169], v[214:217], v[70:73]
	s_setprio 0
	s_setprio 1
	v_mfma_f32_16x16x32_bf16 v[126:129], v[170:173], v[186:189], v[126:129]
	v_mfma_f32_16x16x32_bf16 v[122:125], v[178:181], v[186:189], v[122:125]
	v_mfma_f32_16x16x32_bf16 v[106:109], v[170:173], v[194:197], v[106:109]
	v_mfma_f32_16x16x32_bf16 v[102:105], v[178:181], v[194:197], v[102:105]
	v_mfma_f32_16x16x32_bf16 v[86:89], v[170:173], v[202:205], v[86:89]
	v_mfma_f32_16x16x32_bf16 v[82:85], v[178:181], v[202:205], v[82:85]
	v_mfma_f32_16x16x32_bf16 v[62:65], v[170:173], v[210:213], v[62:65]
	v_mfma_f32_16x16x32_bf16 v[58:61], v[178:181], v[210:213], v[58:61]
	v_mfma_f32_16x16x32_bf16 v[126:129], v[174:177], v[190:193], v[126:129]
	v_mfma_f32_16x16x32_bf16 v[122:125], v[182:185], v[190:193], v[122:125]
	v_mfma_f32_16x16x32_bf16 v[106:109], v[174:177], v[198:201], v[106:109]
	v_mfma_f32_16x16x32_bf16 v[102:105], v[182:185], v[198:201], v[102:105]
	v_mfma_f32_16x16x32_bf16 v[86:89], v[174:177], v[206:209], v[86:89]
	v_mfma_f32_16x16x32_bf16 v[82:85], v[182:185], v[206:209], v[82:85]
	v_mfma_f32_16x16x32_bf16 v[62:65], v[174:177], v[214:217], v[62:65]
	v_mfma_f32_16x16x32_bf16 v[58:61], v[182:185], v[214:217], v[58:61]
	s_barrier
	s_setprio 0
	s_mov_b32 m0, s47
	s_add_u32 s98, s98, 0x80
	s_addc_u32 s99, s99, 0
	s_add_u32 s100, s100, 0x80
	s_addc_u32 s101, s101, 0
	s_add_u32 s6, s6, 0x20080
	ds_read_b128 v[186:189], v160 offset:49152
	ds_read_b128 v[190:193], v160 offset:50176
	ds_read_b128 v[194:197], v160 offset:51200
	ds_read_b128 v[198:201], v160 offset:52224
	ds_read_b128 v[202:205], v160 offset:53248
	ds_read_b128 v[206:209], v160 offset:54272
	ds_read_b128 v[210:213], v160 offset:55296
	ds_read_b128 v[214:217], v160 offset:56320
	global_load_lds_dwordx4 v140, s[98:99]
	s_mov_b32 m0, s86
	s_addc_u32 s7, s7, 0
	global_load_lds_dwordx4 v144, s[98:99]
	s_mov_b32 m0, s56
	s_nop 0
	global_load_lds_dwordx4 v140, s[6:7]
	s_mov_b32 m0, s57
	s_nop 0
	global_load_lds_dwordx4 v144, s[6:7]
	s_mov_b32 m0, s69
	s_nop 0
	global_load_lds_dwordx4 v138, s[100:101]
	s_mov_b32 m0, s70
	s_nop 0
	global_load_lds_dwordx4 v142, s[100:101]
	s_waitcnt vmcnt(8)
	s_waitcnt lgkmcnt(0)
	s_setprio 1
	s_barrier
	v_mfma_f32_16x16x32_bf16 v[74:77], v[132:135], v[186:189], v[74:77]
	v_mfma_f32_16x16x32_bf16 v[66:69], v[162:165], v[186:189], v[66:69]
	v_mfma_f32_16x16x32_bf16 v[46:49], v[132:135], v[194:197], v[46:49]
	v_mfma_f32_16x16x32_bf16 v[42:45], v[162:165], v[194:197], v[42:45]
	v_mfma_f32_16x16x32_bf16 v[30:33], v[132:135], v[202:205], v[30:33]
	v_mfma_f32_16x16x32_bf16 v[26:29], v[162:165], v[202:205], v[26:29]
	v_mfma_f32_16x16x32_bf16 v[14:17], v[132:135], v[210:213], v[14:17]
	v_mfma_f32_16x16x32_bf16 v[10:13], v[162:165], v[210:213], v[10:13]
	v_mfma_f32_16x16x32_bf16 v[74:77], v[154:157], v[190:193], v[74:77]
	v_mfma_f32_16x16x32_bf16 v[66:69], v[166:169], v[190:193], v[66:69]
	v_mfma_f32_16x16x32_bf16 v[46:49], v[154:157], v[198:201], v[46:49]
	v_mfma_f32_16x16x32_bf16 v[42:45], v[166:169], v[198:201], v[42:45]
	v_mfma_f32_16x16x32_bf16 v[30:33], v[154:157], v[206:209], v[30:33]
	v_mfma_f32_16x16x32_bf16 v[26:29], v[166:169], v[206:209], v[26:29]
	v_mfma_f32_16x16x32_bf16 v[14:17], v[154:157], v[214:217], v[14:17]
	v_mfma_f32_16x16x32_bf16 v[10:13], v[166:169], v[214:217], v[10:13]
	s_setprio 0
	s_setprio 1
	v_mfma_f32_16x16x32_bf16 v[54:57], v[170:173], v[186:189], v[54:57]
	v_mfma_f32_16x16x32_bf16 v[50:53], v[178:181], v[186:189], v[50:53]
	v_mfma_f32_16x16x32_bf16 v[38:41], v[170:173], v[194:197], v[38:41]
	v_mfma_f32_16x16x32_bf16 v[34:37], v[178:181], v[194:197], v[34:37]
	v_mfma_f32_16x16x32_bf16 v[22:25], v[170:173], v[202:205], v[22:25]
	v_mfma_f32_16x16x32_bf16 v[18:21], v[178:181], v[202:205], v[18:21]
	v_mfma_f32_16x16x32_bf16 v[6:9], v[170:173], v[210:213], v[6:9]
	v_mfma_f32_16x16x32_bf16 v[2:5], v[178:181], v[210:213], v[2:5]
	v_mfma_f32_16x16x32_bf16 v[54:57], v[174:177], v[190:193], v[54:57]
	v_mfma_f32_16x16x32_bf16 v[50:53], v[182:185], v[190:193], v[50:53]
	v_mfma_f32_16x16x32_bf16 v[38:41], v[174:177], v[198:201], v[38:41]
	v_mfma_f32_16x16x32_bf16 v[34:37], v[182:185], v[198:201], v[34:37]
	v_mfma_f32_16x16x32_bf16 v[22:25], v[174:177], v[206:209], v[22:25]
	v_mfma_f32_16x16x32_bf16 v[18:21], v[182:185], v[206:209], v[18:21]
	v_mfma_f32_16x16x32_bf16 v[6:9], v[174:177], v[214:217], v[6:9]
	v_mfma_f32_16x16x32_bf16 v[2:5], v[182:185], v[214:217], v[2:5]
	s_barrier
	s_setprio 0
	s_add_i32 s26, s26, 2
	s_add_u32 s64, s64, 0x100
	s_addc_u32 s65, s65, 0
	s_add_u32 s14, s14, 0x100
	s_addc_u32 s15, s15, 0
	s_cmp_gt_u32 s26, 5
	s_cbranch_scc0 .LBB0_670
	s_and_b64 vcc, exec, s[18:19]
	s_cbranch_vccz .LBB0_673
	s_barrier

.LBB0_716:
	ds_read_b128 v[132:135], v164
	ds_read_b128 v[136:139], v164 offset:1024
	ds_read_b128 v[140:143], v164 offset:2048
	ds_read_b128 v[168:171], v164 offset:3072
	ds_read_b128 v[172:175], v165
	ds_read_b128 v[176:179], v165 offset:1024
	ds_read_b128 v[180:183], v165 offset:2048
	ds_read_b128 v[184:187], v165 offset:3072
	s_add_u32 s27, s62, 0xfff80080
	s_addc_u32 s50, s63, -1
	s_cmp_eq_u32 s26, 4
	s_cselect_b32 s65, s1, s50
	s_cselect_b32 s64, s0, s27
	s_cselect_b32 s51, s29, s15
	s_cselect_b32 s50, s28, s14
	s_mov_b32 m0, s23
	ds_read_b128 v[188:191], v166
	ds_read_b128 v[192:195], v166 offset:1024
	ds_read_b128 v[196:199], v166 offset:2048
	ds_read_b128 v[200:203], v166 offset:3072
	ds_read_b128 v[204:207], v166 offset:4096
	ds_read_b128 v[208:211], v166 offset:5120
	ds_read_b128 v[212:215], v166 offset:6144
	ds_read_b128 v[216:219], v166 offset:7168
	global_load_lds_dwordx4 v154, s[62:63]
	s_mov_b32 m0, s77
	s_nop 0
	global_load_lds_dwordx4 v156, s[62:63]
	s_waitcnt vmcnt(8)
	s_waitcnt lgkmcnt(0)
	s_setprio 1
	s_barrier
	v_mfma_f32_16x16x32_bf16 v[102:105], v[132:135], v[188:191], v[102:105]
	v_mfma_f32_16x16x32_bf16 v[98:101], v[140:143], v[188:191], v[98:101]
	v_mfma_f32_16x16x32_bf16 v[94:97], v[132:135], v[196:199], v[94:97]
	v_mfma_f32_16x16x32_bf16 v[90:93], v[140:143], v[196:199], v[90:93]
	v_mfma_f32_16x16x32_bf16 v[86:89], v[132:135], v[204:207], v[86:89]
	v_mfma_f32_16x16x32_bf16 v[82:85], v[140:143], v[204:207], v[82:85]
	v_mfma_f32_16x16x32_bf16 v[78:81], v[132:135], v[212:215], v[78:81]
	v_mfma_f32_16x16x32_bf16 v[62:65], v[140:143], v[212:215], v[62:65]
	v_mfma_f32_16x16x32_bf16 v[102:105], v[136:139], v[192:195], v[102:105]
	v_mfma_f32_16x16x32_bf16 v[98:101], v[168:171], v[192:195], v[98:101]
	v_mfma_f32_16x16x32_bf16 v[94:97], v[136:139], v[200:203], v[94:97]
	v_mfma_f32_16x16x32_bf16 v[90:93], v[168:171], v[200:203], v[90:93]
	v_mfma_f32_16x16x32_bf16 v[86:89], v[136:139], v[208:211], v[86:89]
	v_mfma_f32_16x16x32_bf16 v[82:85], v[168:171], v[208:211], v[82:85]
	v_mfma_f32_16x16x32_bf16 v[78:81], v[136:139], v[216:219], v[78:81]
	v_mfma_f32_16x16x32_bf16 v[62:65], v[168:171], v[216:219], v[62:65]
	s_setprio 0
	s_setprio 1
	v_mfma_f32_16x16x32_bf16 v[126:129], v[172:175], v[188:191], v[126:129]
	v_mfma_f32_16x16x32_bf16 v[122:125], v[180:183], v[188:191], v[122:125]
	v_mfma_f32_16x16x32_bf16 v[118:121], v[172:175], v[196:199], v[118:121]
	v_mfma_f32_16x16x32_bf16 v[114:117], v[180:183], v[196:199], v[114:117]
	v_mfma_f32_16x16x32_bf16 v[110:113], v[172:175], v[204:207], v[110:113]
	v_mfma_f32_16x16x32_bf16 v[106:109], v[180:183], v[204:207], v[106:109]
	v_mfma_f32_16x16x32_bf16 v[54:57], v[172:175], v[212:215], v[54:57]
	v_mfma_f32_16x16x32_bf16 v[50:53], v[180:183], v[212:215], v[50:53]
	v_mfma_f32_16x16x32_bf16 v[126:129], v[176:179], v[192:195], v[126:129]
	v_mfma_f32_16x16x32_bf16 v[122:125], v[184:187], v[192:195], v[122:125]
	v_mfma_f32_16x16x32_bf16 v[118:121], v[176:179], v[200:203], v[118:121]
	v_mfma_f32_16x16x32_bf16 v[114:117], v[184:187], v[200:203], v[114:117]
	v_mfma_f32_16x16x32_bf16 v[110:113], v[176:179], v[208:211], v[110:113]
	v_mfma_f32_16x16x32_bf16 v[106:109], v[184:187], v[208:211], v[106:109]
	v_mfma_f32_16x16x32_bf16 v[54:57], v[176:179], v[216:219], v[54:57]
	v_mfma_f32_16x16x32_bf16 v[50:53], v[184:187], v[216:219], v[50:53]
	s_barrier
	s_setprio 0
	s_mov_b32 m0, s78
	s_mov_b64 s[98:99], s[50:51]
	s_add_u32 s82, s50, 0x80000
	ds_read_b128 v[188:191], v166 offset:16384
	ds_read_b128 v[192:195], v166 offset:17408
	ds_read_b128 v[196:199], v166 offset:18432
	ds_read_b128 v[200:203], v166 offset:19456
	ds_read_b128 v[204:207], v166 offset:20480
	ds_read_b128 v[208:211], v166 offset:21504
	ds_read_b128 v[212:215], v166 offset:22528
	ds_read_b128 v[216:219], v166 offset:23552
	global_load_lds_dwordx4 v148, s[50:51]
	s_mov_b32 m0, s79
	s_addc_u32 s83, s51, 0
	global_load_lds_dwordx4 v152, s[50:51]
	s_mov_b32 m0, s80
	s_mov_b64 s[100:101], s[64:65]
	global_load_lds_dwordx4 v148, s[82:83]
	s_mov_b32 m0, s46
	s_nop 0
	global_load_lds_dwordx4 v152, s[82:83]
	s_waitcnt vmcnt(6)
	s_waitcnt lgkmcnt(0)
	s_setprio 1
	s_barrier
	v_mfma_f32_16x16x32_bf16 v[74:77], v[132:135], v[188:191], v[74:77]
	v_mfma_f32_16x16x32_bf16 v[70:73], v[140:143], v[188:191], v[70:73]
	v_mfma_f32_16x16x32_bf16 v[46:49], v[132:135], v[196:199], v[46:49]
	v_mfma_f32_16x16x32_bf16 v[42:45], v[140:143], v[196:199], v[42:45]
	v_mfma_f32_16x16x32_bf16 v[30:33], v[132:135], v[204:207], v[30:33]
	v_mfma_f32_16x16x32_bf16 v[26:29], v[140:143], v[204:207], v[26:29]
	v_mfma_f32_16x16x32_bf16 v[14:17], v[132:135], v[212:215], v[14:17]
	v_mfma_f32_16x16x32_bf16 v[10:13], v[140:143], v[212:215], v[10:13]
	v_mfma_f32_16x16x32_bf16 v[74:77], v[136:139], v[192:195], v[74:77]
	v_mfma_f32_16x16x32_bf16 v[70:73], v[168:171], v[192:195], v[70:73]
	v_mfma_f32_16x16x32_bf16 v[46:49], v[136:139], v[200:203], v[46:49]
	v_mfma_f32_16x16x32_bf16 v[42:45], v[168:171], v[200:203], v[42:45]
	v_mfma_f32_16x16x32_bf16 v[30:33], v[136:139], v[208:211], v[30:33]
	v_mfma_f32_16x16x32_bf16 v[26:29], v[168:171], v[208:211], v[26:29]
	v_mfma_f32_16x16x32_bf16 v[14:17], v[136:139], v[216:219], v[14:17]
	v_mfma_f32_16x16x32_bf16 v[10:13], v[168:171], v[216:219], v[10:13]
	s_setprio 0
	s_setprio 1
	v_mfma_f32_16x16x32_bf16 v[66:69], v[172:175], v[188:191], v[66:69]
	v_mfma_f32_16x16x32_bf16 v[58:61], v[180:183], v[188:191], v[58:61]
	v_mfma_f32_16x16x32_bf16 v[38:41], v[172:175], v[196:199], v[38:41]
	v_mfma_f32_16x16x32_bf16 v[34:37], v[180:183], v[196:199], v[34:37]
	v_mfma_f32_16x16x32_bf16 v[22:25], v[172:175], v[204:207], v[22:25]
	v_mfma_f32_16x16x32_bf16 v[18:21], v[180:183], v[204:207], v[18:21]
	v_mfma_f32_16x16x32_bf16 v[6:9], v[172:175], v[212:215], v[6:9]
	v_mfma_f32_16x16x32_bf16 v[2:5], v[180:183], v[212:215], v[2:5]
	v_mfma_f32_16x16x32_bf16 v[66:69], v[176:179], v[192:195], v[66:69]
	v_mfma_f32_16x16x32_bf16 v[58:61], v[184:187], v[192:195], v[58:61]
	v_mfma_f32_16x16x32_bf16 v[38:41], v[176:179], v[200:203], v[38:41]
	v_mfma_f32_16x16x32_bf16 v[34:37], v[184:187], v[200:203], v[34:37]
	v_mfma_f32_16x16x32_bf16 v[22:25], v[176:179], v[208:211], v[22:25]
	v_mfma_f32_16x16x32_bf16 v[18:21], v[184:187], v[208:211], v[18:21]
	v_mfma_f32_16x16x32_bf16 v[6:9], v[176:179], v[216:219], v[6:9]
	v_mfma_f32_16x16x32_bf16 v[2:5], v[184:187], v[216:219], v[2:5]
	s_barrier
	s_setprio 0
	ds_read_b128 v[132:135], v130
	ds_read_b128 v[136:139], v130 offset:1024
	ds_read_b128 v[140:143], v130 offset:2048
	ds_read_b128 v[168:171], v130 offset:3072
	ds_read_b128 v[172:175], v131
	ds_read_b128 v[176:179], v131 offset:1024
	ds_read_b128 v[180:183], v131 offset:2048
	ds_read_b128 v[184:187], v131 offset:3072
	s_add_u32 s64, s64, 0x80000
	s_addc_u32 s65, s65, 0
	s_mov_b32 m0, s59
	s_nop 0
	global_load_lds_dwordx4 v146, s[100:101]
	s_mov_b32 m0, s31
	s_nop 0
	global_load_lds_dwordx4 v150, s[100:101]
	s_mov_b32 m0, s66
	ds_read_b128 v[188:191], v166 offset:32768
	ds_read_b128 v[192:195], v166 offset:33792
	ds_read_b128 v[196:199], v166 offset:34816
	ds_read_b128 v[200:203], v166 offset:35840
	ds_read_b128 v[204:207], v166 offset:36864
	ds_read_b128 v[208:211], v166 offset:37888
	ds_read_b128 v[212:215], v166 offset:38912
	ds_read_b128 v[216:219], v166 offset:39936
	global_load_lds_dwordx4 v146, s[64:65]
	s_mov_b32 m0, s67
	s_nop 0
	global_load_lds_dwordx4 v150, s[64:65]
	s_waitcnt vmcnt(8)
	s_waitcnt lgkmcnt(0)
	s_setprio 1
	s_barrier
	v_mfma_f32_16x16x32_bf16 v[102:105], v[132:135], v[188:191], v[102:105]
	v_mfma_f32_16x16x32_bf16 v[98:101], v[140:143], v[188:191], v[98:101]
	v_mfma_f32_16x16x32_bf16 v[94:97], v[132:135], v[196:199], v[94:97]
	v_mfma_f32_16x16x32_bf16 v[90:93], v[140:143], v[196:199], v[90:93]
	v_mfma_f32_16x16x32_bf16 v[86:89], v[132:135], v[204:207], v[86:89]
	v_mfma_f32_16x16x32_bf16 v[82:85], v[140:143], v[204:207], v[82:85]
	v_mfma_f32_16x16x32_bf16 v[78:81], v[132:135], v[212:215], v[78:81]
	v_mfma_f32_16x16x32_bf16 v[62:65], v[140:143], v[212:215], v[62:65]
	v_mfma_f32_16x16x32_bf16 v[102:105], v[136:139], v[192:195], v[102:105]
	v_mfma_f32_16x16x32_bf16 v[98:101], v[168:171], v[192:195], v[98:101]
	v_mfma_f32_16x16x32_bf16 v[94:97], v[136:139], v[200:203], v[94:97]
	v_mfma_f32_16x16x32_bf16 v[90:93], v[168:171], v[200:203], v[90:93]
	v_mfma_f32_16x16x32_bf16 v[86:89], v[136:139], v[208:211], v[86:89]
	v_mfma_f32_16x16x32_bf16 v[82:85], v[168:171], v[208:211], v[82:85]
	v_mfma_f32_16x16x32_bf16 v[78:81], v[136:139], v[216:219], v[78:81]
	v_mfma_f32_16x16x32_bf16 v[62:65], v[168:171], v[216:219], v[62:65]
	s_setprio 0
	s_setprio 1
	v_mfma_f32_16x16x32_bf16 v[126:129], v[172:175], v[188:191], v[126:129]
	v_mfma_f32_16x16x32_bf16 v[122:125], v[180:183], v[188:191], v[122:125]
	v_mfma_f32_16x16x32_bf16 v[118:121], v[172:175], v[196:199], v[118:121]
	v_mfma_f32_16x16x32_bf16 v[114:117], v[180:183], v[196:199], v[114:117]
	v_mfma_f32_16x16x32_bf16 v[110:113], v[172:175], v[204:207], v[110:113]
	v_mfma_f32_16x16x32_bf16 v[106:109], v[180:183], v[204:207], v[106:109]
	v_mfma_f32_16x16x32_bf16 v[54:57], v[172:175], v[212:215], v[54:57]
	v_mfma_f32_16x16x32_bf16 v[50:53], v[180:183], v[212:215], v[50:53]
	v_mfma_f32_16x16x32_bf16 v[126:129], v[176:179], v[192:195], v[126:129]
	v_mfma_f32_16x16x32_bf16 v[122:125], v[184:187], v[192:195], v[122:125]
	v_mfma_f32_16x16x32_bf16 v[118:121], v[176:179], v[200:203], v[118:121]
	v_mfma_f32_16x16x32_bf16 v[114:117], v[184:187], v[200:203], v[114:117]
	v_mfma_f32_16x16x32_bf16 v[110:113], v[176:179], v[208:211], v[110:113]
	v_mfma_f32_16x16x32_bf16 v[106:109], v[184:187], v[208:211], v[106:109]
	v_mfma_f32_16x16x32_bf16 v[54:57], v[176:179], v[216:219], v[54:57]
	v_mfma_f32_16x16x32_bf16 v[50:53], v[184:187], v[216:219], v[50:53]
	s_barrier
	s_setprio 0
	s_mov_b32 m0, s47
	s_add_u32 s98, s98, 0x80
	s_addc_u32 s99, s99, 0
	s_add_u32 s100, s100, 0x80
	s_addc_u32 s101, s101, 0
	s_add_u32 s50, s50, 0x80080
	ds_read_b128 v[188:191], v166 offset:49152
	ds_read_b128 v[192:195], v166 offset:50176
	ds_read_b128 v[196:199], v166 offset:51200
	ds_read_b128 v[200:203], v166 offset:52224
	ds_read_b128 v[204:207], v166 offset:53248
	ds_read_b128 v[208:211], v166 offset:54272
	ds_read_b128 v[212:215], v166 offset:55296
	ds_read_b128 v[216:219], v166 offset:56320
	global_load_lds_dwordx4 v148, s[98:99]
	s_mov_b32 m0, s81
	s_addc_u32 s51, s51, 0
	global_load_lds_dwordx4 v152, s[98:99]
	s_mov_b32 m0, s56
	s_nop 0
	global_load_lds_dwordx4 v148, s[50:51]
	s_mov_b32 m0, s57
	s_nop 0
	global_load_lds_dwordx4 v152, s[50:51]
	s_mov_b32 m0, s69
	s_nop 0
	global_load_lds_dwordx4 v146, s[100:101]
	s_mov_b32 m0, s70
	s_nop 0
	global_load_lds_dwordx4 v150, s[100:101]
	s_waitcnt vmcnt(8)
	s_waitcnt lgkmcnt(0)
	s_setprio 1
	s_barrier
	v_mfma_f32_16x16x32_bf16 v[74:77], v[132:135], v[188:191], v[74:77]
	v_mfma_f32_16x16x32_bf16 v[70:73], v[140:143], v[188:191], v[70:73]
	v_mfma_f32_16x16x32_bf16 v[46:49], v[132:135], v[196:199], v[46:49]
	v_mfma_f32_16x16x32_bf16 v[42:45], v[140:143], v[196:199], v[42:45]
	v_mfma_f32_16x16x32_bf16 v[30:33], v[132:135], v[204:207], v[30:33]
	v_mfma_f32_16x16x32_bf16 v[26:29], v[140:143], v[204:207], v[26:29]
	v_mfma_f32_16x16x32_bf16 v[14:17], v[132:135], v[212:215], v[14:17]
	v_mfma_f32_16x16x32_bf16 v[10:13], v[140:143], v[212:215], v[10:13]
	v_mfma_f32_16x16x32_bf16 v[74:77], v[136:139], v[192:195], v[74:77]
	v_mfma_f32_16x16x32_bf16 v[70:73], v[168:171], v[192:195], v[70:73]
	v_mfma_f32_16x16x32_bf16 v[46:49], v[136:139], v[200:203], v[46:49]
	v_mfma_f32_16x16x32_bf16 v[42:45], v[168:171], v[200:203], v[42:45]
	v_mfma_f32_16x16x32_bf16 v[30:33], v[136:139], v[208:211], v[30:33]
	v_mfma_f32_16x16x32_bf16 v[26:29], v[168:171], v[208:211], v[26:29]
	v_mfma_f32_16x16x32_bf16 v[14:17], v[136:139], v[216:219], v[14:17]
	v_mfma_f32_16x16x32_bf16 v[10:13], v[168:171], v[216:219], v[10:13]
	s_setprio 0
	s_setprio 1
	v_mfma_f32_16x16x32_bf16 v[66:69], v[172:175], v[188:191], v[66:69]
	v_mfma_f32_16x16x32_bf16 v[58:61], v[180:183], v[188:191], v[58:61]
	v_mfma_f32_16x16x32_bf16 v[38:41], v[172:175], v[196:199], v[38:41]
	v_mfma_f32_16x16x32_bf16 v[34:37], v[180:183], v[196:199], v[34:37]
	v_mfma_f32_16x16x32_bf16 v[22:25], v[172:175], v[204:207], v[22:25]
	v_mfma_f32_16x16x32_bf16 v[18:21], v[180:183], v[204:207], v[18:21]
	v_mfma_f32_16x16x32_bf16 v[6:9], v[172:175], v[212:215], v[6:9]
	v_mfma_f32_16x16x32_bf16 v[2:5], v[180:183], v[212:215], v[2:5]
	v_mfma_f32_16x16x32_bf16 v[66:69], v[176:179], v[192:195], v[66:69]
	v_mfma_f32_16x16x32_bf16 v[58:61], v[184:187], v[192:195], v[58:61]
	v_mfma_f32_16x16x32_bf16 v[38:41], v[176:179], v[200:203], v[38:41]
	v_mfma_f32_16x16x32_bf16 v[34:37], v[184:187], v[200:203], v[34:37]
	v_mfma_f32_16x16x32_bf16 v[22:25], v[176:179], v[208:211], v[22:25]
	v_mfma_f32_16x16x32_bf16 v[18:21], v[184:187], v[208:211], v[18:21]
	v_mfma_f32_16x16x32_bf16 v[6:9], v[176:179], v[216:219], v[6:9]
	v_mfma_f32_16x16x32_bf16 v[2:5], v[184:187], v[216:219], v[2:5]
	s_barrier
	s_setprio 0
	s_add_i32 s26, s26, 2
	s_add_u32 s62, s62, 0x100
	s_addc_u32 s63, s63, 0
	s_add_u32 s14, s14, 0x100
	s_addc_u32 s15, s15, 0
	s_cmp_gt_u32 s26, 5
	s_cbranch_scc0 .LBB0_716
	s_and_b64 vcc, exec, s[16:17]
	s_cbranch_vccz .LBB0_719
	s_barrier

.LBB0_930:
	ds_read_b128 v[134:137], v130
	ds_read_b128 v[138:141], v130 offset:1024
	ds_read_b128 v[142:145], v130 offset:2048
	ds_read_b128 v[146:149], v130 offset:3072
	ds_read_b128 v[168:171], v131
	ds_read_b128 v[174:177], v131 offset:1024
	ds_read_b128 v[178:181], v131 offset:2048
	ds_read_b128 v[182:185], v131 offset:3072
	s_add_u32 s27, s62, 0xfff80080
	s_addc_u32 s50, s63, -1
	s_cmp_eq_u32 s26, 28
	s_cselect_b32 s65, s7, s50
	s_cselect_b32 s64, s6, s27
	s_cselect_b32 s51, s49, s15
	s_cselect_b32 s50, s48, s14
	s_mov_b32 m0, s0
	ds_read_b128 v[186:189], v172
	ds_read_b128 v[190:193], v172 offset:1024
	ds_read_b128 v[194:197], v172 offset:2048
	ds_read_b128 v[198:201], v172 offset:3072
	ds_read_b128 v[202:205], v172 offset:4096
	ds_read_b128 v[206:209], v172 offset:5120
	ds_read_b128 v[210:213], v172 offset:6144
	ds_read_b128 v[214:217], v172 offset:7168
	global_load_lds_dwordx4 v160, s[62:63]
	s_mov_b32 m0, s11
	s_nop 0
	global_load_lds_dwordx4 v162, s[62:63]
	s_waitcnt vmcnt(8)
	s_waitcnt lgkmcnt(0)
	s_setprio 1
	s_barrier
	v_mfma_f32_16x16x32_bf16 v[126:129], v[134:137], v[186:189], v[126:129]
	v_mfma_f32_16x16x32_bf16 v[122:125], v[142:145], v[186:189], v[122:125]
	v_mfma_f32_16x16x32_bf16 v[118:121], v[134:137], v[194:197], v[118:121]
	v_mfma_f32_16x16x32_bf16 v[114:117], v[142:145], v[194:197], v[114:117]
	v_mfma_f32_16x16x32_bf16 v[110:113], v[134:137], v[202:205], v[110:113]
	v_mfma_f32_16x16x32_bf16 v[106:109], v[142:145], v[202:205], v[106:109]
	v_mfma_f32_16x16x32_bf16 v[102:105], v[134:137], v[210:213], v[102:105]
	v_mfma_f32_16x16x32_bf16 v[98:101], v[142:145], v[210:213], v[98:101]
	v_mfma_f32_16x16x32_bf16 v[126:129], v[138:141], v[190:193], v[126:129]
	v_mfma_f32_16x16x32_bf16 v[122:125], v[146:149], v[190:193], v[122:125]
	v_mfma_f32_16x16x32_bf16 v[118:121], v[138:141], v[198:201], v[118:121]
	v_mfma_f32_16x16x32_bf16 v[114:117], v[146:149], v[198:201], v[114:117]
	v_mfma_f32_16x16x32_bf16 v[110:113], v[138:141], v[206:209], v[110:113]
	v_mfma_f32_16x16x32_bf16 v[106:109], v[146:149], v[206:209], v[106:109]
	v_mfma_f32_16x16x32_bf16 v[102:105], v[138:141], v[214:217], v[102:105]
	v_mfma_f32_16x16x32_bf16 v[98:101], v[146:149], v[214:217], v[98:101]
	s_setprio 0
	s_setprio 1
	v_mfma_f32_16x16x32_bf16 v[94:97], v[168:171], v[186:189], v[94:97]
	v_mfma_f32_16x16x32_bf16 v[90:93], v[178:181], v[186:189], v[90:93]
	v_mfma_f32_16x16x32_bf16 v[86:89], v[168:171], v[194:197], v[86:89]
	v_mfma_f32_16x16x32_bf16 v[82:85], v[178:181], v[194:197], v[82:85]
	v_mfma_f32_16x16x32_bf16 v[78:81], v[168:171], v[202:205], v[78:81]
	v_mfma_f32_16x16x32_bf16 v[74:77], v[178:181], v[202:205], v[74:77]
	v_mfma_f32_16x16x32_bf16 v[70:73], v[168:171], v[210:213], v[70:73]
	v_mfma_f32_16x16x32_bf16 v[66:69], v[178:181], v[210:213], v[66:69]
	v_mfma_f32_16x16x32_bf16 v[94:97], v[174:177], v[190:193], v[94:97]
	v_mfma_f32_16x16x32_bf16 v[90:93], v[182:185], v[190:193], v[90:93]
	v_mfma_f32_16x16x32_bf16 v[86:89], v[174:177], v[198:201], v[86:89]
	v_mfma_f32_16x16x32_bf16 v[82:85], v[182:185], v[198:201], v[82:85]
	v_mfma_f32_16x16x32_bf16 v[78:81], v[174:177], v[206:209], v[78:81]
	v_mfma_f32_16x16x32_bf16 v[74:77], v[182:185], v[206:209], v[74:77]
	v_mfma_f32_16x16x32_bf16 v[70:73], v[174:177], v[214:217], v[70:73]
	v_mfma_f32_16x16x32_bf16 v[66:69], v[182:185], v[214:217], v[66:69]
	s_barrier
	s_setprio 0
	s_mov_b32 m0, s12
	s_mov_b64 s[98:99], s[50:51]
	s_add_u32 s58, s50, 0x80000
	ds_read_b128 v[186:189], v172 offset:16384
	ds_read_b128 v[190:193], v172 offset:17408
	ds_read_b128 v[194:197], v172 offset:18432
	ds_read_b128 v[198:201], v172 offset:19456
	ds_read_b128 v[202:205], v172 offset:20480
	ds_read_b128 v[206:209], v172 offset:21504
	ds_read_b128 v[210:213], v172 offset:22528
	ds_read_b128 v[214:217], v172 offset:23552
	global_load_lds_dwordx4 v152, s[50:51]
	s_mov_b32 m0, s13
	s_addc_u32 s59, s51, 0
	global_load_lds_dwordx4 v156, s[50:51]
	s_mov_b32 m0, s43
	s_mov_b64 s[100:101], s[64:65]
	global_load_lds_dwordx4 v152, s[58:59]
	s_mov_b32 m0, s46
	s_nop 0
	global_load_lds_dwordx4 v156, s[58:59]
	s_waitcnt vmcnt(6)
	s_waitcnt lgkmcnt(0)
	s_setprio 1
	s_barrier
	v_mfma_f32_16x16x32_bf16 v[62:65], v[134:137], v[186:189], v[62:65]
	v_mfma_f32_16x16x32_bf16 v[58:61], v[142:145], v[186:189], v[58:61]
	v_mfma_f32_16x16x32_bf16 v[54:57], v[134:137], v[194:197], v[54:57]
	v_mfma_f32_16x16x32_bf16 v[50:53], v[142:145], v[194:197], v[50:53]
	v_mfma_f32_16x16x32_bf16 v[46:49], v[134:137], v[202:205], v[46:49]
	v_mfma_f32_16x16x32_bf16 v[42:45], v[142:145], v[202:205], v[42:45]
	v_mfma_f32_16x16x32_bf16 v[38:41], v[134:137], v[210:213], v[38:41]
	v_mfma_f32_16x16x32_bf16 v[34:37], v[142:145], v[210:213], v[34:37]
	v_mfma_f32_16x16x32_bf16 v[62:65], v[138:141], v[190:193], v[62:65]
	v_mfma_f32_16x16x32_bf16 v[58:61], v[146:149], v[190:193], v[58:61]
	v_mfma_f32_16x16x32_bf16 v[54:57], v[138:141], v[198:201], v[54:57]
	v_mfma_f32_16x16x32_bf16 v[50:53], v[146:149], v[198:201], v[50:53]
	v_mfma_f32_16x16x32_bf16 v[46:49], v[138:141], v[206:209], v[46:49]
	v_mfma_f32_16x16x32_bf16 v[42:45], v[146:149], v[206:209], v[42:45]
	v_mfma_f32_16x16x32_bf16 v[38:41], v[138:141], v[214:217], v[38:41]
	v_mfma_f32_16x16x32_bf16 v[34:37], v[146:149], v[214:217], v[34:37]
	s_setprio 0
	s_setprio 1
	v_mfma_f32_16x16x32_bf16 v[30:33], v[168:171], v[186:189], v[30:33]
	v_mfma_f32_16x16x32_bf16 v[26:29], v[178:181], v[186:189], v[26:29]
	v_mfma_f32_16x16x32_bf16 v[22:25], v[168:171], v[194:197], v[22:25]
	v_mfma_f32_16x16x32_bf16 v[18:21], v[178:181], v[194:197], v[18:21]
	v_mfma_f32_16x16x32_bf16 v[14:17], v[168:171], v[202:205], v[14:17]
	v_mfma_f32_16x16x32_bf16 v[10:13], v[178:181], v[202:205], v[10:13]
	v_mfma_f32_16x16x32_bf16 v[6:9], v[168:171], v[210:213], v[6:9]
	v_mfma_f32_16x16x32_bf16 v[2:5], v[178:181], v[210:213], v[2:5]
	v_mfma_f32_16x16x32_bf16 v[30:33], v[174:177], v[190:193], v[30:33]
	v_mfma_f32_16x16x32_bf16 v[26:29], v[182:185], v[190:193], v[26:29]
	v_mfma_f32_16x16x32_bf16 v[22:25], v[174:177], v[198:201], v[22:25]
	v_mfma_f32_16x16x32_bf16 v[18:21], v[182:185], v[198:201], v[18:21]
	v_mfma_f32_16x16x32_bf16 v[14:17], v[174:177], v[206:209], v[14:17]
	v_mfma_f32_16x16x32_bf16 v[10:13], v[182:185], v[206:209], v[10:13]
	v_mfma_f32_16x16x32_bf16 v[6:9], v[174:177], v[214:217], v[6:9]
	v_mfma_f32_16x16x32_bf16 v[2:5], v[182:185], v[214:217], v[2:5]
	s_barrier
	s_setprio 0
	ds_read_b128 v[134:137], v132
	ds_read_b128 v[138:141], v132 offset:1024
	ds_read_b128 v[142:145], v132 offset:2048
	ds_read_b128 v[146:149], v132 offset:3072
	ds_read_b128 v[168:171], v133
	ds_read_b128 v[174:177], v133 offset:1024
	ds_read_b128 v[178:181], v133 offset:2048
	ds_read_b128 v[182:185], v133 offset:3072
	s_add_u32 s58, s64, 0x80000
	s_addc_u32 s59, s65, 0
	s_mov_b32 m0, s69
	s_nop 0
	global_load_lds_dwordx4 v150, s[100:101]
	s_mov_b32 m0, s70
	s_nop 0
	global_load_lds_dwordx4 v154, s[100:101]
	s_mov_b32 m0, s71
	ds_read_b128 v[186:189], v172 offset:32768
	ds_read_b128 v[190:193], v172 offset:33792
	ds_read_b128 v[194:197], v172 offset:34816
	ds_read_b128 v[198:201], v172 offset:35840
	ds_read_b128 v[202:205], v172 offset:36864
	ds_read_b128 v[206:209], v172 offset:37888
	ds_read_b128 v[210:213], v172 offset:38912
	ds_read_b128 v[214:217], v172 offset:39936
	global_load_lds_dwordx4 v150, s[58:59]
	s_mov_b32 m0, s72
	s_nop 0
	global_load_lds_dwordx4 v154, s[58:59]
	s_waitcnt vmcnt(8)
	s_waitcnt lgkmcnt(0)
	s_setprio 1
	s_barrier
	v_mfma_f32_16x16x32_bf16 v[126:129], v[134:137], v[186:189], v[126:129]
	v_mfma_f32_16x16x32_bf16 v[122:125], v[142:145], v[186:189], v[122:125]
	v_mfma_f32_16x16x32_bf16 v[118:121], v[134:137], v[194:197], v[118:121]
	v_mfma_f32_16x16x32_bf16 v[114:117], v[142:145], v[194:197], v[114:117]
	v_mfma_f32_16x16x32_bf16 v[110:113], v[134:137], v[202:205], v[110:113]
	v_mfma_f32_16x16x32_bf16 v[106:109], v[142:145], v[202:205], v[106:109]
	v_mfma_f32_16x16x32_bf16 v[102:105], v[134:137], v[210:213], v[102:105]
	v_mfma_f32_16x16x32_bf16 v[98:101], v[142:145], v[210:213], v[98:101]
	v_mfma_f32_16x16x32_bf16 v[126:129], v[138:141], v[190:193], v[126:129]
	v_mfma_f32_16x16x32_bf16 v[122:125], v[146:149], v[190:193], v[122:125]
	v_mfma_f32_16x16x32_bf16 v[118:121], v[138:141], v[198:201], v[118:121]
	v_mfma_f32_16x16x32_bf16 v[114:117], v[146:149], v[198:201], v[114:117]
	v_mfma_f32_16x16x32_bf16 v[110:113], v[138:141], v[206:209], v[110:113]
	v_mfma_f32_16x16x32_bf16 v[106:109], v[146:149], v[206:209], v[106:109]
	v_mfma_f32_16x16x32_bf16 v[102:105], v[138:141], v[214:217], v[102:105]
	v_mfma_f32_16x16x32_bf16 v[98:101], v[146:149], v[214:217], v[98:101]
	s_setprio 0
	s_setprio 1
	v_mfma_f32_16x16x32_bf16 v[94:97], v[168:171], v[186:189], v[94:97]
	v_mfma_f32_16x16x32_bf16 v[90:93], v[178:181], v[186:189], v[90:93]
	v_mfma_f32_16x16x32_bf16 v[86:89], v[168:171], v[194:197], v[86:89]
	v_mfma_f32_16x16x32_bf16 v[82:85], v[178:181], v[194:197], v[82:85]
	v_mfma_f32_16x16x32_bf16 v[78:81], v[168:171], v[202:205], v[78:81]
	v_mfma_f32_16x16x32_bf16 v[74:77], v[178:181], v[202:205], v[74:77]
	v_mfma_f32_16x16x32_bf16 v[70:73], v[168:171], v[210:213], v[70:73]
	v_mfma_f32_16x16x32_bf16 v[66:69], v[178:181], v[210:213], v[66:69]
	v_mfma_f32_16x16x32_bf16 v[94:97], v[174:177], v[190:193], v[94:97]
	v_mfma_f32_16x16x32_bf16 v[90:93], v[182:185], v[190:193], v[90:93]
	v_mfma_f32_16x16x32_bf16 v[86:89], v[174:177], v[198:201], v[86:89]
	v_mfma_f32_16x16x32_bf16 v[82:85], v[182:185], v[198:201], v[82:85]
	v_mfma_f32_16x16x32_bf16 v[78:81], v[174:177], v[206:209], v[78:81]
	v_mfma_f32_16x16x32_bf16 v[74:77], v[182:185], v[206:209], v[74:77]
	v_mfma_f32_16x16x32_bf16 v[70:73], v[174:177], v[214:217], v[70:73]
	v_mfma_f32_16x16x32_bf16 v[66:69], v[182:185], v[214:217], v[66:69]
	s_barrier
	s_setprio 0
	s_mov_b32 m0, s47
	s_add_u32 s98, s98, 0x80
	s_addc_u32 s99, s99, 0
	s_add_u32 s100, s100, 0x80
	s_addc_u32 s101, s101, 0
	s_add_u32 s50, s50, 0x80080
	ds_read_b128 v[186:189], v172 offset:49152
	ds_read_b128 v[190:193], v172 offset:50176
	ds_read_b128 v[194:197], v172 offset:51200
	ds_read_b128 v[198:201], v172 offset:52224
	ds_read_b128 v[202:205], v172 offset:53248
	ds_read_b128 v[206:209], v172 offset:54272
	ds_read_b128 v[210:213], v172 offset:55296
	ds_read_b128 v[214:217], v172 offset:56320
	global_load_lds_dwordx4 v152, s[98:99]
	s_mov_b32 m0, s53
	s_addc_u32 s51, s51, 0
	global_load_lds_dwordx4 v156, s[98:99]
	s_mov_b32 m0, s55
	s_nop 0
	global_load_lds_dwordx4 v152, s[50:51]
	s_mov_b32 m0, s56
	s_nop 0
	global_load_lds_dwordx4 v156, s[50:51]
	s_mov_b32 m0, s77
	s_nop 0
	global_load_lds_dwordx4 v150, s[100:101]
	s_mov_b32 m0, s78
	s_nop 0
	global_load_lds_dwordx4 v154, s[100:101]
	s_waitcnt vmcnt(8)
	s_waitcnt lgkmcnt(0)
	s_setprio 1
	s_barrier
	v_mfma_f32_16x16x32_bf16 v[62:65], v[134:137], v[186:189], v[62:65]
	v_mfma_f32_16x16x32_bf16 v[58:61], v[142:145], v[186:189], v[58:61]
	v_mfma_f32_16x16x32_bf16 v[54:57], v[134:137], v[194:197], v[54:57]
	v_mfma_f32_16x16x32_bf16 v[50:53], v[142:145], v[194:197], v[50:53]
	v_mfma_f32_16x16x32_bf16 v[46:49], v[134:137], v[202:205], v[46:49]
	v_mfma_f32_16x16x32_bf16 v[42:45], v[142:145], v[202:205], v[42:45]
	v_mfma_f32_16x16x32_bf16 v[38:41], v[134:137], v[210:213], v[38:41]
	v_mfma_f32_16x16x32_bf16 v[34:37], v[142:145], v[210:213], v[34:37]
	v_mfma_f32_16x16x32_bf16 v[62:65], v[138:141], v[190:193], v[62:65]
	v_mfma_f32_16x16x32_bf16 v[58:61], v[146:149], v[190:193], v[58:61]
	v_mfma_f32_16x16x32_bf16 v[54:57], v[138:141], v[198:201], v[54:57]
	v_mfma_f32_16x16x32_bf16 v[50:53], v[146:149], v[198:201], v[50:53]
	v_mfma_f32_16x16x32_bf16 v[46:49], v[138:141], v[206:209], v[46:49]
	v_mfma_f32_16x16x32_bf16 v[42:45], v[146:149], v[206:209], v[42:45]
	v_mfma_f32_16x16x32_bf16 v[38:41], v[138:141], v[214:217], v[38:41]
	v_mfma_f32_16x16x32_bf16 v[34:37], v[146:149], v[214:217], v[34:37]
	s_setprio 0
	s_setprio 1
	v_mfma_f32_16x16x32_bf16 v[30:33], v[168:171], v[186:189], v[30:33]
	v_mfma_f32_16x16x32_bf16 v[26:29], v[178:181], v[186:189], v[26:29]
	v_mfma_f32_16x16x32_bf16 v[22:25], v[168:171], v[194:197], v[22:25]
	v_mfma_f32_16x16x32_bf16 v[18:21], v[178:181], v[194:197], v[18:21]
	v_mfma_f32_16x16x32_bf16 v[14:17], v[168:171], v[202:205], v[14:17]
	v_mfma_f32_16x16x32_bf16 v[10:13], v[178:181], v[202:205], v[10:13]
	v_mfma_f32_16x16x32_bf16 v[6:9], v[168:171], v[210:213], v[6:9]
	v_mfma_f32_16x16x32_bf16 v[2:5], v[178:181], v[210:213], v[2:5]
	v_mfma_f32_16x16x32_bf16 v[30:33], v[174:177], v[190:193], v[30:33]
	v_mfma_f32_16x16x32_bf16 v[26:29], v[182:185], v[190:193], v[26:29]
	v_mfma_f32_16x16x32_bf16 v[22:25], v[174:177], v[198:201], v[22:25]
	v_mfma_f32_16x16x32_bf16 v[18:21], v[182:185], v[198:201], v[18:21]
	v_mfma_f32_16x16x32_bf16 v[14:17], v[174:177], v[206:209], v[14:17]
	v_mfma_f32_16x16x32_bf16 v[10:13], v[182:185], v[206:209], v[10:13]
	v_mfma_f32_16x16x32_bf16 v[6:9], v[174:177], v[214:217], v[6:9]
	v_mfma_f32_16x16x32_bf16 v[2:5], v[182:185], v[214:217], v[2:5]
	s_barrier
	s_setprio 0
	s_add_i32 s26, s26, 2
	s_add_u32 s62, s62, 0x100
	s_addc_u32 s63, s63, 0
	s_add_u32 s14, s14, 0x100
	s_addc_u32 s15, s15, 0
	s_cmp_gt_u32 s26, 29
	s_cbranch_scc0 .LBB0_930
	s_and_b64 vcc, exec, s[18:19]
	s_cbranch_vccz .LBB0_933
	s_barrier

.LBB0_1014:
	ds_read_b128 v[132:135], v182
	ds_read_b128 v[136:139], v182 offset:1024
	ds_read_b128 v[140:143], v182 offset:2048
	ds_read_b128 v[144:147], v182 offset:3072
	ds_read_b128 v[148:151], v183
	ds_read_b128 v[170:173], v183 offset:1024
	ds_read_b128 v[174:177], v183 offset:2048
	ds_read_b128 v[178:181], v183 offset:3072
	s_add_u32 s27, s48, 0xfff00080
	s_addc_u32 s42, s49, -1
	s_cmp_eq_u32 s26, 60
	s_cselect_b32 s51, s29, s42
	s_cselect_b32 s50, s41, s27
	s_cselect_b32 s43, s0, s15
	s_cselect_b32 s42, s68, s14
	s_mov_b32 m0, s61
	ds_read_b128 v[186:189], v184
	ds_read_b128 v[190:193], v184 offset:1024
	ds_read_b128 v[194:197], v184 offset:2048
	ds_read_b128 v[198:201], v184 offset:3072
	ds_read_b128 v[202:205], v184 offset:4096
	ds_read_b128 v[206:209], v184 offset:5120
	ds_read_b128 v[210:213], v184 offset:6144
	ds_read_b128 v[214:217], v184 offset:7168
	global_load_lds_dwordx4 v162, s[48:49]
	s_mov_b32 m0, s62
	s_nop 0
	global_load_lds_dwordx4 v164, s[48:49]
	s_waitcnt vmcnt(8)
	s_waitcnt lgkmcnt(0)
	s_setprio 1
	s_barrier
	v_mfma_f32_16x16x32_bf16 v[122:125], v[132:135], v[186:189], v[122:125]
	v_mfma_f32_16x16x32_bf16 v[118:121], v[140:143], v[186:189], v[118:121]
	v_mfma_f32_16x16x32_bf16 v[110:113], v[132:135], v[194:197], v[110:113]
	v_mfma_f32_16x16x32_bf16 v[106:109], v[140:143], v[194:197], v[106:109]
	v_mfma_f32_16x16x32_bf16 v[94:97], v[132:135], v[202:205], v[94:97]
	v_mfma_f32_16x16x32_bf16 v[90:93], v[140:143], v[202:205], v[90:93]
	v_mfma_f32_16x16x32_bf16 v[78:81], v[132:135], v[210:213], v[78:81]
	v_mfma_f32_16x16x32_bf16 v[74:77], v[140:143], v[210:213], v[74:77]
	v_mfma_f32_16x16x32_bf16 v[122:125], v[136:139], v[190:193], v[122:125]
	v_mfma_f32_16x16x32_bf16 v[118:121], v[144:147], v[190:193], v[118:121]
	v_mfma_f32_16x16x32_bf16 v[110:113], v[136:139], v[198:201], v[110:113]
	v_mfma_f32_16x16x32_bf16 v[106:109], v[144:147], v[198:201], v[106:109]
	v_mfma_f32_16x16x32_bf16 v[94:97], v[136:139], v[206:209], v[94:97]
	v_mfma_f32_16x16x32_bf16 v[90:93], v[144:147], v[206:209], v[90:93]
	v_mfma_f32_16x16x32_bf16 v[78:81], v[136:139], v[214:217], v[78:81]
	v_mfma_f32_16x16x32_bf16 v[74:77], v[144:147], v[214:217], v[74:77]
	s_setprio 0
	s_setprio 1
	v_mfma_f32_16x16x32_bf16 v[126:129], v[148:151], v[186:189], v[126:129]
	v_mfma_f32_16x16x32_bf16 v[114:117], v[174:177], v[186:189], v[114:117]
	v_mfma_f32_16x16x32_bf16 v[102:105], v[148:151], v[194:197], v[102:105]
	v_mfma_f32_16x16x32_bf16 v[98:101], v[174:177], v[194:197], v[98:101]
	v_mfma_f32_16x16x32_bf16 v[86:89], v[148:151], v[202:205], v[86:89]
	v_mfma_f32_16x16x32_bf16 v[82:85], v[174:177], v[202:205], v[82:85]
	v_mfma_f32_16x16x32_bf16 v[70:73], v[148:151], v[210:213], v[70:73]
	v_mfma_f32_16x16x32_bf16 v[66:69], v[174:177], v[210:213], v[66:69]
	v_mfma_f32_16x16x32_bf16 v[126:129], v[170:173], v[190:193], v[126:129]
	v_mfma_f32_16x16x32_bf16 v[114:117], v[178:181], v[190:193], v[114:117]
	v_mfma_f32_16x16x32_bf16 v[102:105], v[170:173], v[198:201], v[102:105]
	v_mfma_f32_16x16x32_bf16 v[98:101], v[178:181], v[198:201], v[98:101]
	v_mfma_f32_16x16x32_bf16 v[86:89], v[170:173], v[206:209], v[86:89]
	v_mfma_f32_16x16x32_bf16 v[82:85], v[178:181], v[206:209], v[82:85]
	v_mfma_f32_16x16x32_bf16 v[70:73], v[170:173], v[214:217], v[70:73]
	v_mfma_f32_16x16x32_bf16 v[66:69], v[178:181], v[214:217], v[66:69]
	s_barrier
	s_setprio 0
	s_mov_b32 m0, s63
	s_mov_b64 s[98:99], s[42:43]
	s_add_u32 s72, s42, 0x100000
	ds_read_b128 v[186:189], v184 offset:16384
	ds_read_b128 v[190:193], v184 offset:17408
	ds_read_b128 v[194:197], v184 offset:18432
	ds_read_b128 v[198:201], v184 offset:19456
	ds_read_b128 v[202:205], v184 offset:20480
	ds_read_b128 v[206:209], v184 offset:21504
	ds_read_b128 v[210:213], v184 offset:22528
	ds_read_b128 v[214:217], v184 offset:23552
	global_load_lds_dwordx4 v156, s[42:43]
	s_mov_b32 m0, s64
	s_addc_u32 s73, s43, 0
	global_load_lds_dwordx4 v160, s[42:43]
	s_mov_b32 m0, s69
	s_mov_b64 s[100:101], s[50:51]
	global_load_lds_dwordx4 v156, s[72:73]
	s_mov_b32 m0, s46
	s_nop 0
	global_load_lds_dwordx4 v160, s[72:73]
	s_waitcnt vmcnt(6)
	s_waitcnt lgkmcnt(0)
	s_setprio 1
	s_barrier
	v_mfma_f32_16x16x32_bf16 v[58:61], v[132:135], v[186:189], v[58:61]
	v_mfma_f32_16x16x32_bf16 v[54:57], v[140:143], v[186:189], v[54:57]
	v_mfma_f32_16x16x32_bf16 v[46:49], v[132:135], v[194:197], v[46:49]
	v_mfma_f32_16x16x32_bf16 v[42:45], v[140:143], v[194:197], v[42:45]
	v_mfma_f32_16x16x32_bf16 v[30:33], v[132:135], v[202:205], v[30:33]
	v_mfma_f32_16x16x32_bf16 v[26:29], v[140:143], v[202:205], v[26:29]
	v_mfma_f32_16x16x32_bf16 v[14:17], v[132:135], v[210:213], v[14:17]
	v_mfma_f32_16x16x32_bf16 v[10:13], v[140:143], v[210:213], v[10:13]
	v_mfma_f32_16x16x32_bf16 v[58:61], v[136:139], v[190:193], v[58:61]
	v_mfma_f32_16x16x32_bf16 v[54:57], v[144:147], v[190:193], v[54:57]
	v_mfma_f32_16x16x32_bf16 v[46:49], v[136:139], v[198:201], v[46:49]
	v_mfma_f32_16x16x32_bf16 v[42:45], v[144:147], v[198:201], v[42:45]
	v_mfma_f32_16x16x32_bf16 v[30:33], v[136:139], v[206:209], v[30:33]
	v_mfma_f32_16x16x32_bf16 v[26:29], v[144:147], v[206:209], v[26:29]
	v_mfma_f32_16x16x32_bf16 v[14:17], v[136:139], v[214:217], v[14:17]
	v_mfma_f32_16x16x32_bf16 v[10:13], v[144:147], v[214:217], v[10:13]
	s_setprio 0
	s_setprio 1
	v_mfma_f32_16x16x32_bf16 v[62:65], v[148:151], v[186:189], v[62:65]
	v_mfma_f32_16x16x32_bf16 v[50:53], v[174:177], v[186:189], v[50:53]
	v_mfma_f32_16x16x32_bf16 v[38:41], v[148:151], v[194:197], v[38:41]
	v_mfma_f32_16x16x32_bf16 v[34:37], v[174:177], v[194:197], v[34:37]
	v_mfma_f32_16x16x32_bf16 v[22:25], v[148:151], v[202:205], v[22:25]
	v_mfma_f32_16x16x32_bf16 v[18:21], v[174:177], v[202:205], v[18:21]
	v_mfma_f32_16x16x32_bf16 v[6:9], v[148:151], v[210:213], v[6:9]
	v_mfma_f32_16x16x32_bf16 v[2:5], v[174:177], v[210:213], v[2:5]
	v_mfma_f32_16x16x32_bf16 v[62:65], v[170:173], v[190:193], v[62:65]
	v_mfma_f32_16x16x32_bf16 v[50:53], v[178:181], v[190:193], v[50:53]
	v_mfma_f32_16x16x32_bf16 v[38:41], v[170:173], v[198:201], v[38:41]
	v_mfma_f32_16x16x32_bf16 v[34:37], v[178:181], v[198:201], v[34:37]
	v_mfma_f32_16x16x32_bf16 v[22:25], v[170:173], v[206:209], v[22:25]
	v_mfma_f32_16x16x32_bf16 v[18:21], v[178:181], v[206:209], v[18:21]
	v_mfma_f32_16x16x32_bf16 v[6:9], v[170:173], v[214:217], v[6:9]
	v_mfma_f32_16x16x32_bf16 v[2:5], v[178:181], v[214:217], v[2:5]
	s_barrier
	s_setprio 0
	ds_read_b128 v[132:135], v130
	ds_read_b128 v[136:139], v130 offset:1024
	ds_read_b128 v[140:143], v130 offset:2048
	ds_read_b128 v[144:147], v130 offset:3072
	ds_read_b128 v[148:151], v131
	ds_read_b128 v[170:173], v131 offset:1024
	ds_read_b128 v[174:177], v131 offset:2048
	ds_read_b128 v[178:181], v131 offset:3072
	s_add_u32 s50, s50, 0x100000
	s_addc_u32 s51, s51, 0
	s_mov_b32 m0, s13
	s_nop 0
	global_load_lds_dwordx4 v154, s[100:101]
	s_mov_b32 m0, s33
	s_nop 0
	global_load_lds_dwordx4 v158, s[100:101]
	s_mov_b32 m0, s52
	ds_read_b128 v[186:189], v184 offset:32768
	ds_read_b128 v[190:193], v184 offset:33792
	ds_read_b128 v[194:197], v184 offset:34816
	ds_read_b128 v[198:201], v184 offset:35840
	ds_read_b128 v[202:205], v184 offset:36864
	ds_read_b128 v[206:209], v184 offset:37888
	ds_read_b128 v[210:213], v184 offset:38912
	ds_read_b128 v[214:217], v184 offset:39936
	global_load_lds_dwordx4 v154, s[50:51]
	s_mov_b32 m0, s53
	s_nop 0
	global_load_lds_dwordx4 v158, s[50:51]
	s_waitcnt vmcnt(8)
	s_waitcnt lgkmcnt(0)
	s_setprio 1
	s_barrier
	v_mfma_f32_16x16x32_bf16 v[122:125], v[132:135], v[186:189], v[122:125]
	v_mfma_f32_16x16x32_bf16 v[118:121], v[140:143], v[186:189], v[118:121]
	v_mfma_f32_16x16x32_bf16 v[110:113], v[132:135], v[194:197], v[110:113]
	v_mfma_f32_16x16x32_bf16 v[106:109], v[140:143], v[194:197], v[106:109]
	v_mfma_f32_16x16x32_bf16 v[94:97], v[132:135], v[202:205], v[94:97]
	v_mfma_f32_16x16x32_bf16 v[90:93], v[140:143], v[202:205], v[90:93]
	v_mfma_f32_16x16x32_bf16 v[78:81], v[132:135], v[210:213], v[78:81]
	v_mfma_f32_16x16x32_bf16 v[74:77], v[140:143], v[210:213], v[74:77]
	v_mfma_f32_16x16x32_bf16 v[122:125], v[136:139], v[190:193], v[122:125]
	v_mfma_f32_16x16x32_bf16 v[118:121], v[144:147], v[190:193], v[118:121]
	v_mfma_f32_16x16x32_bf16 v[110:113], v[136:139], v[198:201], v[110:113]
	v_mfma_f32_16x16x32_bf16 v[106:109], v[144:147], v[198:201], v[106:109]
	v_mfma_f32_16x16x32_bf16 v[94:97], v[136:139], v[206:209], v[94:97]
	v_mfma_f32_16x16x32_bf16 v[90:93], v[144:147], v[206:209], v[90:93]
	v_mfma_f32_16x16x32_bf16 v[78:81], v[136:139], v[214:217], v[78:81]
	v_mfma_f32_16x16x32_bf16 v[74:77], v[144:147], v[214:217], v[74:77]
	s_setprio 0
	s_setprio 1
	v_mfma_f32_16x16x32_bf16 v[126:129], v[148:151], v[186:189], v[126:129]
	v_mfma_f32_16x16x32_bf16 v[114:117], v[174:177], v[186:189], v[114:117]
	v_mfma_f32_16x16x32_bf16 v[102:105], v[148:151], v[194:197], v[102:105]
	v_mfma_f32_16x16x32_bf16 v[98:101], v[174:177], v[194:197], v[98:101]
	v_mfma_f32_16x16x32_bf16 v[86:89], v[148:151], v[202:205], v[86:89]
	v_mfma_f32_16x16x32_bf16 v[82:85], v[174:177], v[202:205], v[82:85]
	v_mfma_f32_16x16x32_bf16 v[70:73], v[148:151], v[210:213], v[70:73]
	v_mfma_f32_16x16x32_bf16 v[66:69], v[174:177], v[210:213], v[66:69]
	v_mfma_f32_16x16x32_bf16 v[126:129], v[170:173], v[190:193], v[126:129]
	v_mfma_f32_16x16x32_bf16 v[114:117], v[178:181], v[190:193], v[114:117]
	v_mfma_f32_16x16x32_bf16 v[102:105], v[170:173], v[198:201], v[102:105]
	v_mfma_f32_16x16x32_bf16 v[98:101], v[178:181], v[198:201], v[98:101]
	v_mfma_f32_16x16x32_bf16 v[86:89], v[170:173], v[206:209], v[86:89]
	v_mfma_f32_16x16x32_bf16 v[82:85], v[178:181], v[206:209], v[82:85]
	v_mfma_f32_16x16x32_bf16 v[70:73], v[170:173], v[214:217], v[70:73]
	v_mfma_f32_16x16x32_bf16 v[66:69], v[178:181], v[214:217], v[66:69]
	s_barrier
	s_setprio 0
	s_mov_b32 m0, s47
	s_add_u32 s98, s98, 0x80
	s_addc_u32 s99, s99, 0
	s_add_u32 s100, s100, 0x80
	s_addc_u32 s101, s101, 0
	s_add_u32 s42, s42, 0x100080
	ds_read_b128 v[186:189], v184 offset:49152
	ds_read_b128 v[190:193], v184 offset:50176
	ds_read_b128 v[194:197], v184 offset:51200
	ds_read_b128 v[198:201], v184 offset:52224
	ds_read_b128 v[202:205], v184 offset:53248
	ds_read_b128 v[206:209], v184 offset:54272
	ds_read_b128 v[210:213], v184 offset:55296
	ds_read_b128 v[214:217], v184 offset:56320
	global_load_lds_dwordx4 v156, s[98:99]
	s_mov_b32 m0, s70
	s_addc_u32 s43, s43, 0
	global_load_lds_dwordx4 v160, s[98:99]
	s_mov_b32 m0, s56
	s_nop 0
	global_load_lds_dwordx4 v156, s[42:43]
	s_mov_b32 m0, s57
	s_nop 0
	global_load_lds_dwordx4 v160, s[42:43]
	s_mov_b32 m0, s54
	s_nop 0
	global_load_lds_dwordx4 v154, s[100:101]
	s_mov_b32 m0, s55
	s_nop 0
	global_load_lds_dwordx4 v158, s[100:101]
	s_waitcnt vmcnt(8)
	s_waitcnt lgkmcnt(0)
	s_setprio 1
	s_barrier
	v_mfma_f32_16x16x32_bf16 v[58:61], v[132:135], v[186:189], v[58:61]
	v_mfma_f32_16x16x32_bf16 v[54:57], v[140:143], v[186:189], v[54:57]
	v_mfma_f32_16x16x32_bf16 v[46:49], v[132:135], v[194:197], v[46:49]
	v_mfma_f32_16x16x32_bf16 v[42:45], v[140:143], v[194:197], v[42:45]
	v_mfma_f32_16x16x32_bf16 v[30:33], v[132:135], v[202:205], v[30:33]
	v_mfma_f32_16x16x32_bf16 v[26:29], v[140:143], v[202:205], v[26:29]
	v_mfma_f32_16x16x32_bf16 v[14:17], v[132:135], v[210:213], v[14:17]
	v_mfma_f32_16x16x32_bf16 v[10:13], v[140:143], v[210:213], v[10:13]
	v_mfma_f32_16x16x32_bf16 v[58:61], v[136:139], v[190:193], v[58:61]
	v_mfma_f32_16x16x32_bf16 v[54:57], v[144:147], v[190:193], v[54:57]
	v_mfma_f32_16x16x32_bf16 v[46:49], v[136:139], v[198:201], v[46:49]
	v_mfma_f32_16x16x32_bf16 v[42:45], v[144:147], v[198:201], v[42:45]
	v_mfma_f32_16x16x32_bf16 v[30:33], v[136:139], v[206:209], v[30:33]
	v_mfma_f32_16x16x32_bf16 v[26:29], v[144:147], v[206:209], v[26:29]
	v_mfma_f32_16x16x32_bf16 v[14:17], v[136:139], v[214:217], v[14:17]
	v_mfma_f32_16x16x32_bf16 v[10:13], v[144:147], v[214:217], v[10:13]
	s_setprio 0
	s_setprio 1
	v_mfma_f32_16x16x32_bf16 v[62:65], v[148:151], v[186:189], v[62:65]
	v_mfma_f32_16x16x32_bf16 v[50:53], v[174:177], v[186:189], v[50:53]
	v_mfma_f32_16x16x32_bf16 v[38:41], v[148:151], v[194:197], v[38:41]
	v_mfma_f32_16x16x32_bf16 v[34:37], v[174:177], v[194:197], v[34:37]
	v_mfma_f32_16x16x32_bf16 v[22:25], v[148:151], v[202:205], v[22:25]
	v_mfma_f32_16x16x32_bf16 v[18:21], v[174:177], v[202:205], v[18:21]
	v_mfma_f32_16x16x32_bf16 v[6:9], v[148:151], v[210:213], v[6:9]
	v_mfma_f32_16x16x32_bf16 v[2:5], v[174:177], v[210:213], v[2:5]
	v_mfma_f32_16x16x32_bf16 v[62:65], v[170:173], v[190:193], v[62:65]
	v_mfma_f32_16x16x32_bf16 v[50:53], v[178:181], v[190:193], v[50:53]
	v_mfma_f32_16x16x32_bf16 v[38:41], v[170:173], v[198:201], v[38:41]
	v_mfma_f32_16x16x32_bf16 v[34:37], v[178:181], v[198:201], v[34:37]
	v_mfma_f32_16x16x32_bf16 v[22:25], v[170:173], v[206:209], v[22:25]
	v_mfma_f32_16x16x32_bf16 v[18:21], v[178:181], v[206:209], v[18:21]
	v_mfma_f32_16x16x32_bf16 v[6:9], v[170:173], v[214:217], v[6:9]
	v_mfma_f32_16x16x32_bf16 v[2:5], v[178:181], v[214:217], v[2:5]
	s_barrier
	s_setprio 0
	s_add_i32 s26, s26, 2
	s_add_u32 s48, s48, 0x100
	s_addc_u32 s49, s49, 0
	s_add_u32 s14, s14, 0x100
	s_addc_u32 s15, s15, 0
	s_cmp_gt_u32 s26, 61
	s_cbranch_scc0 .LBB0_1014
	s_and_b64 vcc, exec, s[18:19]
	s_cbranch_vccz .LBB0_1017
	s_barrier

.LBB0_1110:
	ds_read_b128 v[152:155], v148
	ds_read_b128 v[156:159], v148 offset:1024
	ds_read_b128 v[160:163], v148 offset:2048
	ds_read_b128 v[164:167], v148 offset:3072
	ds_read_b128 v[168:171], v149
	ds_read_b128 v[172:175], v149 offset:1024
	ds_read_b128 v[176:179], v149 offset:2048
	ds_read_b128 v[180:183], v149 offset:3072
	s_add_u32 s27, s0, 0xfff00080
	s_addc_u32 s52, s1, -1
	s_cmp_eq_u32 s26, 28
	s_cselect_b32 s55, s43, s52
	s_cselect_b32 s54, s42, s27
	s_cselect_b32 s53, s49, s15
	s_cselect_b32 s52, s48, s14
	s_mov_b32 m0, s41
	ds_read_b128 v[184:187], v150
	ds_read_b128 v[188:191], v150 offset:1024
	ds_read_b128 v[192:195], v150 offset:2048
	ds_read_b128 v[196:199], v150 offset:3072
	ds_read_b128 v[200:203], v150 offset:4096
	ds_read_b128 v[204:207], v150 offset:5120
	ds_read_b128 v[208:211], v150 offset:6144
	ds_read_b128 v[212:215], v150 offset:7168
	global_load_lds_dwordx4 v136, s[0:1]
	s_mov_b32 m0, s73
	s_nop 0
	global_load_lds_dwordx4 v138, s[0:1]
	s_waitcnt vmcnt(8)
	s_waitcnt lgkmcnt(0)
	s_setprio 1
	s_barrier
	v_mfma_f32_16x16x32_bf16 v[118:121], v[152:155], v[184:187], v[118:121]
	v_mfma_f32_16x16x32_bf16 v[114:117], v[160:163], v[184:187], v[114:117]
	v_mfma_f32_16x16x32_bf16 v[102:105], v[152:155], v[192:195], v[102:105]
	v_mfma_f32_16x16x32_bf16 v[98:101], v[160:163], v[192:195], v[98:101]
	v_mfma_f32_16x16x32_bf16 v[86:89], v[152:155], v[200:203], v[86:89]
	v_mfma_f32_16x16x32_bf16 v[82:85], v[160:163], v[200:203], v[82:85]
	v_mfma_f32_16x16x32_bf16 v[74:77], v[152:155], v[208:211], v[74:77]
	v_mfma_f32_16x16x32_bf16 v[54:57], v[160:163], v[208:211], v[54:57]
	v_mfma_f32_16x16x32_bf16 v[118:121], v[156:159], v[188:191], v[118:121]
	v_mfma_f32_16x16x32_bf16 v[114:117], v[164:167], v[188:191], v[114:117]
	v_mfma_f32_16x16x32_bf16 v[102:105], v[156:159], v[196:199], v[102:105]
	v_mfma_f32_16x16x32_bf16 v[98:101], v[164:167], v[196:199], v[98:101]
	v_mfma_f32_16x16x32_bf16 v[86:89], v[156:159], v[204:207], v[86:89]
	v_mfma_f32_16x16x32_bf16 v[82:85], v[164:167], v[204:207], v[82:85]
	v_mfma_f32_16x16x32_bf16 v[74:77], v[156:159], v[212:215], v[74:77]
	v_mfma_f32_16x16x32_bf16 v[54:57], v[164:167], v[212:215], v[54:57]
	s_setprio 0
	s_setprio 1
	v_mfma_f32_16x16x32_bf16 v[126:129], v[168:171], v[184:187], v[126:129]
	v_mfma_f32_16x16x32_bf16 v[122:125], v[176:179], v[184:187], v[122:125]
	v_mfma_f32_16x16x32_bf16 v[110:113], v[168:171], v[192:195], v[110:113]
	v_mfma_f32_16x16x32_bf16 v[106:109], v[176:179], v[192:195], v[106:109]
	v_mfma_f32_16x16x32_bf16 v[94:97], v[168:171], v[200:203], v[94:97]
	v_mfma_f32_16x16x32_bf16 v[90:93], v[176:179], v[200:203], v[90:93]
	v_mfma_f32_16x16x32_bf16 v[70:73], v[168:171], v[208:211], v[70:73]
	v_mfma_f32_16x16x32_bf16 v[50:53], v[176:179], v[208:211], v[50:53]
	v_mfma_f32_16x16x32_bf16 v[126:129], v[172:175], v[188:191], v[126:129]
	v_mfma_f32_16x16x32_bf16 v[122:125], v[180:183], v[188:191], v[122:125]
	v_mfma_f32_16x16x32_bf16 v[110:113], v[172:175], v[196:199], v[110:113]
	v_mfma_f32_16x16x32_bf16 v[106:109], v[180:183], v[196:199], v[106:109]
	v_mfma_f32_16x16x32_bf16 v[94:97], v[172:175], v[204:207], v[94:97]
	v_mfma_f32_16x16x32_bf16 v[90:93], v[180:183], v[204:207], v[90:93]
	v_mfma_f32_16x16x32_bf16 v[70:73], v[172:175], v[212:215], v[70:73]
	v_mfma_f32_16x16x32_bf16 v[50:53], v[180:183], v[212:215], v[50:53]
	s_barrier
	s_setprio 0
	s_mov_b32 m0, s74
	s_mov_b64 s[98:99], s[52:53]
	s_add_u32 s78, s52, 0x100000
	ds_read_b128 v[184:187], v150 offset:16384
	ds_read_b128 v[188:191], v150 offset:17408
	ds_read_b128 v[192:195], v150 offset:18432
	ds_read_b128 v[196:199], v150 offset:19456
	ds_read_b128 v[200:203], v150 offset:20480
	ds_read_b128 v[204:207], v150 offset:21504
	ds_read_b128 v[208:211], v150 offset:22528
	ds_read_b128 v[212:215], v150 offset:23552
	global_load_lds_dwordx4 v130, s[52:53]
	s_mov_b32 m0, s75
	s_addc_u32 s79, s53, 0
	global_load_lds_dwordx4 v132, s[52:53]
	s_mov_b32 m0, s76
	s_mov_b64 s[100:101], s[54:55]
	global_load_lds_dwordx4 v130, s[78:79]
	s_mov_b32 m0, s46
	s_nop 0
	global_load_lds_dwordx4 v132, s[78:79]
	s_waitcnt vmcnt(6)
	s_waitcnt lgkmcnt(0)
	s_setprio 1
	s_barrier
	v_mfma_f32_16x16x32_bf16 v[66:69], v[152:155], v[184:187], v[66:69]
	v_mfma_f32_16x16x32_bf16 v[62:65], v[160:163], v[184:187], v[62:65]
	v_mfma_f32_16x16x32_bf16 v[42:45], v[152:155], v[192:195], v[42:45]
	v_mfma_f32_16x16x32_bf16 v[38:41], v[160:163], v[192:195], v[38:41]
	v_mfma_f32_16x16x32_bf16 v[26:29], v[152:155], v[200:203], v[26:29]
	v_mfma_f32_16x16x32_bf16 v[22:25], v[160:163], v[200:203], v[22:25]
	v_mfma_f32_16x16x32_bf16 v[6:9], v[152:155], v[208:211], v[6:9]
	v_mfma_f32_16x16x32_bf16 v[2:5], v[160:163], v[208:211], v[2:5]
	v_mfma_f32_16x16x32_bf16 v[66:69], v[156:159], v[188:191], v[66:69]
	v_mfma_f32_16x16x32_bf16 v[62:65], v[164:167], v[188:191], v[62:65]
	v_mfma_f32_16x16x32_bf16 v[42:45], v[156:159], v[196:199], v[42:45]
	v_mfma_f32_16x16x32_bf16 v[38:41], v[164:167], v[196:199], v[38:41]
	v_mfma_f32_16x16x32_bf16 v[26:29], v[156:159], v[204:207], v[26:29]
	v_mfma_f32_16x16x32_bf16 v[22:25], v[164:167], v[204:207], v[22:25]
	v_mfma_f32_16x16x32_bf16 v[6:9], v[156:159], v[212:215], v[6:9]
	v_mfma_f32_16x16x32_bf16 v[2:5], v[164:167], v[212:215], v[2:5]
	s_setprio 0
	s_setprio 1
	v_mfma_f32_16x16x32_bf16 v[78:81], v[168:171], v[184:187], v[78:81]
	v_mfma_f32_16x16x32_bf16 v[58:61], v[176:179], v[184:187], v[58:61]
	v_mfma_f32_16x16x32_bf16 v[46:49], v[168:171], v[192:195], v[46:49]
	v_mfma_f32_16x16x32_bf16 v[34:37], v[176:179], v[192:195], v[34:37]
	v_mfma_f32_16x16x32_bf16 v[30:33], v[168:171], v[200:203], v[30:33]
	v_mfma_f32_16x16x32_bf16 v[18:21], v[176:179], v[200:203], v[18:21]
	v_mfma_f32_16x16x32_bf16 v[14:17], v[168:171], v[208:211], v[14:17]
	v_mfma_f32_16x16x32_bf16 v[10:13], v[176:179], v[208:211], v[10:13]
	v_mfma_f32_16x16x32_bf16 v[78:81], v[172:175], v[188:191], v[78:81]
	v_mfma_f32_16x16x32_bf16 v[58:61], v[180:183], v[188:191], v[58:61]
	v_mfma_f32_16x16x32_bf16 v[46:49], v[172:175], v[196:199], v[46:49]
	v_mfma_f32_16x16x32_bf16 v[34:37], v[180:183], v[196:199], v[34:37]
	v_mfma_f32_16x16x32_bf16 v[30:33], v[172:175], v[204:207], v[30:33]
	v_mfma_f32_16x16x32_bf16 v[18:21], v[180:183], v[204:207], v[18:21]
	v_mfma_f32_16x16x32_bf16 v[14:17], v[172:175], v[212:215], v[14:17]
	v_mfma_f32_16x16x32_bf16 v[10:13], v[180:183], v[212:215], v[10:13]
	s_barrier
	s_setprio 0
	ds_read_b128 v[152:155], v134
	ds_read_b128 v[156:159], v134 offset:1024
	ds_read_b128 v[160:163], v134 offset:2048
	ds_read_b128 v[164:167], v134 offset:3072
	ds_read_b128 v[168:171], v144
	ds_read_b128 v[172:175], v144 offset:1024
	ds_read_b128 v[176:179], v144 offset:2048
	ds_read_b128 v[180:183], v144 offset:3072
	s_add_u32 s54, s54, 0x100000
	s_addc_u32 s55, s55, 0
	s_mov_b32 m0, s33
	s_nop 0
	global_load_lds_dwordx4 v130, s[100:101]
	s_mov_b32 m0, s51
	s_nop 0
	global_load_lds_dwordx4 v132, s[100:101]
	s_mov_b32 m0, s58
	ds_read_b128 v[184:187], v150 offset:32768
	ds_read_b128 v[188:191], v150 offset:33792
	ds_read_b128 v[192:195], v150 offset:34816
	ds_read_b128 v[196:199], v150 offset:35840
	ds_read_b128 v[200:203], v150 offset:36864
	ds_read_b128 v[204:207], v150 offset:37888
	ds_read_b128 v[208:211], v150 offset:38912
	ds_read_b128 v[212:215], v150 offset:39936
	global_load_lds_dwordx4 v130, s[54:55]
	s_mov_b32 m0, s59
	s_nop 0
	global_load_lds_dwordx4 v132, s[54:55]
	s_waitcnt vmcnt(8)
	s_waitcnt lgkmcnt(0)
	s_setprio 1
	s_barrier
	v_mfma_f32_16x16x32_bf16 v[118:121], v[152:155], v[184:187], v[118:121]
	v_mfma_f32_16x16x32_bf16 v[114:117], v[160:163], v[184:187], v[114:117]
	v_mfma_f32_16x16x32_bf16 v[102:105], v[152:155], v[192:195], v[102:105]
	v_mfma_f32_16x16x32_bf16 v[98:101], v[160:163], v[192:195], v[98:101]
	v_mfma_f32_16x16x32_bf16 v[86:89], v[152:155], v[200:203], v[86:89]
	v_mfma_f32_16x16x32_bf16 v[82:85], v[160:163], v[200:203], v[82:85]
	v_mfma_f32_16x16x32_bf16 v[74:77], v[152:155], v[208:211], v[74:77]
	v_mfma_f32_16x16x32_bf16 v[54:57], v[160:163], v[208:211], v[54:57]
	v_mfma_f32_16x16x32_bf16 v[118:121], v[156:159], v[188:191], v[118:121]
	v_mfma_f32_16x16x32_bf16 v[114:117], v[164:167], v[188:191], v[114:117]
	v_mfma_f32_16x16x32_bf16 v[102:105], v[156:159], v[196:199], v[102:105]
	v_mfma_f32_16x16x32_bf16 v[98:101], v[164:167], v[196:199], v[98:101]
	v_mfma_f32_16x16x32_bf16 v[86:89], v[156:159], v[204:207], v[86:89]
	v_mfma_f32_16x16x32_bf16 v[82:85], v[164:167], v[204:207], v[82:85]
	v_mfma_f32_16x16x32_bf16 v[74:77], v[156:159], v[212:215], v[74:77]
	v_mfma_f32_16x16x32_bf16 v[54:57], v[164:167], v[212:215], v[54:57]
	s_setprio 0
	s_setprio 1
	v_mfma_f32_16x16x32_bf16 v[126:129], v[168:171], v[184:187], v[126:129]
	v_mfma_f32_16x16x32_bf16 v[122:125], v[176:179], v[184:187], v[122:125]
	v_mfma_f32_16x16x32_bf16 v[110:113], v[168:171], v[192:195], v[110:113]
	v_mfma_f32_16x16x32_bf16 v[106:109], v[176:179], v[192:195], v[106:109]
	v_mfma_f32_16x16x32_bf16 v[94:97], v[168:171], v[200:203], v[94:97]
	v_mfma_f32_16x16x32_bf16 v[90:93], v[176:179], v[200:203], v[90:93]
	v_mfma_f32_16x16x32_bf16 v[70:73], v[168:171], v[208:211], v[70:73]
	v_mfma_f32_16x16x32_bf16 v[50:53], v[176:179], v[208:211], v[50:53]
	v_mfma_f32_16x16x32_bf16 v[126:129], v[172:175], v[188:191], v[126:129]
	v_mfma_f32_16x16x32_bf16 v[122:125], v[180:183], v[188:191], v[122:125]
	v_mfma_f32_16x16x32_bf16 v[110:113], v[172:175], v[196:199], v[110:113]
	v_mfma_f32_16x16x32_bf16 v[106:109], v[180:183], v[196:199], v[106:109]
	v_mfma_f32_16x16x32_bf16 v[94:97], v[172:175], v[204:207], v[94:97]
	v_mfma_f32_16x16x32_bf16 v[90:93], v[180:183], v[204:207], v[90:93]
	v_mfma_f32_16x16x32_bf16 v[70:73], v[172:175], v[212:215], v[70:73]
	v_mfma_f32_16x16x32_bf16 v[50:53], v[180:183], v[212:215], v[50:53]
	s_barrier
	s_setprio 0
	s_mov_b32 m0, s47
	s_add_u32 s98, s98, 0x80
	s_addc_u32 s99, s99, 0
	s_add_u32 s100, s100, 0x80
	s_addc_u32 s101, s101, 0
	s_add_u32 s52, s52, 0x100080
	ds_read_b128 v[184:187], v150 offset:49152
	ds_read_b128 v[188:191], v150 offset:50176
	ds_read_b128 v[192:195], v150 offset:51200
	ds_read_b128 v[196:199], v150 offset:52224
	ds_read_b128 v[200:203], v150 offset:53248
	ds_read_b128 v[204:207], v150 offset:54272
	ds_read_b128 v[208:211], v150 offset:55296
	ds_read_b128 v[212:215], v150 offset:56320
	global_load_lds_dwordx4 v130, s[98:99]
	s_mov_b32 m0, s77
	s_addc_u32 s53, s53, 0
	global_load_lds_dwordx4 v132, s[98:99]
	s_mov_b32 m0, s56
	s_nop 0
	global_load_lds_dwordx4 v130, s[52:53]
	s_mov_b32 m0, s57
	s_nop 0
	global_load_lds_dwordx4 v132, s[52:53]
	s_mov_b32 m0, s61
	s_nop 0
	global_load_lds_dwordx4 v130, s[100:101]
	s_mov_b32 m0, s62
	s_nop 0
	global_load_lds_dwordx4 v132, s[100:101]
	s_waitcnt vmcnt(8)
	s_waitcnt lgkmcnt(0)
	s_setprio 1
	s_barrier
	v_mfma_f32_16x16x32_bf16 v[66:69], v[152:155], v[184:187], v[66:69]
	v_mfma_f32_16x16x32_bf16 v[62:65], v[160:163], v[184:187], v[62:65]
	v_mfma_f32_16x16x32_bf16 v[42:45], v[152:155], v[192:195], v[42:45]
	v_mfma_f32_16x16x32_bf16 v[38:41], v[160:163], v[192:195], v[38:41]
	v_mfma_f32_16x16x32_bf16 v[26:29], v[152:155], v[200:203], v[26:29]
	v_mfma_f32_16x16x32_bf16 v[22:25], v[160:163], v[200:203], v[22:25]
	v_mfma_f32_16x16x32_bf16 v[6:9], v[152:155], v[208:211], v[6:9]
	v_mfma_f32_16x16x32_bf16 v[2:5], v[160:163], v[208:211], v[2:5]
	v_mfma_f32_16x16x32_bf16 v[66:69], v[156:159], v[188:191], v[66:69]
	v_mfma_f32_16x16x32_bf16 v[62:65], v[164:167], v[188:191], v[62:65]
	v_mfma_f32_16x16x32_bf16 v[42:45], v[156:159], v[196:199], v[42:45]
	v_mfma_f32_16x16x32_bf16 v[38:41], v[164:167], v[196:199], v[38:41]
	v_mfma_f32_16x16x32_bf16 v[26:29], v[156:159], v[204:207], v[26:29]
	v_mfma_f32_16x16x32_bf16 v[22:25], v[164:167], v[204:207], v[22:25]
	v_mfma_f32_16x16x32_bf16 v[6:9], v[156:159], v[212:215], v[6:9]
	v_mfma_f32_16x16x32_bf16 v[2:5], v[164:167], v[212:215], v[2:5]
	s_setprio 0
	s_setprio 1
	v_mfma_f32_16x16x32_bf16 v[78:81], v[168:171], v[184:187], v[78:81]
	v_mfma_f32_16x16x32_bf16 v[58:61], v[176:179], v[184:187], v[58:61]
	v_mfma_f32_16x16x32_bf16 v[46:49], v[168:171], v[192:195], v[46:49]
	v_mfma_f32_16x16x32_bf16 v[34:37], v[176:179], v[192:195], v[34:37]
	v_mfma_f32_16x16x32_bf16 v[30:33], v[168:171], v[200:203], v[30:33]
	v_mfma_f32_16x16x32_bf16 v[18:21], v[176:179], v[200:203], v[18:21]
	v_mfma_f32_16x16x32_bf16 v[14:17], v[168:171], v[208:211], v[14:17]
	v_mfma_f32_16x16x32_bf16 v[10:13], v[176:179], v[208:211], v[10:13]
	v_mfma_f32_16x16x32_bf16 v[78:81], v[172:175], v[188:191], v[78:81]
	v_mfma_f32_16x16x32_bf16 v[58:61], v[180:183], v[188:191], v[58:61]
	v_mfma_f32_16x16x32_bf16 v[46:49], v[172:175], v[196:199], v[46:49]
	v_mfma_f32_16x16x32_bf16 v[34:37], v[180:183], v[196:199], v[34:37]
	v_mfma_f32_16x16x32_bf16 v[30:33], v[172:175], v[204:207], v[30:33]
	v_mfma_f32_16x16x32_bf16 v[18:21], v[180:183], v[204:207], v[18:21]
	v_mfma_f32_16x16x32_bf16 v[14:17], v[172:175], v[212:215], v[14:17]
	v_mfma_f32_16x16x32_bf16 v[10:13], v[180:183], v[212:215], v[10:13]
	s_barrier
	s_setprio 0
	s_add_i32 s26, s26, 2
	s_add_u32 s0, s0, 0x100
	s_addc_u32 s1, s1, 0
	s_add_u32 s14, s14, 0x100
	s_addc_u32 s15, s15, 0
	s_cmp_gt_u32 s26, 29
	s_cbranch_scc0 .LBB0_1110
	s_and_b64 vcc, exec, s[18:19]
	s_cbranch_vccz .LBB0_1113
	s_barrier

.LBB0_1261:
	ds_read_b128 v[132:135], v182
	ds_read_b128 v[136:139], v182 offset:1024
	ds_read_b128 v[140:143], v182 offset:2048
	ds_read_b128 v[144:147], v182 offset:3072
	ds_read_b128 v[148:151], v183
	ds_read_b128 v[170:173], v183 offset:1024
	ds_read_b128 v[174:177], v183 offset:2048
	ds_read_b128 v[178:181], v183 offset:3072
	s_add_u32 s38, s40, 0xfffe0080
	s_addc_u32 s39, s41, -1
	s_cmp_eq_u32 s69, 4
	s_cselect_b32 s43, s23, s39
	s_cselect_b32 s42, s31, s38
	s_cselect_b32 s39, s0, s27
	s_cselect_b32 s38, s66, s26
	s_mov_b32 m0, s59
	ds_read_b128 v[186:189], v184
	ds_read_b128 v[190:193], v184 offset:1024
	ds_read_b128 v[194:197], v184 offset:2048
	ds_read_b128 v[198:201], v184 offset:3072
	ds_read_b128 v[202:205], v184 offset:4096
	ds_read_b128 v[206:209], v184 offset:5120
	ds_read_b128 v[210:213], v184 offset:6144
	ds_read_b128 v[214:217], v184 offset:7168
	global_load_lds_dwordx4 v162, s[40:41]
	s_mov_b32 m0, s60
	s_nop 0
	global_load_lds_dwordx4 v164, s[40:41]
	s_waitcnt vmcnt(8)
	s_waitcnt lgkmcnt(0)
	s_setprio 1
	s_barrier
	v_mfma_f32_16x16x32_bf16 v[122:125], v[132:135], v[186:189], v[122:125]
	v_mfma_f32_16x16x32_bf16 v[118:121], v[140:143], v[186:189], v[118:121]
	v_mfma_f32_16x16x32_bf16 v[110:113], v[132:135], v[194:197], v[110:113]
	v_mfma_f32_16x16x32_bf16 v[106:109], v[140:143], v[194:197], v[106:109]
	v_mfma_f32_16x16x32_bf16 v[94:97], v[132:135], v[202:205], v[94:97]
	v_mfma_f32_16x16x32_bf16 v[90:93], v[140:143], v[202:205], v[90:93]
	v_mfma_f32_16x16x32_bf16 v[78:81], v[132:135], v[210:213], v[78:81]
	v_mfma_f32_16x16x32_bf16 v[74:77], v[140:143], v[210:213], v[74:77]
	v_mfma_f32_16x16x32_bf16 v[122:125], v[136:139], v[190:193], v[122:125]
	v_mfma_f32_16x16x32_bf16 v[118:121], v[144:147], v[190:193], v[118:121]
	v_mfma_f32_16x16x32_bf16 v[110:113], v[136:139], v[198:201], v[110:113]
	v_mfma_f32_16x16x32_bf16 v[106:109], v[144:147], v[198:201], v[106:109]
	v_mfma_f32_16x16x32_bf16 v[94:97], v[136:139], v[206:209], v[94:97]
	v_mfma_f32_16x16x32_bf16 v[90:93], v[144:147], v[206:209], v[90:93]
	v_mfma_f32_16x16x32_bf16 v[78:81], v[136:139], v[214:217], v[78:81]
	v_mfma_f32_16x16x32_bf16 v[74:77], v[144:147], v[214:217], v[74:77]
	s_setprio 0
	s_setprio 1
	v_mfma_f32_16x16x32_bf16 v[126:129], v[148:151], v[186:189], v[126:129]
	v_mfma_f32_16x16x32_bf16 v[114:117], v[174:177], v[186:189], v[114:117]
	v_mfma_f32_16x16x32_bf16 v[102:105], v[148:151], v[194:197], v[102:105]
	v_mfma_f32_16x16x32_bf16 v[98:101], v[174:177], v[194:197], v[98:101]
	v_mfma_f32_16x16x32_bf16 v[86:89], v[148:151], v[202:205], v[86:89]
	v_mfma_f32_16x16x32_bf16 v[82:85], v[174:177], v[202:205], v[82:85]
	v_mfma_f32_16x16x32_bf16 v[70:73], v[148:151], v[210:213], v[70:73]
	v_mfma_f32_16x16x32_bf16 v[66:69], v[174:177], v[210:213], v[66:69]
	v_mfma_f32_16x16x32_bf16 v[126:129], v[170:173], v[190:193], v[126:129]
	v_mfma_f32_16x16x32_bf16 v[114:117], v[178:181], v[190:193], v[114:117]
	v_mfma_f32_16x16x32_bf16 v[102:105], v[170:173], v[198:201], v[102:105]
	v_mfma_f32_16x16x32_bf16 v[98:101], v[178:181], v[198:201], v[98:101]
	v_mfma_f32_16x16x32_bf16 v[86:89], v[170:173], v[206:209], v[86:89]
	v_mfma_f32_16x16x32_bf16 v[82:85], v[178:181], v[206:209], v[82:85]
	v_mfma_f32_16x16x32_bf16 v[70:73], v[170:173], v[214:217], v[70:73]
	v_mfma_f32_16x16x32_bf16 v[66:69], v[178:181], v[214:217], v[66:69]
	s_barrier
	s_setprio 0
	s_mov_b32 m0, s61
	s_mov_b64 s[98:99], s[38:39]
	s_add_u32 s70, s38, 0x20000
	ds_read_b128 v[186:189], v184 offset:16384
	ds_read_b128 v[190:193], v184 offset:17408
	ds_read_b128 v[194:197], v184 offset:18432
	ds_read_b128 v[198:201], v184 offset:19456
	ds_read_b128 v[202:205], v184 offset:20480
	ds_read_b128 v[206:209], v184 offset:21504
	ds_read_b128 v[210:213], v184 offset:22528
	ds_read_b128 v[214:217], v184 offset:23552
	global_load_lds_dwordx4 v156, s[38:39]
	s_mov_b32 m0, s62
	s_addc_u32 s71, s39, 0
	global_load_lds_dwordx4 v160, s[38:39]
	s_mov_b32 m0, s67
	s_mov_b64 s[100:101], s[42:43]
	global_load_lds_dwordx4 v156, s[70:71]
	s_mov_b32 m0, s46
	s_nop 0
	global_load_lds_dwordx4 v160, s[70:71]
	s_waitcnt vmcnt(6)
	s_waitcnt lgkmcnt(0)
	s_setprio 1
	s_barrier
	v_mfma_f32_16x16x32_bf16 v[58:61], v[132:135], v[186:189], v[58:61]
	v_mfma_f32_16x16x32_bf16 v[54:57], v[140:143], v[186:189], v[54:57]
	v_mfma_f32_16x16x32_bf16 v[46:49], v[132:135], v[194:197], v[46:49]
	v_mfma_f32_16x16x32_bf16 v[42:45], v[140:143], v[194:197], v[42:45]
	v_mfma_f32_16x16x32_bf16 v[30:33], v[132:135], v[202:205], v[30:33]
	v_mfma_f32_16x16x32_bf16 v[26:29], v[140:143], v[202:205], v[26:29]
	v_mfma_f32_16x16x32_bf16 v[14:17], v[132:135], v[210:213], v[14:17]
	v_mfma_f32_16x16x32_bf16 v[10:13], v[140:143], v[210:213], v[10:13]
	v_mfma_f32_16x16x32_bf16 v[58:61], v[136:139], v[190:193], v[58:61]
	v_mfma_f32_16x16x32_bf16 v[54:57], v[144:147], v[190:193], v[54:57]
	v_mfma_f32_16x16x32_bf16 v[46:49], v[136:139], v[198:201], v[46:49]
	v_mfma_f32_16x16x32_bf16 v[42:45], v[144:147], v[198:201], v[42:45]
	v_mfma_f32_16x16x32_bf16 v[30:33], v[136:139], v[206:209], v[30:33]
	v_mfma_f32_16x16x32_bf16 v[26:29], v[144:147], v[206:209], v[26:29]
	v_mfma_f32_16x16x32_bf16 v[14:17], v[136:139], v[214:217], v[14:17]
	v_mfma_f32_16x16x32_bf16 v[10:13], v[144:147], v[214:217], v[10:13]
	s_setprio 0
	s_setprio 1
	v_mfma_f32_16x16x32_bf16 v[62:65], v[148:151], v[186:189], v[62:65]
	v_mfma_f32_16x16x32_bf16 v[50:53], v[174:177], v[186:189], v[50:53]
	v_mfma_f32_16x16x32_bf16 v[38:41], v[148:151], v[194:197], v[38:41]
	v_mfma_f32_16x16x32_bf16 v[34:37], v[174:177], v[194:197], v[34:37]
	v_mfma_f32_16x16x32_bf16 v[22:25], v[148:151], v[202:205], v[22:25]
	v_mfma_f32_16x16x32_bf16 v[18:21], v[174:177], v[202:205], v[18:21]
	v_mfma_f32_16x16x32_bf16 v[6:9], v[148:151], v[210:213], v[6:9]
	v_mfma_f32_16x16x32_bf16 v[2:5], v[174:177], v[210:213], v[2:5]
	v_mfma_f32_16x16x32_bf16 v[62:65], v[170:173], v[190:193], v[62:65]
	v_mfma_f32_16x16x32_bf16 v[50:53], v[178:181], v[190:193], v[50:53]
	v_mfma_f32_16x16x32_bf16 v[38:41], v[170:173], v[198:201], v[38:41]
	v_mfma_f32_16x16x32_bf16 v[34:37], v[178:181], v[198:201], v[34:37]
	v_mfma_f32_16x16x32_bf16 v[22:25], v[170:173], v[206:209], v[22:25]
	v_mfma_f32_16x16x32_bf16 v[18:21], v[178:181], v[206:209], v[18:21]
	v_mfma_f32_16x16x32_bf16 v[6:9], v[170:173], v[214:217], v[6:9]
	v_mfma_f32_16x16x32_bf16 v[2:5], v[178:181], v[214:217], v[2:5]
	s_barrier
	s_setprio 0
	ds_read_b128 v[132:135], v130
	ds_read_b128 v[136:139], v130 offset:1024
	ds_read_b128 v[140:143], v130 offset:2048
	ds_read_b128 v[144:147], v130 offset:3072
	ds_read_b128 v[148:151], v131
	ds_read_b128 v[170:173], v131 offset:1024
	ds_read_b128 v[174:177], v131 offset:2048
	ds_read_b128 v[178:181], v131 offset:3072
	s_add_u32 s42, s42, 0x20000
	s_addc_u32 s43, s43, 0
	s_mov_b32 m0, s48
	s_nop 0
	global_load_lds_dwordx4 v154, s[100:101]
	s_mov_b32 m0, s49
	s_nop 0
	global_load_lds_dwordx4 v158, s[100:101]
	s_mov_b32 m0, s50
	ds_read_b128 v[186:189], v184 offset:32768
	ds_read_b128 v[190:193], v184 offset:33792
	ds_read_b128 v[194:197], v184 offset:34816
	ds_read_b128 v[198:201], v184 offset:35840
	ds_read_b128 v[202:205], v184 offset:36864
	ds_read_b128 v[206:209], v184 offset:37888
	ds_read_b128 v[210:213], v184 offset:38912
	ds_read_b128 v[214:217], v184 offset:39936
	global_load_lds_dwordx4 v154, s[42:43]
	s_mov_b32 m0, s51
	s_nop 0
	global_load_lds_dwordx4 v158, s[42:43]
	s_waitcnt vmcnt(8)
	s_waitcnt lgkmcnt(0)
	s_setprio 1
	s_barrier
	v_mfma_f32_16x16x32_bf16 v[122:125], v[132:135], v[186:189], v[122:125]
	v_mfma_f32_16x16x32_bf16 v[118:121], v[140:143], v[186:189], v[118:121]
	v_mfma_f32_16x16x32_bf16 v[110:113], v[132:135], v[194:197], v[110:113]
	v_mfma_f32_16x16x32_bf16 v[106:109], v[140:143], v[194:197], v[106:109]
	v_mfma_f32_16x16x32_bf16 v[94:97], v[132:135], v[202:205], v[94:97]
	v_mfma_f32_16x16x32_bf16 v[90:93], v[140:143], v[202:205], v[90:93]
	v_mfma_f32_16x16x32_bf16 v[78:81], v[132:135], v[210:213], v[78:81]
	v_mfma_f32_16x16x32_bf16 v[74:77], v[140:143], v[210:213], v[74:77]
	v_mfma_f32_16x16x32_bf16 v[122:125], v[136:139], v[190:193], v[122:125]
	v_mfma_f32_16x16x32_bf16 v[118:121], v[144:147], v[190:193], v[118:121]
	v_mfma_f32_16x16x32_bf16 v[110:113], v[136:139], v[198:201], v[110:113]
	v_mfma_f32_16x16x32_bf16 v[106:109], v[144:147], v[198:201], v[106:109]
	v_mfma_f32_16x16x32_bf16 v[94:97], v[136:139], v[206:209], v[94:97]
	v_mfma_f32_16x16x32_bf16 v[90:93], v[144:147], v[206:209], v[90:93]
	v_mfma_f32_16x16x32_bf16 v[78:81], v[136:139], v[214:217], v[78:81]
	v_mfma_f32_16x16x32_bf16 v[74:77], v[144:147], v[214:217], v[74:77]
	s_setprio 0
	s_setprio 1
	v_mfma_f32_16x16x32_bf16 v[126:129], v[148:151], v[186:189], v[126:129]
	v_mfma_f32_16x16x32_bf16 v[114:117], v[174:177], v[186:189], v[114:117]
	v_mfma_f32_16x16x32_bf16 v[102:105], v[148:151], v[194:197], v[102:105]
	v_mfma_f32_16x16x32_bf16 v[98:101], v[174:177], v[194:197], v[98:101]
	v_mfma_f32_16x16x32_bf16 v[86:89], v[148:151], v[202:205], v[86:89]
	v_mfma_f32_16x16x32_bf16 v[82:85], v[174:177], v[202:205], v[82:85]
	v_mfma_f32_16x16x32_bf16 v[70:73], v[148:151], v[210:213], v[70:73]
	v_mfma_f32_16x16x32_bf16 v[66:69], v[174:177], v[210:213], v[66:69]
	v_mfma_f32_16x16x32_bf16 v[126:129], v[170:173], v[190:193], v[126:129]
	v_mfma_f32_16x16x32_bf16 v[114:117], v[178:181], v[190:193], v[114:117]
	v_mfma_f32_16x16x32_bf16 v[102:105], v[170:173], v[198:201], v[102:105]
	v_mfma_f32_16x16x32_bf16 v[98:101], v[178:181], v[198:201], v[98:101]
	v_mfma_f32_16x16x32_bf16 v[86:89], v[170:173], v[206:209], v[86:89]
	v_mfma_f32_16x16x32_bf16 v[82:85], v[178:181], v[206:209], v[82:85]
	v_mfma_f32_16x16x32_bf16 v[70:73], v[170:173], v[214:217], v[70:73]
	v_mfma_f32_16x16x32_bf16 v[66:69], v[178:181], v[214:217], v[66:69]
	s_barrier
	s_setprio 0
	s_mov_b32 m0, s47
	s_add_u32 s98, s98, 0x80
	s_addc_u32 s99, s99, 0
	s_add_u32 s100, s100, 0x80
	s_addc_u32 s101, s101, 0
	s_add_u32 s38, s38, 0x20080
	ds_read_b128 v[186:189], v184 offset:49152
	ds_read_b128 v[190:193], v184 offset:50176
	ds_read_b128 v[194:197], v184 offset:51200
	ds_read_b128 v[198:201], v184 offset:52224
	ds_read_b128 v[202:205], v184 offset:53248
	ds_read_b128 v[206:209], v184 offset:54272
	ds_read_b128 v[210:213], v184 offset:55296
	ds_read_b128 v[214:217], v184 offset:56320
	global_load_lds_dwordx4 v156, s[98:99]
	s_mov_b32 m0, s68
	s_addc_u32 s39, s39, 0
	global_load_lds_dwordx4 v160, s[98:99]
	s_mov_b32 m0, s56
	s_nop 0
	global_load_lds_dwordx4 v156, s[38:39]
	s_mov_b32 m0, s57
	s_nop 0
	global_load_lds_dwordx4 v160, s[38:39]
	s_mov_b32 m0, s52
	s_nop 0
	global_load_lds_dwordx4 v154, s[100:101]
	s_mov_b32 m0, s53
	s_nop 0
	global_load_lds_dwordx4 v158, s[100:101]
	s_waitcnt vmcnt(8)
	s_waitcnt lgkmcnt(0)
	s_setprio 1
	s_barrier
	v_mfma_f32_16x16x32_bf16 v[58:61], v[132:135], v[186:189], v[58:61]
	v_mfma_f32_16x16x32_bf16 v[54:57], v[140:143], v[186:189], v[54:57]
	v_mfma_f32_16x16x32_bf16 v[46:49], v[132:135], v[194:197], v[46:49]
	v_mfma_f32_16x16x32_bf16 v[42:45], v[140:143], v[194:197], v[42:45]
	v_mfma_f32_16x16x32_bf16 v[30:33], v[132:135], v[202:205], v[30:33]
	v_mfma_f32_16x16x32_bf16 v[26:29], v[140:143], v[202:205], v[26:29]
	v_mfma_f32_16x16x32_bf16 v[14:17], v[132:135], v[210:213], v[14:17]
	v_mfma_f32_16x16x32_bf16 v[10:13], v[140:143], v[210:213], v[10:13]
	v_mfma_f32_16x16x32_bf16 v[58:61], v[136:139], v[190:193], v[58:61]
	v_mfma_f32_16x16x32_bf16 v[54:57], v[144:147], v[190:193], v[54:57]
	v_mfma_f32_16x16x32_bf16 v[46:49], v[136:139], v[198:201], v[46:49]
	v_mfma_f32_16x16x32_bf16 v[42:45], v[144:147], v[198:201], v[42:45]
	v_mfma_f32_16x16x32_bf16 v[30:33], v[136:139], v[206:209], v[30:33]
	v_mfma_f32_16x16x32_bf16 v[26:29], v[144:147], v[206:209], v[26:29]
	v_mfma_f32_16x16x32_bf16 v[14:17], v[136:139], v[214:217], v[14:17]
	v_mfma_f32_16x16x32_bf16 v[10:13], v[144:147], v[214:217], v[10:13]
	s_setprio 0
	s_setprio 1
	v_mfma_f32_16x16x32_bf16 v[62:65], v[148:151], v[186:189], v[62:65]
	v_mfma_f32_16x16x32_bf16 v[50:53], v[174:177], v[186:189], v[50:53]
	v_mfma_f32_16x16x32_bf16 v[38:41], v[148:151], v[194:197], v[38:41]
	v_mfma_f32_16x16x32_bf16 v[34:37], v[174:177], v[194:197], v[34:37]
	v_mfma_f32_16x16x32_bf16 v[22:25], v[148:151], v[202:205], v[22:25]
	v_mfma_f32_16x16x32_bf16 v[18:21], v[174:177], v[202:205], v[18:21]
	v_mfma_f32_16x16x32_bf16 v[6:9], v[148:151], v[210:213], v[6:9]
	v_mfma_f32_16x16x32_bf16 v[2:5], v[174:177], v[210:213], v[2:5]
	v_mfma_f32_16x16x32_bf16 v[62:65], v[170:173], v[190:193], v[62:65]
	v_mfma_f32_16x16x32_bf16 v[50:53], v[178:181], v[190:193], v[50:53]
	v_mfma_f32_16x16x32_bf16 v[38:41], v[170:173], v[198:201], v[38:41]
	v_mfma_f32_16x16x32_bf16 v[34:37], v[178:181], v[198:201], v[34:37]
	v_mfma_f32_16x16x32_bf16 v[22:25], v[170:173], v[206:209], v[22:25]
	v_mfma_f32_16x16x32_bf16 v[18:21], v[178:181], v[206:209], v[18:21]
	v_mfma_f32_16x16x32_bf16 v[6:9], v[170:173], v[214:217], v[6:9]
	v_mfma_f32_16x16x32_bf16 v[2:5], v[178:181], v[214:217], v[2:5]
	s_barrier
	s_setprio 0
	s_add_i32 s69, s69, 2
	s_add_u32 s40, s40, 0x100
	s_addc_u32 s41, s41, 0
	s_add_u32 s26, s26, 0x100
	s_addc_u32 s27, s27, 0
	s_cmp_gt_u32 s69, 5
	s_cbranch_scc0 .LBB0_1261
	s_and_b64 vcc, exec, s[16:17]
	s_cbranch_vccz .LBB0_1264
	s_barrier

.LBB0_1345:
	ds_read_b128 v[156:159], v150
	ds_read_b128 v[160:163], v150 offset:1024
	ds_read_b128 v[164:167], v150 offset:2048
	ds_read_b128 v[168:171], v150 offset:3072
	ds_read_b128 v[172:175], v151
	ds_read_b128 v[176:179], v151 offset:1024
	ds_read_b128 v[180:183], v151 offset:2048
	ds_read_b128 v[184:187], v151 offset:3072
	s_add_u32 s38, s40, 0xfff00080
	s_addc_u32 s39, s41, -1
	s_cmp_eq_u32 s68, 60
	s_cselect_b32 s43, s1, s39
	s_cselect_b32 s42, s25, s38
	s_cselect_b32 s39, s8, s27
	s_cselect_b32 s38, s67, s26
	s_mov_b32 m0, s53
	ds_read_b128 v[188:191], v152
	ds_read_b128 v[192:195], v152 offset:1024
	ds_read_b128 v[196:199], v152 offset:2048
	ds_read_b128 v[200:203], v152 offset:3072
	ds_read_b128 v[204:207], v152 offset:4096
	ds_read_b128 v[208:211], v152 offset:5120
	ds_read_b128 v[212:215], v152 offset:6144
	ds_read_b128 v[216:219], v152 offset:7168
	global_load_lds_dwordx4 v0, s[40:41]
	s_mov_b32 m0, s54
	s_nop 0
	global_load_lds_dwordx4 v140, s[40:41]
	s_waitcnt vmcnt(8)
	s_waitcnt lgkmcnt(0)
	s_setprio 1
	s_barrier
	v_mfma_f32_16x16x32_bf16 v[118:121], v[156:159], v[188:191], v[118:121]
	v_mfma_f32_16x16x32_bf16 v[114:117], v[164:167], v[188:191], v[114:117]
	v_mfma_f32_16x16x32_bf16 v[102:105], v[156:159], v[196:199], v[102:105]
	v_mfma_f32_16x16x32_bf16 v[98:101], v[164:167], v[196:199], v[98:101]
	v_mfma_f32_16x16x32_bf16 v[86:89], v[156:159], v[204:207], v[86:89]
	v_mfma_f32_16x16x32_bf16 v[82:85], v[164:167], v[204:207], v[82:85]
	v_mfma_f32_16x16x32_bf16 v[66:69], v[156:159], v[212:215], v[66:69]
	v_mfma_f32_16x16x32_bf16 v[62:65], v[164:167], v[212:215], v[62:65]
	v_mfma_f32_16x16x32_bf16 v[118:121], v[160:163], v[192:195], v[118:121]
	v_mfma_f32_16x16x32_bf16 v[114:117], v[168:171], v[192:195], v[114:117]
	v_mfma_f32_16x16x32_bf16 v[102:105], v[160:163], v[200:203], v[102:105]
	v_mfma_f32_16x16x32_bf16 v[98:101], v[168:171], v[200:203], v[98:101]
	v_mfma_f32_16x16x32_bf16 v[86:89], v[160:163], v[208:211], v[86:89]
	v_mfma_f32_16x16x32_bf16 v[82:85], v[168:171], v[208:211], v[82:85]
	v_mfma_f32_16x16x32_bf16 v[66:69], v[160:163], v[216:219], v[66:69]
	v_mfma_f32_16x16x32_bf16 v[62:65], v[168:171], v[216:219], v[62:65]
	s_setprio 0
	s_setprio 1
	v_mfma_f32_16x16x32_bf16 v[126:129], v[172:175], v[188:191], v[126:129]
	v_mfma_f32_16x16x32_bf16 v[122:125], v[180:183], v[188:191], v[122:125]
	v_mfma_f32_16x16x32_bf16 v[110:113], v[172:175], v[196:199], v[110:113]
	v_mfma_f32_16x16x32_bf16 v[106:109], v[180:183], v[196:199], v[106:109]
	v_mfma_f32_16x16x32_bf16 v[94:97], v[172:175], v[204:207], v[94:97]
	v_mfma_f32_16x16x32_bf16 v[90:93], v[180:183], v[204:207], v[90:93]
	v_mfma_f32_16x16x32_bf16 v[78:81], v[172:175], v[212:215], v[78:81]
	v_mfma_f32_16x16x32_bf16 v[74:77], v[180:183], v[212:215], v[74:77]
	v_mfma_f32_16x16x32_bf16 v[126:129], v[176:179], v[192:195], v[126:129]
	v_mfma_f32_16x16x32_bf16 v[122:125], v[184:187], v[192:195], v[122:125]
	v_mfma_f32_16x16x32_bf16 v[110:113], v[176:179], v[200:203], v[110:113]
	v_mfma_f32_16x16x32_bf16 v[106:109], v[184:187], v[200:203], v[106:109]
	v_mfma_f32_16x16x32_bf16 v[94:97], v[176:179], v[208:211], v[94:97]
	v_mfma_f32_16x16x32_bf16 v[90:93], v[184:187], v[208:211], v[90:93]
	v_mfma_f32_16x16x32_bf16 v[78:81], v[176:179], v[216:219], v[78:81]
	v_mfma_f32_16x16x32_bf16 v[74:77], v[184:187], v[216:219], v[74:77]
	s_barrier
	s_setprio 0
	s_mov_b32 m0, s59
	s_mov_b64 s[98:99], s[38:39]
	s_add_u32 s70, s38, 0x100000
	ds_read_b128 v[188:191], v152 offset:16384
	ds_read_b128 v[192:195], v152 offset:17408
	ds_read_b128 v[196:199], v152 offset:18432
	ds_read_b128 v[200:203], v152 offset:19456
	ds_read_b128 v[204:207], v152 offset:20480
	ds_read_b128 v[208:211], v152 offset:21504
	ds_read_b128 v[212:215], v152 offset:22528
	ds_read_b128 v[216:219], v152 offset:23552
	global_load_lds_dwordx4 v134, s[38:39]
	s_mov_b32 m0, s60
	s_addc_u32 s71, s39, 0
	global_load_lds_dwordx4 v130, s[38:39]
	s_mov_b32 m0, s61
	s_mov_b64 s[100:101], s[42:43]
	global_load_lds_dwordx4 v134, s[70:71]
	s_mov_b32 m0, s62
	s_nop 0
	global_load_lds_dwordx4 v130, s[70:71]
	s_waitcnt vmcnt(6)
	s_waitcnt lgkmcnt(0)
	s_setprio 1
	s_barrier
	v_mfma_f32_16x16x32_bf16 v[54:57], v[156:159], v[188:191], v[54:57]
	v_mfma_f32_16x16x32_bf16 v[50:53], v[164:167], v[188:191], v[50:53]
	v_mfma_f32_16x16x32_bf16 v[38:41], v[156:159], v[196:199], v[38:41]
	v_mfma_f32_16x16x32_bf16 v[34:37], v[164:167], v[196:199], v[34:37]
	v_mfma_f32_16x16x32_bf16 v[22:25], v[156:159], v[204:207], v[22:25]
	v_mfma_f32_16x16x32_bf16 v[18:21], v[164:167], v[204:207], v[18:21]
	v_mfma_f32_16x16x32_bf16 v[6:9], v[156:159], v[212:215], v[6:9]
	v_mfma_f32_16x16x32_bf16 v[2:5], v[164:167], v[212:215], v[2:5]
	v_mfma_f32_16x16x32_bf16 v[54:57], v[160:163], v[192:195], v[54:57]
	v_mfma_f32_16x16x32_bf16 v[50:53], v[168:171], v[192:195], v[50:53]
	v_mfma_f32_16x16x32_bf16 v[38:41], v[160:163], v[200:203], v[38:41]
	v_mfma_f32_16x16x32_bf16 v[34:37], v[168:171], v[200:203], v[34:37]
	v_mfma_f32_16x16x32_bf16 v[22:25], v[160:163], v[208:211], v[22:25]
	v_mfma_f32_16x16x32_bf16 v[18:21], v[168:171], v[208:211], v[18:21]
	v_mfma_f32_16x16x32_bf16 v[6:9], v[160:163], v[216:219], v[6:9]
	v_mfma_f32_16x16x32_bf16 v[2:5], v[168:171], v[216:219], v[2:5]
	s_setprio 0
	s_setprio 1
	v_mfma_f32_16x16x32_bf16 v[70:73], v[172:175], v[188:191], v[70:73]
	v_mfma_f32_16x16x32_bf16 v[58:61], v[180:183], v[188:191], v[58:61]
	v_mfma_f32_16x16x32_bf16 v[46:49], v[172:175], v[196:199], v[46:49]
	v_mfma_f32_16x16x32_bf16 v[42:45], v[180:183], v[196:199], v[42:45]
	v_mfma_f32_16x16x32_bf16 v[30:33], v[172:175], v[204:207], v[30:33]
	v_mfma_f32_16x16x32_bf16 v[26:29], v[180:183], v[204:207], v[26:29]
	v_mfma_f32_16x16x32_bf16 v[14:17], v[172:175], v[212:215], v[14:17]
	v_mfma_f32_16x16x32_bf16 v[10:13], v[180:183], v[212:215], v[10:13]
	v_mfma_f32_16x16x32_bf16 v[70:73], v[176:179], v[192:195], v[70:73]
	v_mfma_f32_16x16x32_bf16 v[58:61], v[184:187], v[192:195], v[58:61]
	v_mfma_f32_16x16x32_bf16 v[46:49], v[176:179], v[200:203], v[46:49]
	v_mfma_f32_16x16x32_bf16 v[42:45], v[184:187], v[200:203], v[42:45]
	v_mfma_f32_16x16x32_bf16 v[30:33], v[176:179], v[208:211], v[30:33]
	v_mfma_f32_16x16x32_bf16 v[26:29], v[184:187], v[208:211], v[26:29]
	v_mfma_f32_16x16x32_bf16 v[14:17], v[176:179], v[216:219], v[14:17]
	v_mfma_f32_16x16x32_bf16 v[10:13], v[184:187], v[216:219], v[10:13]
	s_barrier
	s_setprio 0
	ds_read_b128 v[156:159], v154
	ds_read_b128 v[160:163], v154 offset:1024
	ds_read_b128 v[164:167], v154 offset:2048
	ds_read_b128 v[168:171], v154 offset:3072
	ds_read_b128 v[172:175], v146
	ds_read_b128 v[176:179], v146 offset:1024
	ds_read_b128 v[180:183], v146 offset:2048
	ds_read_b128 v[184:187], v146 offset:3072
	s_add_u32 s42, s42, 0x100000
	s_addc_u32 s43, s43, 0
	s_mov_b32 m0, s13
	s_nop 0
	global_load_lds_dwordx4 v136, s[100:101]
	s_mov_b32 m0, s33
	s_nop 0
	global_load_lds_dwordx4 v132, s[100:101]
	s_mov_b32 m0, s48
	ds_read_b128 v[188:191], v152 offset:32768
	ds_read_b128 v[192:195], v152 offset:33792
	ds_read_b128 v[196:199], v152 offset:34816
	ds_read_b128 v[200:203], v152 offset:35840
	ds_read_b128 v[204:207], v152 offset:36864
	ds_read_b128 v[208:211], v152 offset:37888
	ds_read_b128 v[212:215], v152 offset:38912
	ds_read_b128 v[216:219], v152 offset:39936
	global_load_lds_dwordx4 v136, s[42:43]
	s_mov_b32 m0, s49
	s_nop 0
	global_load_lds_dwordx4 v132, s[42:43]
	s_waitcnt vmcnt(8)
	s_waitcnt lgkmcnt(0)
	s_setprio 1
	s_barrier
	v_mfma_f32_16x16x32_bf16 v[118:121], v[156:159], v[188:191], v[118:121]
	v_mfma_f32_16x16x32_bf16 v[114:117], v[164:167], v[188:191], v[114:117]
	v_mfma_f32_16x16x32_bf16 v[102:105], v[156:159], v[196:199], v[102:105]
	v_mfma_f32_16x16x32_bf16 v[98:101], v[164:167], v[196:199], v[98:101]
	v_mfma_f32_16x16x32_bf16 v[86:89], v[156:159], v[204:207], v[86:89]
	v_mfma_f32_16x16x32_bf16 v[82:85], v[164:167], v[204:207], v[82:85]
	v_mfma_f32_16x16x32_bf16 v[66:69], v[156:159], v[212:215], v[66:69]
	v_mfma_f32_16x16x32_bf16 v[62:65], v[164:167], v[212:215], v[62:65]
	v_mfma_f32_16x16x32_bf16 v[118:121], v[160:163], v[192:195], v[118:121]
	v_mfma_f32_16x16x32_bf16 v[114:117], v[168:171], v[192:195], v[114:117]
	v_mfma_f32_16x16x32_bf16 v[102:105], v[160:163], v[200:203], v[102:105]
	v_mfma_f32_16x16x32_bf16 v[98:101], v[168:171], v[200:203], v[98:101]
	v_mfma_f32_16x16x32_bf16 v[86:89], v[160:163], v[208:211], v[86:89]
	v_mfma_f32_16x16x32_bf16 v[82:85], v[168:171], v[208:211], v[82:85]
	v_mfma_f32_16x16x32_bf16 v[66:69], v[160:163], v[216:219], v[66:69]
	v_mfma_f32_16x16x32_bf16 v[62:65], v[168:171], v[216:219], v[62:65]
	s_setprio 0
	s_setprio 1
	v_mfma_f32_16x16x32_bf16 v[126:129], v[172:175], v[188:191], v[126:129]
	v_mfma_f32_16x16x32_bf16 v[122:125], v[180:183], v[188:191], v[122:125]
	v_mfma_f32_16x16x32_bf16 v[110:113], v[172:175], v[196:199], v[110:113]
	v_mfma_f32_16x16x32_bf16 v[106:109], v[180:183], v[196:199], v[106:109]
	v_mfma_f32_16x16x32_bf16 v[94:97], v[172:175], v[204:207], v[94:97]
	v_mfma_f32_16x16x32_bf16 v[90:93], v[180:183], v[204:207], v[90:93]
	v_mfma_f32_16x16x32_bf16 v[78:81], v[172:175], v[212:215], v[78:81]
	v_mfma_f32_16x16x32_bf16 v[74:77], v[180:183], v[212:215], v[74:77]
	v_mfma_f32_16x16x32_bf16 v[126:129], v[176:179], v[192:195], v[126:129]
	v_mfma_f32_16x16x32_bf16 v[122:125], v[184:187], v[192:195], v[122:125]
	v_mfma_f32_16x16x32_bf16 v[110:113], v[176:179], v[200:203], v[110:113]
	v_mfma_f32_16x16x32_bf16 v[106:109], v[184:187], v[200:203], v[106:109]
	v_mfma_f32_16x16x32_bf16 v[94:97], v[176:179], v[208:211], v[94:97]
	v_mfma_f32_16x16x32_bf16 v[90:93], v[184:187], v[208:211], v[90:93]
	v_mfma_f32_16x16x32_bf16 v[78:81], v[176:179], v[216:219], v[78:81]
	v_mfma_f32_16x16x32_bf16 v[74:77], v[184:187], v[216:219], v[74:77]
	s_barrier
	s_setprio 0
	s_mov_b32 m0, s46
	s_add_u32 s98, s98, 0x80
	s_addc_u32 s99, s99, 0
	s_add_u32 s100, s100, 0x80
	s_addc_u32 s101, s101, 0
	s_add_u32 s38, s38, 0x100080
	ds_read_b128 v[188:191], v152 offset:49152
	ds_read_b128 v[192:195], v152 offset:50176
	ds_read_b128 v[196:199], v152 offset:51200
	ds_read_b128 v[200:203], v152 offset:52224
	ds_read_b128 v[204:207], v152 offset:53248
	ds_read_b128 v[208:211], v152 offset:54272
	ds_read_b128 v[212:215], v152 offset:55296
	ds_read_b128 v[216:219], v152 offset:56320
	global_load_lds_dwordx4 v134, s[98:99]
	s_mov_b32 m0, s47
	s_addc_u32 s39, s39, 0
	global_load_lds_dwordx4 v130, s[98:99]
	s_mov_b32 m0, s56
	s_nop 0
	global_load_lds_dwordx4 v134, s[38:39]
	s_mov_b32 m0, s57
	s_nop 0
	global_load_lds_dwordx4 v130, s[38:39]
	s_mov_b32 m0, s50
	s_nop 0
	global_load_lds_dwordx4 v136, s[100:101]
	s_mov_b32 m0, s51
	s_nop 0
	global_load_lds_dwordx4 v132, s[100:101]
	s_waitcnt vmcnt(8)
	s_waitcnt lgkmcnt(0)
	s_setprio 1
	s_barrier
	v_mfma_f32_16x16x32_bf16 v[54:57], v[156:159], v[188:191], v[54:57]
	v_mfma_f32_16x16x32_bf16 v[50:53], v[164:167], v[188:191], v[50:53]
	v_mfma_f32_16x16x32_bf16 v[38:41], v[156:159], v[196:199], v[38:41]
	v_mfma_f32_16x16x32_bf16 v[34:37], v[164:167], v[196:199], v[34:37]
	v_mfma_f32_16x16x32_bf16 v[22:25], v[156:159], v[204:207], v[22:25]
	v_mfma_f32_16x16x32_bf16 v[18:21], v[164:167], v[204:207], v[18:21]
	v_mfma_f32_16x16x32_bf16 v[6:9], v[156:159], v[212:215], v[6:9]
	v_mfma_f32_16x16x32_bf16 v[2:5], v[164:167], v[212:215], v[2:5]
	v_mfma_f32_16x16x32_bf16 v[54:57], v[160:163], v[192:195], v[54:57]
	v_mfma_f32_16x16x32_bf16 v[50:53], v[168:171], v[192:195], v[50:53]
	v_mfma_f32_16x16x32_bf16 v[38:41], v[160:163], v[200:203], v[38:41]
	v_mfma_f32_16x16x32_bf16 v[34:37], v[168:171], v[200:203], v[34:37]
	v_mfma_f32_16x16x32_bf16 v[22:25], v[160:163], v[208:211], v[22:25]
	v_mfma_f32_16x16x32_bf16 v[18:21], v[168:171], v[208:211], v[18:21]
	v_mfma_f32_16x16x32_bf16 v[6:9], v[160:163], v[216:219], v[6:9]
	v_mfma_f32_16x16x32_bf16 v[2:5], v[168:171], v[216:219], v[2:5]
	s_setprio 0
	s_setprio 1
	v_mfma_f32_16x16x32_bf16 v[70:73], v[172:175], v[188:191], v[70:73]
	v_mfma_f32_16x16x32_bf16 v[58:61], v[180:183], v[188:191], v[58:61]
	v_mfma_f32_16x16x32_bf16 v[46:49], v[172:175], v[196:199], v[46:49]
	v_mfma_f32_16x16x32_bf16 v[42:45], v[180:183], v[196:199], v[42:45]
	v_mfma_f32_16x16x32_bf16 v[30:33], v[172:175], v[204:207], v[30:33]
	v_mfma_f32_16x16x32_bf16 v[26:29], v[180:183], v[204:207], v[26:29]
	v_mfma_f32_16x16x32_bf16 v[14:17], v[172:175], v[212:215], v[14:17]
	v_mfma_f32_16x16x32_bf16 v[10:13], v[180:183], v[212:215], v[10:13]
	v_mfma_f32_16x16x32_bf16 v[70:73], v[176:179], v[192:195], v[70:73]
	v_mfma_f32_16x16x32_bf16 v[58:61], v[184:187], v[192:195], v[58:61]
	v_mfma_f32_16x16x32_bf16 v[46:49], v[176:179], v[200:203], v[46:49]
	v_mfma_f32_16x16x32_bf16 v[42:45], v[184:187], v[200:203], v[42:45]
	v_mfma_f32_16x16x32_bf16 v[30:33], v[176:179], v[208:211], v[30:33]
	v_mfma_f32_16x16x32_bf16 v[26:29], v[184:187], v[208:211], v[26:29]
	v_mfma_f32_16x16x32_bf16 v[14:17], v[176:179], v[216:219], v[14:17]
	v_mfma_f32_16x16x32_bf16 v[10:13], v[184:187], v[216:219], v[10:13]
	s_barrier
	s_setprio 0
	s_add_i32 s68, s68, 2
	s_add_u32 s40, s40, 0x100
	s_addc_u32 s41, s41, 0
	s_add_u32 s26, s26, 0x100
	s_addc_u32 s27, s27, 0
	s_cmp_gt_u32 s68, 61
	s_cbranch_scc0 .LBB0_1345
	s_and_b64 vcc, exec, s[18:19]
	s_cbranch_vccz .LBB0_1348
	s_barrier

.LBB0_1425:
	ds_read_b128 v[148:151], v152
	ds_read_b128 v[156:159], v152 offset:1024
	ds_read_b128 v[160:163], v152 offset:2048
	ds_read_b128 v[164:167], v152 offset:3072
	ds_read_b128 v[168:171], v153
	ds_read_b128 v[172:175], v153 offset:1024
	ds_read_b128 v[176:179], v153 offset:2048
	ds_read_b128 v[180:183], v153 offset:3072
	s_add_u32 s20, s18, 0x200
	s_addc_u32 s21, s19, 0
	s_cmpk_eq_i32 s57, 0xa8
	s_cselect_b32 s23, s5, s21
	s_cselect_b32 s22, s4, s20
	s_cselect_b32 s21, s17, s27
	s_cselect_b32 s20, s16, s26
	s_mov_b32 m0, s49
	ds_read_b128 v[184:187], v154
	ds_read_b128 v[188:191], v154 offset:1024
	ds_read_b128 v[192:195], v154 offset:2048
	ds_read_b128 v[196:199], v154 offset:3072
	ds_read_b128 v[200:203], v154 offset:4096
	ds_read_b128 v[204:207], v154 offset:5120
	ds_read_b128 v[208:211], v154 offset:6144
	ds_read_b128 v[212:215], v154 offset:7168
	global_load_lds_dwordx4 v138, s[18:19]
	s_mov_b32 m0, s50
	s_nop 0
	global_load_lds_dwordx4 v140, s[18:19]
	s_waitcnt vmcnt(8)
	s_waitcnt lgkmcnt(0)
	s_setprio 1
	s_barrier
	v_mfma_f32_16x16x32_bf16 v[126:129], v[148:151], v[184:187], v[126:129]
	v_mfma_f32_16x16x32_bf16 v[122:125], v[160:163], v[184:187], v[122:125]
	v_mfma_f32_16x16x32_bf16 v[110:113], v[148:151], v[192:195], v[110:113]
	v_mfma_f32_16x16x32_bf16 v[106:109], v[160:163], v[192:195], v[106:109]
	v_mfma_f32_16x16x32_bf16 v[94:97], v[148:151], v[200:203], v[94:97]
	v_mfma_f32_16x16x32_bf16 v[90:93], v[160:163], v[200:203], v[90:93]
	v_mfma_f32_16x16x32_bf16 v[78:81], v[148:151], v[208:211], v[78:81]
	v_mfma_f32_16x16x32_bf16 v[74:77], v[160:163], v[208:211], v[74:77]
	v_mfma_f32_16x16x32_bf16 v[126:129], v[156:159], v[188:191], v[126:129]
	v_mfma_f32_16x16x32_bf16 v[122:125], v[164:167], v[188:191], v[122:125]
	v_mfma_f32_16x16x32_bf16 v[110:113], v[156:159], v[196:199], v[110:113]
	v_mfma_f32_16x16x32_bf16 v[106:109], v[164:167], v[196:199], v[106:109]
	v_mfma_f32_16x16x32_bf16 v[94:97], v[156:159], v[204:207], v[94:97]
	v_mfma_f32_16x16x32_bf16 v[90:93], v[164:167], v[204:207], v[90:93]
	v_mfma_f32_16x16x32_bf16 v[78:81], v[156:159], v[212:215], v[78:81]
	v_mfma_f32_16x16x32_bf16 v[74:77], v[164:167], v[212:215], v[74:77]
	s_setprio 0
	s_setprio 1
	v_mfma_f32_16x16x32_bf16 v[118:121], v[168:171], v[184:187], v[118:121]
	v_mfma_f32_16x16x32_bf16 v[114:117], v[176:179], v[184:187], v[114:117]
	v_mfma_f32_16x16x32_bf16 v[102:105], v[168:171], v[192:195], v[102:105]
	v_mfma_f32_16x16x32_bf16 v[98:101], v[176:179], v[192:195], v[98:101]
	v_mfma_f32_16x16x32_bf16 v[86:89], v[168:171], v[200:203], v[86:89]
	v_mfma_f32_16x16x32_bf16 v[82:85], v[176:179], v[200:203], v[82:85]
	v_mfma_f32_16x16x32_bf16 v[70:73], v[168:171], v[208:211], v[70:73]
	v_mfma_f32_16x16x32_bf16 v[66:69], v[176:179], v[208:211], v[66:69]
	v_mfma_f32_16x16x32_bf16 v[118:121], v[172:175], v[188:191], v[118:121]
	v_mfma_f32_16x16x32_bf16 v[114:117], v[180:183], v[188:191], v[114:117]
	v_mfma_f32_16x16x32_bf16 v[102:105], v[172:175], v[196:199], v[102:105]
	v_mfma_f32_16x16x32_bf16 v[98:101], v[180:183], v[196:199], v[98:101]
	v_mfma_f32_16x16x32_bf16 v[86:89], v[172:175], v[204:207], v[86:89]
	v_mfma_f32_16x16x32_bf16 v[82:85], v[180:183], v[204:207], v[82:85]
	v_mfma_f32_16x16x32_bf16 v[70:73], v[172:175], v[212:215], v[70:73]
	v_mfma_f32_16x16x32_bf16 v[66:69], v[180:183], v[212:215], v[66:69]
	s_barrier
	s_setprio 0
	s_mov_b32 m0, s51
	s_mov_b64 s[98:99], s[20:21]
	s_add_u32 s58, s20, 0x2b0000
	ds_read_b128 v[184:187], v154 offset:16384
	ds_read_b128 v[188:191], v154 offset:17408
	ds_read_b128 v[192:195], v154 offset:18432
	ds_read_b128 v[196:199], v154 offset:19456
	ds_read_b128 v[200:203], v154 offset:20480
	ds_read_b128 v[204:207], v154 offset:21504
	ds_read_b128 v[208:211], v154 offset:22528
	ds_read_b128 v[212:215], v154 offset:23552
	global_load_lds_dwordx4 v132, s[20:21]
	s_mov_b32 m0, s52
	s_addc_u32 s59, s21, 0
	global_load_lds_dwordx4 v136, s[20:21]
	s_mov_b32 m0, s46
	s_mov_b64 s[100:101], s[22:23]
	global_load_lds_dwordx4 v132, s[58:59]
	s_mov_b32 m0, s47
	s_nop 0
	global_load_lds_dwordx4 v136, s[58:59]
	s_waitcnt vmcnt(6)
	s_waitcnt lgkmcnt(0)
	s_setprio 1
	s_barrier
	v_mfma_f32_16x16x32_bf16 v[62:65], v[148:151], v[184:187], v[62:65]
	v_mfma_f32_16x16x32_bf16 v[58:61], v[160:163], v[184:187], v[58:61]
	v_mfma_f32_16x16x32_bf16 v[46:49], v[148:151], v[192:195], v[46:49]
	v_mfma_f32_16x16x32_bf16 v[42:45], v[160:163], v[192:195], v[42:45]
	v_mfma_f32_16x16x32_bf16 v[30:33], v[148:151], v[200:203], v[30:33]
	v_mfma_f32_16x16x32_bf16 v[26:29], v[160:163], v[200:203], v[26:29]
	v_mfma_f32_16x16x32_bf16 v[14:17], v[148:151], v[208:211], v[14:17]
	v_mfma_f32_16x16x32_bf16 v[10:13], v[160:163], v[208:211], v[10:13]
	v_mfma_f32_16x16x32_bf16 v[62:65], v[156:159], v[188:191], v[62:65]
	v_mfma_f32_16x16x32_bf16 v[58:61], v[164:167], v[188:191], v[58:61]
	v_mfma_f32_16x16x32_bf16 v[46:49], v[156:159], v[196:199], v[46:49]
	v_mfma_f32_16x16x32_bf16 v[42:45], v[164:167], v[196:199], v[42:45]
	v_mfma_f32_16x16x32_bf16 v[30:33], v[156:159], v[204:207], v[30:33]
	v_mfma_f32_16x16x32_bf16 v[26:29], v[164:167], v[204:207], v[26:29]
	v_mfma_f32_16x16x32_bf16 v[14:17], v[156:159], v[212:215], v[14:17]
	v_mfma_f32_16x16x32_bf16 v[10:13], v[164:167], v[212:215], v[10:13]
	s_setprio 0
	s_setprio 1
	v_mfma_f32_16x16x32_bf16 v[54:57], v[168:171], v[184:187], v[54:57]
	v_mfma_f32_16x16x32_bf16 v[50:53], v[176:179], v[184:187], v[50:53]
	v_mfma_f32_16x16x32_bf16 v[38:41], v[168:171], v[192:195], v[38:41]
	v_mfma_f32_16x16x32_bf16 v[34:37], v[176:179], v[192:195], v[34:37]
	v_mfma_f32_16x16x32_bf16 v[22:25], v[168:171], v[200:203], v[22:25]
	v_mfma_f32_16x16x32_bf16 v[18:21], v[176:179], v[200:203], v[18:21]
	v_mfma_f32_16x16x32_bf16 v[6:9], v[168:171], v[208:211], v[6:9]
	v_mfma_f32_16x16x32_bf16 v[2:5], v[176:179], v[208:211], v[2:5]
	v_mfma_f32_16x16x32_bf16 v[54:57], v[172:175], v[188:191], v[54:57]
	v_mfma_f32_16x16x32_bf16 v[50:53], v[180:183], v[188:191], v[50:53]
	v_mfma_f32_16x16x32_bf16 v[38:41], v[172:175], v[196:199], v[38:41]
	v_mfma_f32_16x16x32_bf16 v[34:37], v[180:183], v[196:199], v[34:37]
	v_mfma_f32_16x16x32_bf16 v[22:25], v[172:175], v[204:207], v[22:25]
	v_mfma_f32_16x16x32_bf16 v[18:21], v[180:183], v[204:207], v[18:21]
	v_mfma_f32_16x16x32_bf16 v[6:9], v[172:175], v[212:215], v[6:9]
	v_mfma_f32_16x16x32_bf16 v[2:5], v[180:183], v[212:215], v[2:5]
	s_barrier
	s_setprio 0
	ds_read_b128 v[148:151], v146
	ds_read_b128 v[156:159], v146 offset:1024
	ds_read_b128 v[160:163], v146 offset:2048
	ds_read_b128 v[164:167], v146 offset:3072
	ds_read_b128 v[168:171], v147
	ds_read_b128 v[172:175], v147 offset:1024
	ds_read_b128 v[176:179], v147 offset:2048
	ds_read_b128 v[180:183], v147 offset:3072
	s_add_u32 s22, s22, 0x2b0000
	s_addc_u32 s23, s23, 0
	s_mov_b32 m0, s28
	s_nop 0
	global_load_lds_dwordx4 v130, s[100:101]
	s_mov_b32 m0, s29
	s_nop 0
	global_load_lds_dwordx4 v134, s[100:101]
	s_mov_b32 m0, s30
	ds_read_b128 v[184:187], v154 offset:32768
	ds_read_b128 v[188:191], v154 offset:33792
	ds_read_b128 v[192:195], v154 offset:34816
	ds_read_b128 v[196:199], v154 offset:35840
	ds_read_b128 v[200:203], v154 offset:36864
	ds_read_b128 v[204:207], v154 offset:37888
	ds_read_b128 v[208:211], v154 offset:38912
	ds_read_b128 v[212:215], v154 offset:39936
	global_load_lds_dwordx4 v130, s[22:23]
	s_mov_b32 m0, s31
	s_nop 0
	global_load_lds_dwordx4 v134, s[22:23]
	s_waitcnt vmcnt(8)
	s_waitcnt lgkmcnt(0)
	s_setprio 1
	s_barrier
	v_mfma_f32_16x16x32_bf16 v[126:129], v[148:151], v[184:187], v[126:129]
	v_mfma_f32_16x16x32_bf16 v[122:125], v[160:163], v[184:187], v[122:125]
	v_mfma_f32_16x16x32_bf16 v[110:113], v[148:151], v[192:195], v[110:113]
	v_mfma_f32_16x16x32_bf16 v[106:109], v[160:163], v[192:195], v[106:109]
	v_mfma_f32_16x16x32_bf16 v[94:97], v[148:151], v[200:203], v[94:97]
	v_mfma_f32_16x16x32_bf16 v[90:93], v[160:163], v[200:203], v[90:93]
	v_mfma_f32_16x16x32_bf16 v[78:81], v[148:151], v[208:211], v[78:81]
	v_mfma_f32_16x16x32_bf16 v[74:77], v[160:163], v[208:211], v[74:77]
	v_mfma_f32_16x16x32_bf16 v[126:129], v[156:159], v[188:191], v[126:129]
	v_mfma_f32_16x16x32_bf16 v[122:125], v[164:167], v[188:191], v[122:125]
	v_mfma_f32_16x16x32_bf16 v[110:113], v[156:159], v[196:199], v[110:113]
	v_mfma_f32_16x16x32_bf16 v[106:109], v[164:167], v[196:199], v[106:109]
	v_mfma_f32_16x16x32_bf16 v[94:97], v[156:159], v[204:207], v[94:97]
	v_mfma_f32_16x16x32_bf16 v[90:93], v[164:167], v[204:207], v[90:93]
	v_mfma_f32_16x16x32_bf16 v[78:81], v[156:159], v[212:215], v[78:81]
	v_mfma_f32_16x16x32_bf16 v[74:77], v[164:167], v[212:215], v[74:77]
	s_setprio 0
	s_setprio 1
	v_mfma_f32_16x16x32_bf16 v[118:121], v[168:171], v[184:187], v[118:121]
	v_mfma_f32_16x16x32_bf16 v[114:117], v[176:179], v[184:187], v[114:117]
	v_mfma_f32_16x16x32_bf16 v[102:105], v[168:171], v[192:195], v[102:105]
	v_mfma_f32_16x16x32_bf16 v[98:101], v[176:179], v[192:195], v[98:101]
	v_mfma_f32_16x16x32_bf16 v[86:89], v[168:171], v[200:203], v[86:89]
	v_mfma_f32_16x16x32_bf16 v[82:85], v[176:179], v[200:203], v[82:85]
	v_mfma_f32_16x16x32_bf16 v[70:73], v[168:171], v[208:211], v[70:73]
	v_mfma_f32_16x16x32_bf16 v[66:69], v[176:179], v[208:211], v[66:69]
	v_mfma_f32_16x16x32_bf16 v[118:121], v[172:175], v[188:191], v[118:121]
	v_mfma_f32_16x16x32_bf16 v[114:117], v[180:183], v[188:191], v[114:117]
	v_mfma_f32_16x16x32_bf16 v[102:105], v[172:175], v[196:199], v[102:105]
	v_mfma_f32_16x16x32_bf16 v[98:101], v[180:183], v[196:199], v[98:101]
	v_mfma_f32_16x16x32_bf16 v[86:89], v[172:175], v[204:207], v[86:89]
	v_mfma_f32_16x16x32_bf16 v[82:85], v[180:183], v[204:207], v[82:85]
	v_mfma_f32_16x16x32_bf16 v[70:73], v[172:175], v[212:215], v[70:73]
	v_mfma_f32_16x16x32_bf16 v[66:69], v[180:183], v[212:215], v[66:69]
	s_barrier
	s_setprio 0
	s_mov_b32 m0, s53
	s_add_u32 s98, s98, 0x80
	s_addc_u32 s99, s99, 0
	s_add_u32 s100, s100, 0x80
	s_addc_u32 s101, s101, 0
	s_add_u32 s20, s20, 0x2b0080
	ds_read_b128 v[184:187], v154 offset:49152
	ds_read_b128 v[188:191], v154 offset:50176
	ds_read_b128 v[192:195], v154 offset:51200
	ds_read_b128 v[196:199], v154 offset:52224
	ds_read_b128 v[200:203], v154 offset:53248
	ds_read_b128 v[204:207], v154 offset:54272
	ds_read_b128 v[208:211], v154 offset:55296
	ds_read_b128 v[212:215], v154 offset:56320
	global_load_lds_dwordx4 v132, s[98:99]
	s_mov_b32 m0, s54
	s_addc_u32 s21, s21, 0
	global_load_lds_dwordx4 v136, s[98:99]
	s_mov_b32 m0, s55
	s_nop 0
	global_load_lds_dwordx4 v132, s[20:21]
	s_mov_b32 m0, s56
	s_nop 0
	global_load_lds_dwordx4 v136, s[20:21]
	s_mov_b32 m0, s34
	s_nop 0
	global_load_lds_dwordx4 v130, s[100:101]
	s_mov_b32 m0, s35
	s_nop 0
	global_load_lds_dwordx4 v134, s[100:101]
	s_waitcnt vmcnt(8)
	s_waitcnt lgkmcnt(0)
	s_setprio 1
	s_barrier
	v_mfma_f32_16x16x32_bf16 v[62:65], v[148:151], v[184:187], v[62:65]
	v_mfma_f32_16x16x32_bf16 v[58:61], v[160:163], v[184:187], v[58:61]
	v_mfma_f32_16x16x32_bf16 v[46:49], v[148:151], v[192:195], v[46:49]
	v_mfma_f32_16x16x32_bf16 v[42:45], v[160:163], v[192:195], v[42:45]
	v_mfma_f32_16x16x32_bf16 v[30:33], v[148:151], v[200:203], v[30:33]
	v_mfma_f32_16x16x32_bf16 v[26:29], v[160:163], v[200:203], v[26:29]
	v_mfma_f32_16x16x32_bf16 v[14:17], v[148:151], v[208:211], v[14:17]
	v_mfma_f32_16x16x32_bf16 v[10:13], v[160:163], v[208:211], v[10:13]
	v_mfma_f32_16x16x32_bf16 v[62:65], v[156:159], v[188:191], v[62:65]
	v_mfma_f32_16x16x32_bf16 v[58:61], v[164:167], v[188:191], v[58:61]
	v_mfma_f32_16x16x32_bf16 v[46:49], v[156:159], v[196:199], v[46:49]
	v_mfma_f32_16x16x32_bf16 v[42:45], v[164:167], v[196:199], v[42:45]
	v_mfma_f32_16x16x32_bf16 v[30:33], v[156:159], v[204:207], v[30:33]
	v_mfma_f32_16x16x32_bf16 v[26:29], v[164:167], v[204:207], v[26:29]
	v_mfma_f32_16x16x32_bf16 v[14:17], v[156:159], v[212:215], v[14:17]
	v_mfma_f32_16x16x32_bf16 v[10:13], v[164:167], v[212:215], v[10:13]
	s_setprio 0
	s_setprio 1
	v_mfma_f32_16x16x32_bf16 v[54:57], v[168:171], v[184:187], v[54:57]
	v_mfma_f32_16x16x32_bf16 v[50:53], v[176:179], v[184:187], v[50:53]
	v_mfma_f32_16x16x32_bf16 v[38:41], v[168:171], v[192:195], v[38:41]
	v_mfma_f32_16x16x32_bf16 v[34:37], v[176:179], v[192:195], v[34:37]
	v_mfma_f32_16x16x32_bf16 v[22:25], v[168:171], v[200:203], v[22:25]
	v_mfma_f32_16x16x32_bf16 v[18:21], v[176:179], v[200:203], v[18:21]
	v_mfma_f32_16x16x32_bf16 v[6:9], v[168:171], v[208:211], v[6:9]
	v_mfma_f32_16x16x32_bf16 v[2:5], v[176:179], v[208:211], v[2:5]
	v_mfma_f32_16x16x32_bf16 v[54:57], v[172:175], v[188:191], v[54:57]
	v_mfma_f32_16x16x32_bf16 v[50:53], v[180:183], v[188:191], v[50:53]
	v_mfma_f32_16x16x32_bf16 v[38:41], v[172:175], v[196:199], v[38:41]
	v_mfma_f32_16x16x32_bf16 v[34:37], v[180:183], v[196:199], v[34:37]
	v_mfma_f32_16x16x32_bf16 v[22:25], v[172:175], v[204:207], v[22:25]
	v_mfma_f32_16x16x32_bf16 v[18:21], v[180:183], v[204:207], v[18:21]
	v_mfma_f32_16x16x32_bf16 v[6:9], v[172:175], v[212:215], v[6:9]
	v_mfma_f32_16x16x32_bf16 v[2:5], v[180:183], v[212:215], v[2:5]
	s_barrier
	s_setprio 0
	s_add_i32 s57, s57, 2
	s_add_u32 s18, s18, 0x100
	s_addc_u32 s19, s19, 0
	s_add_u32 s26, s26, 0x100
	s_addc_u32 s27, s27, 0
	s_cmpk_gt_u32 s57, 0xa9
	s_cbranch_scc0 .LBB0_1425
	s_and_b64 vcc, exec, s[10:11]
	s_cbranch_vccz .LBB0_1428
	s_barrier
